# 7.11 back-edge rotation (reduced): K-loop counter / pointer updates and the exit compare issued before the loop-back barrier in all GEMM loops
# baseline (speedup 1.0000x reference)
; #define PG8_STAGE(bufoff, gbase, voff) do { _Pragma("unroll") for (int _i = 0; _i < 2; ++_i) \
;         __builtin_amdgcn_global_load_lds((const unsigned*)((const char*)(gbase) + (voff)[_i]), (PG8_LAS unsigned*)(lds + (bufoff) + ldsw + _i * 8192), 16, 0, 0); } while (0)
; #define PG8_STAGEA(bufoff, gbase, voff) do { _Pragma("unroll") for (int _i = 0; _i < 2; ++_i) \
;         __builtin_amdgcn_global_load_lds((const unsigned*)((const char*)(gbase) + (voff)[_i]), (PG8_LAS unsigned*)(lds + (bufoff) + ldsw + _i * 8192), 16, 0, AUXA); } while (0)
; #define PG8_LDA(dst, b, h) do { _Pragma("unroll") for (int m = 0; m < 4; ++m) _Pragma("unroll") for (int k = 0; k < 2; ++k) dst[m][k] = *(const PG8_LAS bf16x8*)(lds + PG8_SA(b, h) + aoff + m * 2048 + k * 1024); } while (0)
; #define PG8_LDB(dst, b, h) do { _Pragma("unroll") for (int n = 0; n < 2; ++n) _Pragma("unroll") for (int k = 0; k < 2; ++k) dst[n][k] = *(const PG8_LAS bf16x8*)(lds + PG8_SB(b, h) + boff + n * 2048 + k * 1024); } while (0)
; #define PG8_MMA(ai, bj, At, Bt) do { __builtin_amdgcn_s_setprio(1); _Pragma("unroll") for (int m = 0; m < 4; ++m) _Pragma("unroll") for (int n = 0; n < 2; ++n) _Pragma("unroll") for (int k = 0; k < 2; ++k) \
;         acc[ai][bj][m][n] = __builtin_amdgcn_mfma_f32_16x16x32_bf16(Bt[n][k], At[m][k], acc[ai][bj][m][n], 0, 0, 0); __builtin_amdgcn_s_setprio(0); } while (0)
; #define PG8_WAIT_V(n) asm volatile("s_waitcnt vmcnt(" #n ")" ::: "memory")
; #define PG8_WAIT_L(n) asm volatile("s_waitcnt lgkmcnt(" #n ")" ::: "memory")
; #define PG8_BAR __builtin_amdgcn_s_barrier()
; #define PG8_SCHED __builtin_amdgcn_sched_barrier(0)
;     ...
;             if constexpr (SP2) {
;             PG8_LDB(B0, 0, 0); PG8_LDB(B1, 0, 1); PG8_SCHED; PG8_LDA(At, 0, 0); PG8_STAGEA(PG8_SA(1, 1), a1 + hstep, voffA);
;             PG8_WAIT_V(8); PG8_WAIT_L(0); PG8_BAR; PG8_MMA(0, 0, At, B0); PG8_MMA(0, 1, At, B1); PG8_BAR; PG8_SCHED;
;             PG8_LDA(At, 0, 1); PG8_STAGE(PG8_SB(0, 0), b2, voffB); PG8_STAGE(PG8_SB(0, 1), b2 + hstepB, voffB); PG8_STAGEA(PG8_SA(0, 0), a2, voffA);
;             PG8_WAIT_V(8); PG8_WAIT_L(0); PG8_BAR; PG8_MMA(1, 0, At, B0); PG8_MMA(1, 1, At, B1); PG8_BAR; PG8_SCHED;
.Lsprio_0:
.LBB0_119:
	ds_read_b128 v[128:131], v229
	ds_read_b128 v[132:135], v229 offset:1024
	ds_read_b128 v[136:139], v229 offset:2048
	ds_read_b128 v[140:143], v229 offset:3072
	ds_read_b128 v[176:179], v230
	ds_read_b128 v[180:183], v230 offset:1024
	ds_read_b128 v[184:187], v230 offset:2048
	ds_read_b128 v[188:191], v230 offset:3072
	s_add_u32 s36, s8, 0xfffc0080
	s_addc_u32 s37, s9, -1
	s_cmp_eq_u32 s78, 12
	s_cselect_b32 s39, s5, s37
	s_cselect_b32 s38, s7, s36
	s_cselect_b32 s37, s27, s59
	s_cselect_b32 s36, s29, s58
	v_lshl_add_u64 v[172:173], s[8:9], 0, v[164:165]
	s_add_i32 m0, s85, 0xc000
	ds_read_b128 v[192:195], v231
	ds_read_b128 v[196:199], v231 offset:1024
	ds_read_b128 v[238:241], v231 offset:2048
	ds_read_b128 v[242:245], v231 offset:3072
	ds_read_b128 v[246:249], v231 offset:4096
	ds_read_b128 v[250:253], v231 offset:5120
	ds_read_b128 v[210:213], v231 offset:6144
	ds_read_b128 v[214:217], v231 offset:7168
	global_load_lds_dwordx4 v[172:173], off
	v_lshl_add_u64 v[172:173], s[8:9], 0, v[166:167]
	s_add_i32 m0, s85, 0xe000
	s_nop 0
	global_load_lds_dwordx4 v[172:173], off
	s_waitcnt vmcnt(8)
	s_waitcnt lgkmcnt(0)
	s_barrier
	s_waitcnt lgkmcnt(0)
	v_mfma_f32_16x16x32_bf16 v[76:79], v[128:131], v[192:195], v[76:79]
	v_mfma_f32_16x16x32_bf16 v[72:75], v[136:139], v[192:195], v[72:75]
	v_mfma_f32_16x16x32_bf16 v[124:127], v[128:131], v[238:241], v[124:127]
	v_mfma_f32_16x16x32_bf16 v[120:123], v[136:139], v[238:241], v[120:123]
	v_mfma_f32_16x16x32_bf16 v[108:111], v[128:131], v[246:249], v[108:111]
	v_mfma_f32_16x16x32_bf16 v[104:107], v[136:139], v[246:249], v[104:107]
	v_mfma_f32_16x16x32_bf16 v[92:95], v[128:131], v[210:213], v[92:95]
	v_mfma_f32_16x16x32_bf16 v[88:91], v[136:139], v[210:213], v[88:91]
	v_mfma_f32_16x16x32_bf16 v[76:79], v[132:135], v[196:199], v[76:79]
	v_mfma_f32_16x16x32_bf16 v[72:75], v[140:143], v[196:199], v[72:75]
	v_mfma_f32_16x16x32_bf16 v[124:127], v[132:135], v[242:245], v[124:127]
	v_mfma_f32_16x16x32_bf16 v[120:123], v[140:143], v[242:245], v[120:123]
	v_mfma_f32_16x16x32_bf16 v[108:111], v[132:135], v[250:253], v[108:111]
	v_mfma_f32_16x16x32_bf16 v[104:107], v[140:143], v[250:253], v[104:107]
	v_mfma_f32_16x16x32_bf16 v[92:95], v[132:135], v[214:217], v[92:95]
	v_mfma_f32_16x16x32_bf16 v[88:91], v[140:143], v[214:217], v[88:91]
	v_mfma_f32_16x16x32_bf16 v[52:55], v[176:179], v[192:195], v[52:55]
	v_mfma_f32_16x16x32_bf16 v[48:51], v[184:187], v[192:195], v[48:51]
	v_mfma_f32_16x16x32_bf16 v[116:119], v[176:179], v[238:241], v[116:119]
	v_mfma_f32_16x16x32_bf16 v[112:115], v[184:187], v[238:241], v[112:115]
	v_mfma_f32_16x16x32_bf16 v[100:103], v[176:179], v[246:249], v[100:103]
	v_mfma_f32_16x16x32_bf16 v[96:99], v[184:187], v[246:249], v[96:99]
	v_mfma_f32_16x16x32_bf16 v[84:87], v[176:179], v[210:213], v[84:87]
	v_mfma_f32_16x16x32_bf16 v[80:83], v[184:187], v[210:213], v[80:83]
	v_mfma_f32_16x16x32_bf16 v[52:55], v[180:183], v[196:199], v[52:55]
	v_mfma_f32_16x16x32_bf16 v[48:51], v[188:191], v[196:199], v[48:51]
	v_mfma_f32_16x16x32_bf16 v[116:119], v[180:183], v[242:245], v[116:119]
	v_mfma_f32_16x16x32_bf16 v[112:115], v[188:191], v[242:245], v[112:115]
	v_mfma_f32_16x16x32_bf16 v[100:103], v[180:183], v[250:253], v[100:103]
	v_mfma_f32_16x16x32_bf16 v[96:99], v[188:191], v[250:253], v[96:99]
	v_mfma_f32_16x16x32_bf16 v[84:87], v[180:183], v[214:217], v[84:87]
	v_mfma_f32_16x16x32_bf16 v[80:83], v[188:191], v[214:217], v[80:83]
	s_barrier
	s_add_i32 s79, s73, s67
	v_lshl_add_u64 v[172:173], s[36:37], 0, v[146:147]
	s_mov_b32 m0, s79
	ds_read_b128 v[192:195], v231 offset:16384
	ds_read_b128 v[196:199], v231 offset:17408
	ds_read_b128 v[210:213], v231 offset:18432
	ds_read_b128 v[214:217], v231 offset:19456
	ds_read_b128 v[238:241], v231 offset:20480
	ds_read_b128 v[242:245], v231 offset:21504
	ds_read_b128 v[246:249], v231 offset:22528
	ds_read_b128 v[250:253], v231 offset:23552
	global_load_lds_dwordx4 v[172:173], off
	s_add_i32 m0, s79, 0x2000
	s_add_u32 s80, s36, 0x10000
	v_lshl_add_u64 v[202:203], s[36:37], 0, v[150:151]
	s_addc_u32 s81, s37, 0
	s_add_i32 s79, s46, s67
	global_load_lds_dwordx4 v[202:203], off
	v_lshl_add_u64 v[204:205], s[80:81], 0, v[146:147]
	s_mov_b32 m0, s79
	v_lshl_add_u64 v[206:207], s[38:39], 0, v[148:149]
	global_load_lds_dwordx4 v[204:205], off
	v_lshl_add_u64 v[204:205], s[80:81], 0, v[150:151]
	s_add_i32 m0, s79, 0x2000
	s_nop 0
	global_load_lds_dwordx4 v[204:205], off
	v_lshl_add_u64 v[204:205], s[38:39], 0, v[144:145]
	s_mov_b32 m0, s85
	s_nop 0
	global_load_lds_dwordx4 v[204:205], off
	s_mov_b32 m0, s86
	s_nop 0
	global_load_lds_dwordx4 v[206:207], off
	s_waitcnt vmcnt(8)
	s_waitcnt lgkmcnt(0)
	s_barrier
; #define PG8_STAGE(bufoff, gbase, voff) do { _Pragma("unroll") for (int _i = 0; _i < 2; ++_i) \
;         __builtin_amdgcn_global_load_lds((const unsigned*)((const char*)(gbase) + (voff)[_i]), (PG8_LAS unsigned*)(lds + (bufoff) + ldsw + _i * 8192), 16, 0, 0); } while (0)
; #define PG8_STAGEA(bufoff, gbase, voff) do { _Pragma("unroll") for (int _i = 0; _i < 2; ++_i) \
;         __builtin_amdgcn_global_load_lds((const unsigned*)((const char*)(gbase) + (voff)[_i]), (PG8_LAS unsigned*)(lds + (bufoff) + ldsw + _i * 8192), 16, 0, AUXA); } while (0)
; #define PG8_LDA(dst, b, h) do { _Pragma("unroll") for (int m = 0; m < 4; ++m) _Pragma("unroll") for (int k = 0; k < 2; ++k) dst[m][k] = *(const PG8_LAS bf16x8*)(lds + PG8_SA(b, h) + aoff + m * 2048 + k * 1024); } while (0)
; #define PG8_LDB(dst, b, h) do { _Pragma("unroll") for (int n = 0; n < 2; ++n) _Pragma("unroll") for (int k = 0; k < 2; ++k) dst[n][k] = *(const PG8_LAS bf16x8*)(lds + PG8_SB(b, h) + boff + n * 2048 + k * 1024); } while (0)
; #define PG8_MMA(ai, bj, At, Bt) do { __builtin_amdgcn_s_setprio(1); _Pragma("unroll") for (int m = 0; m < 4; ++m) _Pragma("unroll") for (int n = 0; n < 2; ++n) _Pragma("unroll") for (int k = 0; k < 2; ++k) \
;         acc[ai][bj][m][n] = __builtin_amdgcn_mfma_f32_16x16x32_bf16(Bt[n][k], At[m][k], acc[ai][bj][m][n], 0, 0, 0); __builtin_amdgcn_s_setprio(0); } while (0)
; #define PG8_WAIT_V(n) asm volatile("s_waitcnt vmcnt(" #n ")" ::: "memory")
; #define PG8_WAIT_L(n) asm volatile("s_waitcnt lgkmcnt(" #n ")" ::: "memory")
; #define PG8_BAR __builtin_amdgcn_s_barrier()
; #define PG8_SCHED __builtin_amdgcn_sched_barrier(0)
;     ...
;             PG8_WAIT_V(8); PG8_WAIT_L(0); PG8_BAR; PG8_MMA(0, 0, At, B0); PG8_MMA(0, 1, At, B1); PG8_BAR; PG8_SCHED;
;             PG8_LDA(At, 0, 1); PG8_STAGE(PG8_SB(0, 0), b2, voffB); PG8_STAGE(PG8_SB(0, 1), b2 + hstepB, voffB); PG8_STAGEA(PG8_SA(0, 0), a2, voffA);
;             PG8_WAIT_V(8); PG8_WAIT_L(0); PG8_BAR; PG8_MMA(1, 0, At, B0); PG8_MMA(1, 1, At, B1); PG8_BAR; PG8_SCHED;
;             PG8_LDB(B0, 1, 0); PG8_LDB(B1, 1, 1); PG8_SCHED; PG8_LDA(At, 1, 0); PG8_STAGEA(PG8_SA(0, 1), a2 + hstep, voffA);
;             PG8_WAIT_V(8); PG8_WAIT_L(0); PG8_BAR; PG8_MMA(0, 0, At, B0); PG8_MMA(0, 1, At, B1); PG8_BAR; PG8_SCHED;
	s_waitcnt lgkmcnt(0)
	v_mfma_f32_16x16x32_bf16 v[68:71], v[128:131], v[192:195], v[68:71]
	v_mfma_f32_16x16x32_bf16 v[64:67], v[136:139], v[192:195], v[64:67]
	v_mfma_f32_16x16x32_bf16 v[44:47], v[128:131], v[210:213], v[44:47]
	v_mfma_f32_16x16x32_bf16 v[40:43], v[136:139], v[210:213], v[40:43]
	v_mfma_f32_16x16x32_bf16 v[28:31], v[128:131], v[238:241], v[28:31]
	v_mfma_f32_16x16x32_bf16 v[24:27], v[136:139], v[238:241], v[24:27]
	v_mfma_f32_16x16x32_bf16 v[12:15], v[128:131], v[246:249], v[12:15]
	v_mfma_f32_16x16x32_bf16 v[8:11], v[136:139], v[246:249], v[8:11]
	v_mfma_f32_16x16x32_bf16 v[68:71], v[132:135], v[196:199], v[68:71]
	v_mfma_f32_16x16x32_bf16 v[64:67], v[140:143], v[196:199], v[64:67]
	v_mfma_f32_16x16x32_bf16 v[44:47], v[132:135], v[214:217], v[44:47]
	v_mfma_f32_16x16x32_bf16 v[40:43], v[140:143], v[214:217], v[40:43]
	v_mfma_f32_16x16x32_bf16 v[28:31], v[132:135], v[242:245], v[28:31]
	v_mfma_f32_16x16x32_bf16 v[24:27], v[140:143], v[242:245], v[24:27]
	v_mfma_f32_16x16x32_bf16 v[12:15], v[132:135], v[250:253], v[12:15]
	v_mfma_f32_16x16x32_bf16 v[8:11], v[140:143], v[250:253], v[8:11]
	v_mfma_f32_16x16x32_bf16 v[60:63], v[176:179], v[192:195], v[60:63]
	v_mfma_f32_16x16x32_bf16 v[56:59], v[184:187], v[192:195], v[56:59]
	v_mfma_f32_16x16x32_bf16 v[36:39], v[176:179], v[210:213], v[36:39]
	v_mfma_f32_16x16x32_bf16 v[32:35], v[184:187], v[210:213], v[32:35]
	v_mfma_f32_16x16x32_bf16 v[20:23], v[176:179], v[238:241], v[20:23]
	v_mfma_f32_16x16x32_bf16 v[16:19], v[184:187], v[238:241], v[16:19]
	v_mfma_f32_16x16x32_bf16 v[4:7], v[176:179], v[246:249], v[4:7]
	v_mfma_f32_16x16x32_bf16 v[0:3], v[184:187], v[246:249], v[0:3]
	v_mfma_f32_16x16x32_bf16 v[60:63], v[180:183], v[196:199], v[60:63]
	v_mfma_f32_16x16x32_bf16 v[56:59], v[188:191], v[196:199], v[56:59]
	v_mfma_f32_16x16x32_bf16 v[36:39], v[180:183], v[214:217], v[36:39]
	v_mfma_f32_16x16x32_bf16 v[32:35], v[188:191], v[214:217], v[32:35]
	v_mfma_f32_16x16x32_bf16 v[20:23], v[180:183], v[242:245], v[20:23]
	v_mfma_f32_16x16x32_bf16 v[16:19], v[188:191], v[242:245], v[16:19]
	v_mfma_f32_16x16x32_bf16 v[4:7], v[180:183], v[250:253], v[4:7]
	v_mfma_f32_16x16x32_bf16 v[0:3], v[188:191], v[250:253], v[0:3]
	s_barrier
	s_add_i32 s79, 0, 0x18000
	s_add_i32 s80, 0, 0x1c000
	v_add_u32_e32 v140, s79, v226
	v_add_u32_e32 v152, s80, v226
	ds_read_b128 v[128:131], v140
	ds_read_b128 v[132:135], v140 offset:1024
	ds_read_b128 v[136:139], v140 offset:2048
	ds_read_b128 v[140:143], v140 offset:3072
	ds_read_b128 v[176:179], v152
	ds_read_b128 v[180:183], v152 offset:1024
	ds_read_b128 v[184:187], v152 offset:2048
	ds_read_b128 v[188:191], v152 offset:3072
	s_add_u32 s38, s38, 0x40000
	s_addc_u32 s39, s39, 0
	s_mov_b32 m0, s87
	v_lshl_add_u64 v[218:219], s[38:39], 0, v[144:145]
	ds_read_b128 v[192:195], v231 offset:32768
	ds_read_b128 v[196:199], v231 offset:33792
	ds_read_b128 v[210:213], v231 offset:34816
	ds_read_b128 v[214:217], v231 offset:35840
	ds_read_b128 v[238:241], v231 offset:36864
	ds_read_b128 v[242:245], v231 offset:37888
	ds_read_b128 v[246:249], v231 offset:38912
	ds_read_b128 v[250:253], v231 offset:39936
	global_load_lds_dwordx4 v[218:219], off
	v_lshl_add_u64 v[218:219], s[38:39], 0, v[148:149]
	s_mov_b32 m0, s88
	s_nop 0
	global_load_lds_dwordx4 v[218:219], off
	s_waitcnt vmcnt(8)
	s_waitcnt lgkmcnt(0)
	s_barrier
	s_waitcnt lgkmcnt(0)
	v_mfma_f32_16x16x32_bf16 v[76:79], v[128:131], v[192:195], v[76:79]
	v_mfma_f32_16x16x32_bf16 v[72:75], v[136:139], v[192:195], v[72:75]
	v_mfma_f32_16x16x32_bf16 v[124:127], v[128:131], v[210:213], v[124:127]
	v_mfma_f32_16x16x32_bf16 v[120:123], v[136:139], v[210:213], v[120:123]
	v_mfma_f32_16x16x32_bf16 v[108:111], v[128:131], v[238:241], v[108:111]
	v_mfma_f32_16x16x32_bf16 v[104:107], v[136:139], v[238:241], v[104:107]
	v_mfma_f32_16x16x32_bf16 v[92:95], v[128:131], v[246:249], v[92:95]
	v_mfma_f32_16x16x32_bf16 v[88:91], v[136:139], v[246:249], v[88:91]
	v_mfma_f32_16x16x32_bf16 v[76:79], v[132:135], v[196:199], v[76:79]
	v_mfma_f32_16x16x32_bf16 v[72:75], v[140:143], v[196:199], v[72:75]
	v_mfma_f32_16x16x32_bf16 v[124:127], v[132:135], v[214:217], v[124:127]
	v_mfma_f32_16x16x32_bf16 v[120:123], v[140:143], v[214:217], v[120:123]
	v_mfma_f32_16x16x32_bf16 v[108:111], v[132:135], v[242:245], v[108:111]
	v_mfma_f32_16x16x32_bf16 v[104:107], v[140:143], v[242:245], v[104:107]
	v_mfma_f32_16x16x32_bf16 v[92:95], v[132:135], v[250:253], v[92:95]
	v_mfma_f32_16x16x32_bf16 v[88:91], v[140:143], v[250:253], v[88:91]
	v_mfma_f32_16x16x32_bf16 v[52:55], v[176:179], v[192:195], v[52:55]
	v_mfma_f32_16x16x32_bf16 v[48:51], v[184:187], v[192:195], v[48:51]
	v_mfma_f32_16x16x32_bf16 v[116:119], v[176:179], v[210:213], v[116:119]
	v_mfma_f32_16x16x32_bf16 v[112:115], v[184:187], v[210:213], v[112:115]
	v_mfma_f32_16x16x32_bf16 v[100:103], v[176:179], v[238:241], v[100:103]
	v_mfma_f32_16x16x32_bf16 v[96:99], v[184:187], v[238:241], v[96:99]
	v_mfma_f32_16x16x32_bf16 v[84:87], v[176:179], v[246:249], v[84:87]
	v_mfma_f32_16x16x32_bf16 v[80:83], v[184:187], v[246:249], v[80:83]
	v_mfma_f32_16x16x32_bf16 v[52:55], v[180:183], v[196:199], v[52:55]
	v_mfma_f32_16x16x32_bf16 v[48:51], v[188:191], v[196:199], v[48:51]
	v_mfma_f32_16x16x32_bf16 v[116:119], v[180:183], v[214:217], v[116:119]
	v_mfma_f32_16x16x32_bf16 v[112:115], v[188:191], v[214:217], v[112:115]
	v_mfma_f32_16x16x32_bf16 v[100:103], v[180:183], v[242:245], v[100:103]
	v_mfma_f32_16x16x32_bf16 v[96:99], v[188:191], v[242:245], v[96:99]
	v_mfma_f32_16x16x32_bf16 v[84:87], v[180:183], v[250:253], v[84:87]
	v_mfma_f32_16x16x32_bf16 v[80:83], v[188:191], v[250:253], v[80:83]
	s_barrier
; #define PG8_STAGE(bufoff, gbase, voff) do { _Pragma("unroll") for (int _i = 0; _i < 2; ++_i) \
;         __builtin_amdgcn_global_load_lds((const unsigned*)((const char*)(gbase) + (voff)[_i]), (PG8_LAS unsigned*)(lds + (bufoff) + ldsw + _i * 8192), 16, 0, 0); } while (0)
; #define PG8_STAGEA(bufoff, gbase, voff) do { _Pragma("unroll") for (int _i = 0; _i < 2; ++_i) \
;         __builtin_amdgcn_global_load_lds((const unsigned*)((const char*)(gbase) + (voff)[_i]), (PG8_LAS unsigned*)(lds + (bufoff) + ldsw + _i * 8192), 16, 0, AUXA); } while (0)
; #define PG8_LDA(dst, b, h) do { _Pragma("unroll") for (int m = 0; m < 4; ++m) _Pragma("unroll") for (int k = 0; k < 2; ++k) dst[m][k] = *(const PG8_LAS bf16x8*)(lds + PG8_SA(b, h) + aoff + m * 2048 + k * 1024); } while (0)
; #define PG8_WAIT_V(n) asm volatile("s_waitcnt vmcnt(" #n ")" ::: "memory")
; #define PG8_BAR __builtin_amdgcn_s_barrier()
;     ...
;         for (int t = 0; t < nt; t += 2) {
;             const bool last = (t == nt - 2);
;             const char* a1 = cA + (size_t)(t + 1) * kstep;
;             const char* a2 = last ? nA : cA + (size_t)(t + 2) * kstep; const char* b2 = last ? nB : cB + (size_t)(t + 2) * kstep;
;             const char* a3 = a2 + kstep; const char* b3 = b2 + kstep;
;             if (last && has_next) S.a_ready(nxt);
;             if constexpr (SP2) {
;             PG8_LDB(B0, 0, 0); PG8_LDB(B1, 0, 1); PG8_SCHED; PG8_LDA(At, 0, 0); PG8_STAGEA(PG8_SA(1, 1), a1 + hstep, voffA);
;             PG8_WAIT_V(8); PG8_WAIT_L(0); PG8_BAR; PG8_MMA(0, 0, At, B0); PG8_MMA(0, 1, At, B1); PG8_BAR; PG8_SCHED;
;             PG8_LDA(At, 0, 1); PG8_STAGE(PG8_SB(0, 0), b2, voffB); PG8_STAGE(PG8_SB(0, 1), b2 + hstepB, voffB); PG8_STAGEA(PG8_SA(0, 0), a2, voffA);
;             PG8_WAIT_V(8); PG8_WAIT_L(0); PG8_BAR; PG8_MMA(1, 0, At, B0); PG8_MMA(1, 1, At, B1); PG8_BAR; PG8_SCHED;
;             PG8_LDB(B0, 1, 0); PG8_LDB(B1, 1, 1); PG8_SCHED; PG8_LDA(At, 1, 0); PG8_STAGEA(PG8_SA(0, 1), a2 + hstep, voffA);
;             PG8_WAIT_V(8); PG8_WAIT_L(0); PG8_BAR; PG8_MMA(0, 0, At, B0); PG8_MMA(0, 1, At, B1); PG8_BAR; PG8_SCHED;
;             PG8_LDA(At, 1, 1); PG8_STAGE(PG8_SB(1, 0), b3, voffB); PG8_STAGE(PG8_SB(1, 1), b3 + hstepB, voffB); PG8_STAGEA(PG8_SA(1, 0), a3, voffA);
;             PG8_WAIT_V(8); PG8_WAIT_L(0); PG8_BAR; PG8_MMA(1, 0, At, B0); PG8_MMA(1, 1, At, B1); PG8_BAR; PG8_SCHED;
	s_add_i32 s38, s79, s67
	v_lshl_add_u64 v[172:173], v[172:173], 0, s[16:17]
	s_mov_b32 m0, s38
	ds_read_b128 v[192:195], v231 offset:49152
	ds_read_b128 v[196:199], v231 offset:50176
	ds_read_b128 v[210:213], v231 offset:51200
	ds_read_b128 v[214:217], v231 offset:52224
	ds_read_b128 v[238:241], v231 offset:53248
	ds_read_b128 v[242:245], v231 offset:54272
	ds_read_b128 v[246:249], v231 offset:55296
	ds_read_b128 v[250:253], v231 offset:56320
	global_load_lds_dwordx4 v[172:173], off
	s_add_i32 m0, s38, 0x2000
	s_add_u32 s36, s36, 0x10080
	v_lshl_add_u64 v[172:173], v[202:203], 0, s[16:17]
	s_addc_u32 s37, s37, 0
	s_add_i32 s38, s80, s67
	global_load_lds_dwordx4 v[172:173], off
	v_lshl_add_u64 v[172:173], s[36:37], 0, v[146:147]
	s_mov_b32 m0, s38
	s_nop 0
	global_load_lds_dwordx4 v[172:173], off
	v_lshl_add_u64 v[172:173], s[36:37], 0, v[150:151]
	s_add_i32 m0, s38, 0x2000
	s_nop 0
	global_load_lds_dwordx4 v[172:173], off
	v_lshl_add_u64 v[172:173], v[204:205], 0, s[16:17]
	s_mov_b32 m0, s89
	s_nop 0
	global_load_lds_dwordx4 v[172:173], off
	v_lshl_add_u64 v[172:173], v[206:207], 0, s[16:17]
	s_mov_b32 m0, s90
	s_nop 0
	global_load_lds_dwordx4 v[172:173], off
	s_waitcnt vmcnt(8)
	s_waitcnt lgkmcnt(0)
	s_barrier
	s_waitcnt lgkmcnt(0)
	v_mfma_f32_16x16x32_bf16 v[68:71], v[128:131], v[192:195], v[68:71]
	v_mfma_f32_16x16x32_bf16 v[64:67], v[136:139], v[192:195], v[64:67]
	v_mfma_f32_16x16x32_bf16 v[44:47], v[128:131], v[210:213], v[44:47]
	v_mfma_f32_16x16x32_bf16 v[40:43], v[136:139], v[210:213], v[40:43]
	v_mfma_f32_16x16x32_bf16 v[28:31], v[128:131], v[238:241], v[28:31]
	v_mfma_f32_16x16x32_bf16 v[24:27], v[136:139], v[238:241], v[24:27]
	v_mfma_f32_16x16x32_bf16 v[12:15], v[128:131], v[246:249], v[12:15]
	v_mfma_f32_16x16x32_bf16 v[8:11], v[136:139], v[246:249], v[8:11]
	v_mfma_f32_16x16x32_bf16 v[68:71], v[132:135], v[196:199], v[68:71]
	v_mfma_f32_16x16x32_bf16 v[64:67], v[140:143], v[196:199], v[64:67]
	v_mfma_f32_16x16x32_bf16 v[44:47], v[132:135], v[214:217], v[44:47]
	v_mfma_f32_16x16x32_bf16 v[40:43], v[140:143], v[214:217], v[40:43]
	v_mfma_f32_16x16x32_bf16 v[28:31], v[132:135], v[242:245], v[28:31]
	v_mfma_f32_16x16x32_bf16 v[24:27], v[140:143], v[242:245], v[24:27]
	v_mfma_f32_16x16x32_bf16 v[12:15], v[132:135], v[250:253], v[12:15]
	v_mfma_f32_16x16x32_bf16 v[8:11], v[140:143], v[250:253], v[8:11]
	v_mfma_f32_16x16x32_bf16 v[60:63], v[176:179], v[192:195], v[60:63]
	v_mfma_f32_16x16x32_bf16 v[56:59], v[184:187], v[192:195], v[56:59]
	v_mfma_f32_16x16x32_bf16 v[36:39], v[176:179], v[210:213], v[36:39]
	v_mfma_f32_16x16x32_bf16 v[32:35], v[184:187], v[210:213], v[32:35]
	v_mfma_f32_16x16x32_bf16 v[20:23], v[176:179], v[238:241], v[20:23]
	v_mfma_f32_16x16x32_bf16 v[16:19], v[184:187], v[238:241], v[16:19]
	v_mfma_f32_16x16x32_bf16 v[4:7], v[176:179], v[246:249], v[4:7]
	v_mfma_f32_16x16x32_bf16 v[0:3], v[184:187], v[246:249], v[0:3]
	v_mfma_f32_16x16x32_bf16 v[60:63], v[180:183], v[196:199], v[60:63]
	v_mfma_f32_16x16x32_bf16 v[56:59], v[188:191], v[196:199], v[56:59]
	v_mfma_f32_16x16x32_bf16 v[36:39], v[180:183], v[214:217], v[36:39]
	v_mfma_f32_16x16x32_bf16 v[32:35], v[188:191], v[214:217], v[32:35]
	v_mfma_f32_16x16x32_bf16 v[20:23], v[180:183], v[242:245], v[20:23]
	v_mfma_f32_16x16x32_bf16 v[16:19], v[188:191], v[242:245], v[16:19]
	v_mfma_f32_16x16x32_bf16 v[4:7], v[180:183], v[250:253], v[4:7]
	v_mfma_f32_16x16x32_bf16 v[0:3], v[188:191], v[250:253], v[0:3]
	s_add_i32 s78, s78, 2
	s_add_u32 s8, s8, 0x100
	s_addc_u32 s9, s9, 0
	s_add_u32 s58, s58, 0x100
	s_addc_u32 s59, s59, 0
	s_cmp_gt_u32 s78, 13
	s_barrier
	s_cbranch_scc0 .LBB0_119
	s_setprio 0
	s_and_b64 vcc, exec, s[18:19]
	s_cbranch_vccz .LBB0_122
	s_barrier

; #define PG8_STAGE(bufoff, gbase, voff) do { _Pragma("unroll") for (int _i = 0; _i < 2; ++_i) \
;         __builtin_amdgcn_global_load_lds((const unsigned*)((const char*)(gbase) + (voff)[_i]), (PG8_LAS unsigned*)(lds + (bufoff) + ldsw + _i * 8192), 16, 0, 0); } while (0)
; #define PG8_STAGEA(bufoff, gbase, voff) do { _Pragma("unroll") for (int _i = 0; _i < 2; ++_i) \
;         __builtin_amdgcn_global_load_lds((const unsigned*)((const char*)(gbase) + (voff)[_i]), (PG8_LAS unsigned*)(lds + (bufoff) + ldsw + _i * 8192), 16, 0, AUXA); } while (0)
; #define PG8_LDA(dst, b, h) do { _Pragma("unroll") for (int m = 0; m < 4; ++m) _Pragma("unroll") for (int k = 0; k < 2; ++k) dst[m][k] = *(const PG8_LAS bf16x8*)(lds + PG8_SA(b, h) + aoff + m * 2048 + k * 1024); } while (0)
; #define PG8_LDB(dst, b, h) do { _Pragma("unroll") for (int n = 0; n < 2; ++n) _Pragma("unroll") for (int k = 0; k < 2; ++k) dst[n][k] = *(const PG8_LAS bf16x8*)(lds + PG8_SB(b, h) + boff + n * 2048 + k * 1024); } while (0)
; #define PG8_MMA(ai, bj, At, Bt) do { __builtin_amdgcn_s_setprio(1); _Pragma("unroll") for (int m = 0; m < 4; ++m) _Pragma("unroll") for (int n = 0; n < 2; ++n) _Pragma("unroll") for (int k = 0; k < 2; ++k) \
;         acc[ai][bj][m][n] = __builtin_amdgcn_mfma_f32_16x16x32_bf16(Bt[n][k], At[m][k], acc[ai][bj][m][n], 0, 0, 0); __builtin_amdgcn_s_setprio(0); } while (0)
; #define PG8_WAIT_V(n) asm volatile("s_waitcnt vmcnt(" #n ")" ::: "memory")
; #define PG8_WAIT_L(n) asm volatile("s_waitcnt lgkmcnt(" #n ")" ::: "memory")
; #define PG8_BAR __builtin_amdgcn_s_barrier()
; #define PG8_SCHED __builtin_amdgcn_sched_barrier(0)
;     ...
;             if constexpr (SP2) {
;             PG8_LDB(B0, 0, 0); PG8_LDB(B1, 0, 1); PG8_SCHED; PG8_LDA(At, 0, 0); PG8_STAGEA(PG8_SA(1, 1), a1 + hstep, voffA);
;             PG8_WAIT_V(8); PG8_WAIT_L(0); PG8_BAR; PG8_MMA(0, 0, At, B0); PG8_MMA(0, 1, At, B1); PG8_BAR; PG8_SCHED;
;             PG8_LDA(At, 0, 1); PG8_STAGE(PG8_SB(0, 0), b2, voffB); PG8_STAGE(PG8_SB(0, 1), b2 + hstepB, voffB); PG8_STAGEA(PG8_SA(0, 0), a2, voffA);
;             PG8_WAIT_V(8); PG8_WAIT_L(0); PG8_BAR; PG8_MMA(1, 0, At, B0); PG8_MMA(1, 1, At, B1); PG8_BAR; PG8_SCHED;
.Lsprio_1:
.LBB0_444:
	ds_read_b128 v[148:151], v142
	ds_read_b128 v[152:155], v142 offset:1024
	ds_read_b128 v[156:159], v142 offset:2048
	ds_read_b128 v[160:163], v142 offset:3072
	ds_read_b128 v[164:167], v143
	ds_read_b128 v[168:171], v143 offset:1024
	ds_read_b128 v[176:179], v143 offset:2048
	ds_read_b128 v[180:183], v143 offset:3072
	s_add_u32 s14, s12, 0xf25c0080
	s_addc_u32 s15, s13, -1
	s_cmp_lg_u32 s22, 12
	s_cselect_b32 s14, s14, 0
	s_cselect_b32 s15, s15, 0
	s_add_u32 s16, s8, s14
	s_addc_u32 s17, s9, s15
	s_add_u32 s14, s6, s14
	s_addc_u32 s15, s7, s15
	s_mov_b32 m0, s23
	v_lshl_add_u64 v[172:173], v[136:137], 0, s[12:13]
	ds_read_b128 v[184:187], v144
	ds_read_b128 v[188:191], v144 offset:1024
	ds_read_b128 v[192:195], v144 offset:2048
	ds_read_b128 v[196:199], v144 offset:3072
	ds_read_b128 v[202:205], v144 offset:4096
	ds_read_b128 v[210:213], v144 offset:5120
	ds_read_b128 v[214:217], v144 offset:6144
	ds_read_b128 v[218:221], v144 offset:7168
	global_load_lds_dwordx4 v[172:173], off
	v_lshl_add_u64 v[172:173], v[138:139], 0, s[12:13]
	s_mov_b32 m0, s24
	s_nop 0
	global_load_lds_dwordx4 v[172:173], off
	s_waitcnt vmcnt(8)
	s_waitcnt lgkmcnt(0)
	s_barrier
	s_waitcnt lgkmcnt(0)
	v_mfma_f32_16x16x32_bf16 v[124:127], v[148:151], v[184:187], v[124:127]
	v_mfma_f32_16x16x32_bf16 v[120:123], v[156:159], v[184:187], v[120:123]
	v_mfma_f32_16x16x32_bf16 v[108:111], v[148:151], v[192:195], v[108:111]
	v_mfma_f32_16x16x32_bf16 v[104:107], v[156:159], v[192:195], v[104:107]
	v_mfma_f32_16x16x32_bf16 v[92:95], v[148:151], v[202:205], v[92:95]
	v_mfma_f32_16x16x32_bf16 v[88:91], v[156:159], v[202:205], v[88:91]
	v_mfma_f32_16x16x32_bf16 v[76:79], v[148:151], v[214:217], v[76:79]
	v_mfma_f32_16x16x32_bf16 v[72:75], v[156:159], v[214:217], v[72:75]
	v_mfma_f32_16x16x32_bf16 v[124:127], v[152:155], v[188:191], v[124:127]
	v_mfma_f32_16x16x32_bf16 v[120:123], v[160:163], v[188:191], v[120:123]
	v_mfma_f32_16x16x32_bf16 v[108:111], v[152:155], v[196:199], v[108:111]
	v_mfma_f32_16x16x32_bf16 v[104:107], v[160:163], v[196:199], v[104:107]
	v_mfma_f32_16x16x32_bf16 v[92:95], v[152:155], v[210:213], v[92:95]
	v_mfma_f32_16x16x32_bf16 v[88:91], v[160:163], v[210:213], v[88:91]
	v_mfma_f32_16x16x32_bf16 v[76:79], v[152:155], v[218:221], v[76:79]
	v_mfma_f32_16x16x32_bf16 v[72:75], v[160:163], v[218:221], v[72:75]
	v_mfma_f32_16x16x32_bf16 v[116:119], v[164:167], v[184:187], v[116:119]
	v_mfma_f32_16x16x32_bf16 v[112:115], v[176:179], v[184:187], v[112:115]
	v_mfma_f32_16x16x32_bf16 v[100:103], v[164:167], v[192:195], v[100:103]
	v_mfma_f32_16x16x32_bf16 v[96:99], v[176:179], v[192:195], v[96:99]
	v_mfma_f32_16x16x32_bf16 v[84:87], v[164:167], v[202:205], v[84:87]
	v_mfma_f32_16x16x32_bf16 v[80:83], v[176:179], v[202:205], v[80:83]
	v_mfma_f32_16x16x32_bf16 v[68:71], v[164:167], v[214:217], v[68:71]
	v_mfma_f32_16x16x32_bf16 v[64:67], v[176:179], v[214:217], v[64:67]
	v_mfma_f32_16x16x32_bf16 v[116:119], v[168:171], v[188:191], v[116:119]
	v_mfma_f32_16x16x32_bf16 v[112:115], v[180:183], v[188:191], v[112:115]
	v_mfma_f32_16x16x32_bf16 v[100:103], v[168:171], v[196:199], v[100:103]
	v_mfma_f32_16x16x32_bf16 v[96:99], v[180:183], v[196:199], v[96:99]
	v_mfma_f32_16x16x32_bf16 v[84:87], v[168:171], v[210:213], v[84:87]
	v_mfma_f32_16x16x32_bf16 v[80:83], v[180:183], v[210:213], v[80:83]
	v_mfma_f32_16x16x32_bf16 v[68:71], v[168:171], v[218:221], v[68:71]
	v_mfma_f32_16x16x32_bf16 v[64:67], v[180:183], v[218:221], v[64:67]
	s_barrier
	s_mov_b32 m0, s25
	v_lshl_add_u64 v[172:173], s[14:15], 0, v[132:133]
	s_add_u32 s36, s14, 0x10000
	ds_read_b128 v[184:187], v144 offset:16384
	ds_read_b128 v[188:191], v144 offset:17408
	ds_read_b128 v[192:195], v144 offset:18432
	ds_read_b128 v[196:199], v144 offset:19456
	ds_read_b128 v[202:205], v144 offset:20480
	ds_read_b128 v[210:213], v144 offset:21504
	ds_read_b128 v[214:217], v144 offset:22528
	ds_read_b128 v[218:221], v144 offset:23552
	global_load_lds_dwordx4 v[172:173], off
	v_lshl_add_u64 v[206:207], s[14:15], 0, v[128:129]
	s_mov_b32 m0, s26
	s_addc_u32 s37, s15, 0
	global_load_lds_dwordx4 v[206:207], off
	v_lshl_add_u64 v[222:223], s[36:37], 0, v[132:133]
	s_mov_b32 m0, s27
	v_lshl_add_u64 v[224:225], s[16:17], 0, v[130:131]
	global_load_lds_dwordx4 v[222:223], off
	v_lshl_add_u64 v[222:223], s[36:37], 0, v[128:129]
	s_mov_b32 m0, s28
	s_nop 0
	global_load_lds_dwordx4 v[222:223], off
	v_lshl_add_u64 v[222:223], s[16:17], 0, v[134:135]
	s_mov_b32 m0, s1
	s_nop 0
	global_load_lds_dwordx4 v[222:223], off
	s_mov_b32 m0, s3
	s_nop 0
	global_load_lds_dwordx4 v[224:225], off
	s_waitcnt vmcnt(8)
	s_waitcnt lgkmcnt(0)
	s_barrier
; #define PG8_STAGE(bufoff, gbase, voff) do { _Pragma("unroll") for (int _i = 0; _i < 2; ++_i) \
;         __builtin_amdgcn_global_load_lds((const unsigned*)((const char*)(gbase) + (voff)[_i]), (PG8_LAS unsigned*)(lds + (bufoff) + ldsw + _i * 8192), 16, 0, 0); } while (0)
; #define PG8_STAGEA(bufoff, gbase, voff) do { _Pragma("unroll") for (int _i = 0; _i < 2; ++_i) \
;         __builtin_amdgcn_global_load_lds((const unsigned*)((const char*)(gbase) + (voff)[_i]), (PG8_LAS unsigned*)(lds + (bufoff) + ldsw + _i * 8192), 16, 0, AUXA); } while (0)
; #define PG8_LDA(dst, b, h) do { _Pragma("unroll") for (int m = 0; m < 4; ++m) _Pragma("unroll") for (int k = 0; k < 2; ++k) dst[m][k] = *(const PG8_LAS bf16x8*)(lds + PG8_SA(b, h) + aoff + m * 2048 + k * 1024); } while (0)
; #define PG8_LDB(dst, b, h) do { _Pragma("unroll") for (int n = 0; n < 2; ++n) _Pragma("unroll") for (int k = 0; k < 2; ++k) dst[n][k] = *(const PG8_LAS bf16x8*)(lds + PG8_SB(b, h) + boff + n * 2048 + k * 1024); } while (0)
; #define PG8_MMA(ai, bj, At, Bt) do { __builtin_amdgcn_s_setprio(1); _Pragma("unroll") for (int m = 0; m < 4; ++m) _Pragma("unroll") for (int n = 0; n < 2; ++n) _Pragma("unroll") for (int k = 0; k < 2; ++k) \
;         acc[ai][bj][m][n] = __builtin_amdgcn_mfma_f32_16x16x32_bf16(Bt[n][k], At[m][k], acc[ai][bj][m][n], 0, 0, 0); __builtin_amdgcn_s_setprio(0); } while (0)
; #define PG8_WAIT_V(n) asm volatile("s_waitcnt vmcnt(" #n ")" ::: "memory")
; #define PG8_WAIT_L(n) asm volatile("s_waitcnt lgkmcnt(" #n ")" ::: "memory")
; #define PG8_BAR __builtin_amdgcn_s_barrier()
; #define PG8_SCHED __builtin_amdgcn_sched_barrier(0)
;     ...
;             PG8_WAIT_V(8); PG8_WAIT_L(0); PG8_BAR; PG8_MMA(0, 0, At, B0); PG8_MMA(0, 1, At, B1); PG8_BAR; PG8_SCHED;
;             PG8_LDA(At, 0, 1); PG8_STAGE(PG8_SB(0, 0), b2, voffB); PG8_STAGE(PG8_SB(0, 1), b2 + hstepB, voffB); PG8_STAGEA(PG8_SA(0, 0), a2, voffA);
;             PG8_WAIT_V(8); PG8_WAIT_L(0); PG8_BAR; PG8_MMA(1, 0, At, B0); PG8_MMA(1, 1, At, B1); PG8_BAR; PG8_SCHED;
;             PG8_LDB(B0, 1, 0); PG8_LDB(B1, 1, 1); PG8_SCHED; PG8_LDA(At, 1, 0); PG8_STAGEA(PG8_SA(0, 1), a2 + hstep, voffA);
;             PG8_WAIT_V(8); PG8_WAIT_L(0); PG8_BAR; PG8_MMA(0, 0, At, B0); PG8_MMA(0, 1, At, B1); PG8_BAR; PG8_SCHED;
	s_waitcnt lgkmcnt(0)
	v_mfma_f32_16x16x32_bf16 v[60:63], v[148:151], v[184:187], v[60:63]
	v_mfma_f32_16x16x32_bf16 v[56:59], v[156:159], v[184:187], v[56:59]
	v_mfma_f32_16x16x32_bf16 v[44:47], v[148:151], v[192:195], v[44:47]
	v_mfma_f32_16x16x32_bf16 v[40:43], v[156:159], v[192:195], v[40:43]
	v_mfma_f32_16x16x32_bf16 v[28:31], v[148:151], v[202:205], v[28:31]
	v_mfma_f32_16x16x32_bf16 v[24:27], v[156:159], v[202:205], v[24:27]
	v_mfma_f32_16x16x32_bf16 v[12:15], v[148:151], v[214:217], v[12:15]
	v_mfma_f32_16x16x32_bf16 v[8:11], v[156:159], v[214:217], v[8:11]
	v_mfma_f32_16x16x32_bf16 v[60:63], v[152:155], v[188:191], v[60:63]
	v_mfma_f32_16x16x32_bf16 v[56:59], v[160:163], v[188:191], v[56:59]
	v_mfma_f32_16x16x32_bf16 v[44:47], v[152:155], v[196:199], v[44:47]
	v_mfma_f32_16x16x32_bf16 v[40:43], v[160:163], v[196:199], v[40:43]
	v_mfma_f32_16x16x32_bf16 v[28:31], v[152:155], v[210:213], v[28:31]
	v_mfma_f32_16x16x32_bf16 v[24:27], v[160:163], v[210:213], v[24:27]
	v_mfma_f32_16x16x32_bf16 v[12:15], v[152:155], v[218:221], v[12:15]
	v_mfma_f32_16x16x32_bf16 v[8:11], v[160:163], v[218:221], v[8:11]
	v_mfma_f32_16x16x32_bf16 v[52:55], v[164:167], v[184:187], v[52:55]
	v_mfma_f32_16x16x32_bf16 v[48:51], v[176:179], v[184:187], v[48:51]
	v_mfma_f32_16x16x32_bf16 v[36:39], v[164:167], v[192:195], v[36:39]
	v_mfma_f32_16x16x32_bf16 v[32:35], v[176:179], v[192:195], v[32:35]
	v_mfma_f32_16x16x32_bf16 v[20:23], v[164:167], v[202:205], v[20:23]
	v_mfma_f32_16x16x32_bf16 v[16:19], v[176:179], v[202:205], v[16:19]
	v_mfma_f32_16x16x32_bf16 v[4:7], v[164:167], v[214:217], v[4:7]
	v_mfma_f32_16x16x32_bf16 v[0:3], v[176:179], v[214:217], v[0:3]
	v_mfma_f32_16x16x32_bf16 v[52:55], v[168:171], v[188:191], v[52:55]
	v_mfma_f32_16x16x32_bf16 v[48:51], v[180:183], v[188:191], v[48:51]
	v_mfma_f32_16x16x32_bf16 v[36:39], v[168:171], v[196:199], v[36:39]
	v_mfma_f32_16x16x32_bf16 v[32:35], v[180:183], v[196:199], v[32:35]
	v_mfma_f32_16x16x32_bf16 v[20:23], v[168:171], v[210:213], v[20:23]
	v_mfma_f32_16x16x32_bf16 v[16:19], v[180:183], v[210:213], v[16:19]
	v_mfma_f32_16x16x32_bf16 v[4:7], v[168:171], v[218:221], v[4:7]
	v_mfma_f32_16x16x32_bf16 v[0:3], v[180:183], v[218:221], v[0:3]
	s_barrier
	ds_read_b128 v[148:151], v145
	ds_read_b128 v[152:155], v145 offset:1024
	ds_read_b128 v[156:159], v145 offset:2048
	ds_read_b128 v[160:163], v145 offset:3072
	ds_read_b128 v[164:167], v146
	ds_read_b128 v[168:171], v146 offset:1024
	ds_read_b128 v[176:179], v146 offset:2048
	ds_read_b128 v[180:183], v146 offset:3072
	s_add_u32 s16, s16, 0x40000
	s_addc_u32 s17, s17, 0
	s_mov_b32 m0, s18
	v_lshl_add_u64 v[226:227], s[16:17], 0, v[134:135]
	ds_read_b128 v[184:187], v144 offset:32768
	ds_read_b128 v[188:191], v144 offset:33792
	ds_read_b128 v[192:195], v144 offset:34816
	ds_read_b128 v[196:199], v144 offset:35840
	ds_read_b128 v[202:205], v144 offset:36864
	ds_read_b128 v[210:213], v144 offset:37888
	ds_read_b128 v[214:217], v144 offset:38912
	ds_read_b128 v[218:221], v144 offset:39936
	global_load_lds_dwordx4 v[226:227], off
	v_lshl_add_u64 v[226:227], s[16:17], 0, v[130:131]
	s_mov_b32 m0, s19
	s_nop 0
	global_load_lds_dwordx4 v[226:227], off
	s_waitcnt vmcnt(8)
	s_waitcnt lgkmcnt(0)
	s_barrier
	s_waitcnt lgkmcnt(0)
	v_mfma_f32_16x16x32_bf16 v[124:127], v[148:151], v[184:187], v[124:127]
	v_mfma_f32_16x16x32_bf16 v[120:123], v[156:159], v[184:187], v[120:123]
	v_mfma_f32_16x16x32_bf16 v[108:111], v[148:151], v[192:195], v[108:111]
	v_mfma_f32_16x16x32_bf16 v[104:107], v[156:159], v[192:195], v[104:107]
	v_mfma_f32_16x16x32_bf16 v[92:95], v[148:151], v[202:205], v[92:95]
	v_mfma_f32_16x16x32_bf16 v[88:91], v[156:159], v[202:205], v[88:91]
	v_mfma_f32_16x16x32_bf16 v[76:79], v[148:151], v[214:217], v[76:79]
	v_mfma_f32_16x16x32_bf16 v[72:75], v[156:159], v[214:217], v[72:75]
	v_mfma_f32_16x16x32_bf16 v[124:127], v[152:155], v[188:191], v[124:127]
	v_mfma_f32_16x16x32_bf16 v[120:123], v[160:163], v[188:191], v[120:123]
	v_mfma_f32_16x16x32_bf16 v[108:111], v[152:155], v[196:199], v[108:111]
	v_mfma_f32_16x16x32_bf16 v[104:107], v[160:163], v[196:199], v[104:107]
	v_mfma_f32_16x16x32_bf16 v[92:95], v[152:155], v[210:213], v[92:95]
	v_mfma_f32_16x16x32_bf16 v[88:91], v[160:163], v[210:213], v[88:91]
	v_mfma_f32_16x16x32_bf16 v[76:79], v[152:155], v[218:221], v[76:79]
	v_mfma_f32_16x16x32_bf16 v[72:75], v[160:163], v[218:221], v[72:75]
	v_mfma_f32_16x16x32_bf16 v[116:119], v[164:167], v[184:187], v[116:119]
	v_mfma_f32_16x16x32_bf16 v[112:115], v[176:179], v[184:187], v[112:115]
	v_mfma_f32_16x16x32_bf16 v[100:103], v[164:167], v[192:195], v[100:103]
	v_mfma_f32_16x16x32_bf16 v[96:99], v[176:179], v[192:195], v[96:99]
	v_mfma_f32_16x16x32_bf16 v[84:87], v[164:167], v[202:205], v[84:87]
	v_mfma_f32_16x16x32_bf16 v[80:83], v[176:179], v[202:205], v[80:83]
	v_mfma_f32_16x16x32_bf16 v[68:71], v[164:167], v[214:217], v[68:71]
	v_mfma_f32_16x16x32_bf16 v[64:67], v[176:179], v[214:217], v[64:67]
	v_mfma_f32_16x16x32_bf16 v[116:119], v[168:171], v[188:191], v[116:119]
	v_mfma_f32_16x16x32_bf16 v[112:115], v[180:183], v[188:191], v[112:115]
	v_mfma_f32_16x16x32_bf16 v[100:103], v[168:171], v[196:199], v[100:103]
	v_mfma_f32_16x16x32_bf16 v[96:99], v[180:183], v[196:199], v[96:99]
	v_mfma_f32_16x16x32_bf16 v[84:87], v[168:171], v[210:213], v[84:87]
	v_mfma_f32_16x16x32_bf16 v[80:83], v[180:183], v[210:213], v[80:83]
	v_mfma_f32_16x16x32_bf16 v[68:71], v[168:171], v[218:221], v[68:71]
	v_mfma_f32_16x16x32_bf16 v[64:67], v[180:183], v[218:221], v[64:67]
	s_barrier
; #define PG8_STAGE(bufoff, gbase, voff) do { _Pragma("unroll") for (int _i = 0; _i < 2; ++_i) \
;         __builtin_amdgcn_global_load_lds((const unsigned*)((const char*)(gbase) + (voff)[_i]), (PG8_LAS unsigned*)(lds + (bufoff) + ldsw + _i * 8192), 16, 0, 0); } while (0)
; #define PG8_STAGEA(bufoff, gbase, voff) do { _Pragma("unroll") for (int _i = 0; _i < 2; ++_i) \
;         __builtin_amdgcn_global_load_lds((const unsigned*)((const char*)(gbase) + (voff)[_i]), (PG8_LAS unsigned*)(lds + (bufoff) + ldsw + _i * 8192), 16, 0, AUXA); } while (0)
; #define PG8_LDA(dst, b, h) do { _Pragma("unroll") for (int m = 0; m < 4; ++m) _Pragma("unroll") for (int k = 0; k < 2; ++k) dst[m][k] = *(const PG8_LAS bf16x8*)(lds + PG8_SA(b, h) + aoff + m * 2048 + k * 1024); } while (0)
; #define PG8_WAIT_V(n) asm volatile("s_waitcnt vmcnt(" #n ")" ::: "memory")
; #define PG8_BAR __builtin_amdgcn_s_barrier()
;     ...
;         for (int t = 0; t < nt; t += 2) {
;             const bool last = (t == nt - 2);
;             const char* a1 = cA + (size_t)(t + 1) * kstep;
;             const char* a2 = last ? nA : cA + (size_t)(t + 2) * kstep; const char* b2 = last ? nB : cB + (size_t)(t + 2) * kstep;
;             const char* a3 = a2 + kstep; const char* b3 = b2 + kstep;
;             if (last && has_next) S.a_ready(nxt);
;             if constexpr (SP2) {
;             PG8_LDB(B0, 0, 0); PG8_LDB(B1, 0, 1); PG8_SCHED; PG8_LDA(At, 0, 0); PG8_STAGEA(PG8_SA(1, 1), a1 + hstep, voffA);
;             PG8_WAIT_V(8); PG8_WAIT_L(0); PG8_BAR; PG8_MMA(0, 0, At, B0); PG8_MMA(0, 1, At, B1); PG8_BAR; PG8_SCHED;
;             PG8_LDA(At, 0, 1); PG8_STAGE(PG8_SB(0, 0), b2, voffB); PG8_STAGE(PG8_SB(0, 1), b2 + hstepB, voffB); PG8_STAGEA(PG8_SA(0, 0), a2, voffA);
;             PG8_WAIT_V(8); PG8_WAIT_L(0); PG8_BAR; PG8_MMA(1, 0, At, B0); PG8_MMA(1, 1, At, B1); PG8_BAR; PG8_SCHED;
;             PG8_LDB(B0, 1, 0); PG8_LDB(B1, 1, 1); PG8_SCHED; PG8_LDA(At, 1, 0); PG8_STAGEA(PG8_SA(0, 1), a2 + hstep, voffA);
;             PG8_WAIT_V(8); PG8_WAIT_L(0); PG8_BAR; PG8_MMA(0, 0, At, B0); PG8_MMA(0, 1, At, B1); PG8_BAR; PG8_SCHED;
;             PG8_LDA(At, 1, 1); PG8_STAGE(PG8_SB(1, 0), b3, voffB); PG8_STAGE(PG8_SB(1, 1), b3 + hstepB, voffB); PG8_STAGEA(PG8_SA(1, 0), a3, voffA);
;             PG8_WAIT_V(8); PG8_WAIT_L(0); PG8_BAR; PG8_MMA(1, 0, At, B0); PG8_MMA(1, 1, At, B1); PG8_BAR; PG8_SCHED;
	s_mov_b32 m0, s29
	v_lshl_add_u64 v[172:173], v[172:173], 0, s[10:11]
	s_add_u32 s14, s14, 0x10080
	ds_read_b128 v[184:187], v144 offset:49152
	ds_read_b128 v[188:191], v144 offset:50176
	ds_read_b128 v[192:195], v144 offset:51200
	ds_read_b128 v[196:199], v144 offset:52224
	ds_read_b128 v[202:205], v144 offset:53248
	ds_read_b128 v[210:213], v144 offset:54272
	ds_read_b128 v[214:217], v144 offset:55296
	ds_read_b128 v[218:221], v144 offset:56320
	global_load_lds_dwordx4 v[172:173], off
	v_lshl_add_u64 v[172:173], v[206:207], 0, s[10:11]
	s_mov_b32 m0, s30
	s_addc_u32 s15, s15, 0
	global_load_lds_dwordx4 v[172:173], off
	v_lshl_add_u64 v[172:173], s[14:15], 0, v[132:133]
	s_mov_b32 m0, s31
	s_nop 0
	global_load_lds_dwordx4 v[172:173], off
	v_lshl_add_u64 v[172:173], s[14:15], 0, v[128:129]
	s_mov_b32 m0, s34
	s_nop 0
	global_load_lds_dwordx4 v[172:173], off
	v_lshl_add_u64 v[172:173], v[222:223], 0, s[10:11]
	s_mov_b32 m0, s20
	s_nop 0
	global_load_lds_dwordx4 v[172:173], off
	v_lshl_add_u64 v[172:173], v[224:225], 0, s[10:11]
	s_mov_b32 m0, s21
	s_nop 0
	global_load_lds_dwordx4 v[172:173], off
	s_waitcnt vmcnt(8)
	s_waitcnt lgkmcnt(0)
	s_barrier
	s_waitcnt lgkmcnt(0)
	v_mfma_f32_16x16x32_bf16 v[60:63], v[148:151], v[184:187], v[60:63]
	v_mfma_f32_16x16x32_bf16 v[56:59], v[156:159], v[184:187], v[56:59]
	v_mfma_f32_16x16x32_bf16 v[44:47], v[148:151], v[192:195], v[44:47]
	v_mfma_f32_16x16x32_bf16 v[40:43], v[156:159], v[192:195], v[40:43]
	v_mfma_f32_16x16x32_bf16 v[28:31], v[148:151], v[202:205], v[28:31]
	v_mfma_f32_16x16x32_bf16 v[24:27], v[156:159], v[202:205], v[24:27]
	v_mfma_f32_16x16x32_bf16 v[12:15], v[148:151], v[214:217], v[12:15]
	v_mfma_f32_16x16x32_bf16 v[8:11], v[156:159], v[214:217], v[8:11]
	v_mfma_f32_16x16x32_bf16 v[60:63], v[152:155], v[188:191], v[60:63]
	v_mfma_f32_16x16x32_bf16 v[56:59], v[160:163], v[188:191], v[56:59]
	v_mfma_f32_16x16x32_bf16 v[44:47], v[152:155], v[196:199], v[44:47]
	v_mfma_f32_16x16x32_bf16 v[40:43], v[160:163], v[196:199], v[40:43]
	v_mfma_f32_16x16x32_bf16 v[28:31], v[152:155], v[210:213], v[28:31]
	v_mfma_f32_16x16x32_bf16 v[24:27], v[160:163], v[210:213], v[24:27]
	v_mfma_f32_16x16x32_bf16 v[12:15], v[152:155], v[218:221], v[12:15]
	v_mfma_f32_16x16x32_bf16 v[8:11], v[160:163], v[218:221], v[8:11]
	v_mfma_f32_16x16x32_bf16 v[52:55], v[164:167], v[184:187], v[52:55]
	v_mfma_f32_16x16x32_bf16 v[48:51], v[176:179], v[184:187], v[48:51]
	v_mfma_f32_16x16x32_bf16 v[36:39], v[164:167], v[192:195], v[36:39]
	v_mfma_f32_16x16x32_bf16 v[32:35], v[176:179], v[192:195], v[32:35]
	v_mfma_f32_16x16x32_bf16 v[20:23], v[164:167], v[202:205], v[20:23]
	v_mfma_f32_16x16x32_bf16 v[16:19], v[176:179], v[202:205], v[16:19]
	v_mfma_f32_16x16x32_bf16 v[4:7], v[164:167], v[214:217], v[4:7]
	v_mfma_f32_16x16x32_bf16 v[0:3], v[176:179], v[214:217], v[0:3]
	v_mfma_f32_16x16x32_bf16 v[52:55], v[168:171], v[188:191], v[52:55]
	v_mfma_f32_16x16x32_bf16 v[48:51], v[180:183], v[188:191], v[48:51]
	v_mfma_f32_16x16x32_bf16 v[36:39], v[168:171], v[196:199], v[36:39]
	v_mfma_f32_16x16x32_bf16 v[32:35], v[180:183], v[196:199], v[32:35]
	v_mfma_f32_16x16x32_bf16 v[20:23], v[168:171], v[210:213], v[20:23]
	v_mfma_f32_16x16x32_bf16 v[16:19], v[180:183], v[210:213], v[16:19]
	v_mfma_f32_16x16x32_bf16 v[4:7], v[168:171], v[218:221], v[4:7]
	v_mfma_f32_16x16x32_bf16 v[0:3], v[180:183], v[218:221], v[0:3]
	s_add_i32 s22, s22, 2
	s_add_u32 s12, s12, 0x100
	s_addc_u32 s13, s13, 0
	s_cmp_gt_u32 s22, 13
	s_barrier
	s_cbranch_scc0 .LBB0_444
	s_setprio 0
	v_readlane_b32 s1, v255, 10
	s_cmpk_lt_u32 s1, 0x100
	s_cbranch_scc0 .LBB0_447
	s_barrier

; #define PG8_STAGE(bufoff, gbase, voff) do { _Pragma("unroll") for (int _i = 0; _i < 2; ++_i) \
;         __builtin_amdgcn_global_load_lds((const unsigned*)((const char*)(gbase) + (voff)[_i]), (PG8_LAS unsigned*)(lds + (bufoff) + ldsw + _i * 8192), 16, 0, 0); } while (0)
; #define PG8_STAGEA(bufoff, gbase, voff) do { _Pragma("unroll") for (int _i = 0; _i < 2; ++_i) \
;         __builtin_amdgcn_global_load_lds((const unsigned*)((const char*)(gbase) + (voff)[_i]), (PG8_LAS unsigned*)(lds + (bufoff) + ldsw + _i * 8192), 16, 0, AUXA); } while (0)
; #define PG8_LDA(dst, b, h) do { _Pragma("unroll") for (int m = 0; m < 4; ++m) _Pragma("unroll") for (int k = 0; k < 2; ++k) dst[m][k] = *(const PG8_LAS bf16x8*)(lds + PG8_SA(b, h) + aoff + m * 2048 + k * 1024); } while (0)
; #define PG8_LDB(dst, b, h) do { _Pragma("unroll") for (int n = 0; n < 2; ++n) _Pragma("unroll") for (int k = 0; k < 2; ++k) dst[n][k] = *(const PG8_LAS bf16x8*)(lds + PG8_SB(b, h) + boff + n * 2048 + k * 1024); } while (0)
; #define PG8_MMA(ai, bj, At, Bt) do { __builtin_amdgcn_s_setprio(1); _Pragma("unroll") for (int m = 0; m < 4; ++m) _Pragma("unroll") for (int n = 0; n < 2; ++n) _Pragma("unroll") for (int k = 0; k < 2; ++k) \
;         acc[ai][bj][m][n] = __builtin_amdgcn_mfma_f32_16x16x32_bf16(Bt[n][k], At[m][k], acc[ai][bj][m][n], 0, 0, 0); __builtin_amdgcn_s_setprio(0); } while (0)
; #define PG8_WAIT_V(n) asm volatile("s_waitcnt vmcnt(" #n ")" ::: "memory")
; #define PG8_WAIT_L(n) asm volatile("s_waitcnt lgkmcnt(" #n ")" ::: "memory")
; #define PG8_BAR __builtin_amdgcn_s_barrier()
; #define PG8_SCHED __builtin_amdgcn_sched_barrier(0)
;     ...
;             if constexpr (SP2) {
;             PG8_LDB(B0, 0, 0); PG8_LDB(B1, 0, 1); PG8_SCHED; PG8_LDA(At, 0, 0); PG8_STAGEA(PG8_SA(1, 1), a1 + hstep, voffA);
;             PG8_WAIT_V(8); PG8_WAIT_L(0); PG8_BAR; PG8_MMA(0, 0, At, B0); PG8_MMA(0, 1, At, B1); PG8_BAR; PG8_SCHED;
;             PG8_LDA(At, 0, 1); PG8_STAGE(PG8_SB(0, 0), b2, voffB); PG8_STAGE(PG8_SB(0, 1), b2 + hstepB, voffB); PG8_STAGEA(PG8_SA(0, 0), a2, voffA);
;             PG8_WAIT_V(8); PG8_WAIT_L(0); PG8_BAR; PG8_MMA(1, 0, At, B0); PG8_MMA(1, 1, At, B1); PG8_BAR; PG8_SCHED;
.Lsprio_2:
.LBB0_758:
	ds_read_b128 v[148:151], v142
	ds_read_b128 v[152:155], v142 offset:1024
	ds_read_b128 v[156:159], v142 offset:2048
	ds_read_b128 v[160:163], v142 offset:3072
	ds_read_b128 v[164:167], v143
	ds_read_b128 v[168:171], v143 offset:1024
	ds_read_b128 v[176:179], v143 offset:2048
	ds_read_b128 v[180:183], v143 offset:3072
	s_add_u32 s14, s12, 0xf03c0080
	s_addc_u32 s15, s13, -1
	s_cmp_lg_u32 s22, 12
	s_cselect_b32 s14, s14, 0
	s_cselect_b32 s15, s15, 0
	s_add_u32 s16, s8, s14
	s_addc_u32 s17, s9, s15
	s_add_u32 s14, s6, s14
	s_addc_u32 s15, s7, s15
	s_mov_b32 m0, s23
	v_lshl_add_u64 v[172:173], v[138:139], 0, s[12:13]
	ds_read_b128 v[184:187], v144
	ds_read_b128 v[188:191], v144 offset:1024
	ds_read_b128 v[192:195], v144 offset:2048
	ds_read_b128 v[196:199], v144 offset:3072
	ds_read_b128 v[202:205], v144 offset:4096
	ds_read_b128 v[210:213], v144 offset:5120
	ds_read_b128 v[214:217], v144 offset:6144
	ds_read_b128 v[218:221], v144 offset:7168
	global_load_lds_dwordx4 v[172:173], off
	v_lshl_add_u64 v[172:173], v[140:141], 0, s[12:13]
	s_mov_b32 m0, s24
	s_nop 0
	global_load_lds_dwordx4 v[172:173], off
	s_waitcnt vmcnt(8)
	s_waitcnt lgkmcnt(0)
	s_barrier
	s_waitcnt lgkmcnt(0)
	v_mfma_f32_16x16x32_bf16 v[124:127], v[148:151], v[184:187], v[124:127]
	v_mfma_f32_16x16x32_bf16 v[120:123], v[156:159], v[184:187], v[120:123]
	v_mfma_f32_16x16x32_bf16 v[108:111], v[148:151], v[192:195], v[108:111]
	v_mfma_f32_16x16x32_bf16 v[104:107], v[156:159], v[192:195], v[104:107]
	v_mfma_f32_16x16x32_bf16 v[92:95], v[148:151], v[202:205], v[92:95]
	v_mfma_f32_16x16x32_bf16 v[88:91], v[156:159], v[202:205], v[88:91]
	v_mfma_f32_16x16x32_bf16 v[76:79], v[148:151], v[214:217], v[76:79]
	v_mfma_f32_16x16x32_bf16 v[72:75], v[156:159], v[214:217], v[72:75]
	v_mfma_f32_16x16x32_bf16 v[124:127], v[152:155], v[188:191], v[124:127]
	v_mfma_f32_16x16x32_bf16 v[120:123], v[160:163], v[188:191], v[120:123]
	v_mfma_f32_16x16x32_bf16 v[108:111], v[152:155], v[196:199], v[108:111]
	v_mfma_f32_16x16x32_bf16 v[104:107], v[160:163], v[196:199], v[104:107]
	v_mfma_f32_16x16x32_bf16 v[92:95], v[152:155], v[210:213], v[92:95]
	v_mfma_f32_16x16x32_bf16 v[88:91], v[160:163], v[210:213], v[88:91]
	v_mfma_f32_16x16x32_bf16 v[76:79], v[152:155], v[218:221], v[76:79]
	v_mfma_f32_16x16x32_bf16 v[72:75], v[160:163], v[218:221], v[72:75]
	v_mfma_f32_16x16x32_bf16 v[116:119], v[164:167], v[184:187], v[116:119]
	v_mfma_f32_16x16x32_bf16 v[112:115], v[176:179], v[184:187], v[112:115]
	v_mfma_f32_16x16x32_bf16 v[100:103], v[164:167], v[192:195], v[100:103]
	v_mfma_f32_16x16x32_bf16 v[96:99], v[176:179], v[192:195], v[96:99]
	v_mfma_f32_16x16x32_bf16 v[84:87], v[164:167], v[202:205], v[84:87]
	v_mfma_f32_16x16x32_bf16 v[80:83], v[176:179], v[202:205], v[80:83]
	v_mfma_f32_16x16x32_bf16 v[68:71], v[164:167], v[214:217], v[68:71]
	v_mfma_f32_16x16x32_bf16 v[64:67], v[176:179], v[214:217], v[64:67]
	v_mfma_f32_16x16x32_bf16 v[116:119], v[168:171], v[188:191], v[116:119]
	v_mfma_f32_16x16x32_bf16 v[112:115], v[180:183], v[188:191], v[112:115]
	v_mfma_f32_16x16x32_bf16 v[100:103], v[168:171], v[196:199], v[100:103]
	v_mfma_f32_16x16x32_bf16 v[96:99], v[180:183], v[196:199], v[96:99]
	v_mfma_f32_16x16x32_bf16 v[84:87], v[168:171], v[210:213], v[84:87]
	v_mfma_f32_16x16x32_bf16 v[80:83], v[180:183], v[210:213], v[80:83]
	v_mfma_f32_16x16x32_bf16 v[68:71], v[168:171], v[218:221], v[68:71]
	v_mfma_f32_16x16x32_bf16 v[64:67], v[180:183], v[218:221], v[64:67]
	s_barrier
	s_mov_b32 m0, s25
	v_lshl_add_u64 v[172:173], s[14:15], 0, v[134:135]
	s_add_u32 s36, s14, 0x10000
	ds_read_b128 v[184:187], v144 offset:16384
	ds_read_b128 v[188:191], v144 offset:17408
	ds_read_b128 v[192:195], v144 offset:18432
	ds_read_b128 v[196:199], v144 offset:19456
	ds_read_b128 v[202:205], v144 offset:20480
	ds_read_b128 v[210:213], v144 offset:21504
	ds_read_b128 v[214:217], v144 offset:22528
	ds_read_b128 v[218:221], v144 offset:23552
	global_load_lds_dwordx4 v[172:173], off
	v_lshl_add_u64 v[206:207], s[14:15], 0, v[130:131]
	s_mov_b32 m0, s26
	s_addc_u32 s37, s15, 0
	global_load_lds_dwordx4 v[206:207], off
	v_lshl_add_u64 v[222:223], s[36:37], 0, v[134:135]
	s_mov_b32 m0, s27
	v_lshl_add_u64 v[224:225], s[16:17], 0, v[132:133]
	global_load_lds_dwordx4 v[222:223], off
	v_lshl_add_u64 v[222:223], s[36:37], 0, v[130:131]
	s_mov_b32 m0, s28
	s_nop 0
	global_load_lds_dwordx4 v[222:223], off
	v_lshl_add_u64 v[222:223], s[16:17], 0, v[136:137]
	s_mov_b32 m0, s1
	s_nop 0
	global_load_lds_dwordx4 v[222:223], off
	s_mov_b32 m0, s5
	s_nop 0
	global_load_lds_dwordx4 v[224:225], off
	s_waitcnt vmcnt(8)
	s_waitcnt lgkmcnt(0)
	s_barrier
; #define PG8_STAGE(bufoff, gbase, voff) do { _Pragma("unroll") for (int _i = 0; _i < 2; ++_i) \
;         __builtin_amdgcn_global_load_lds((const unsigned*)((const char*)(gbase) + (voff)[_i]), (PG8_LAS unsigned*)(lds + (bufoff) + ldsw + _i * 8192), 16, 0, 0); } while (0)
; #define PG8_STAGEA(bufoff, gbase, voff) do { _Pragma("unroll") for (int _i = 0; _i < 2; ++_i) \
;         __builtin_amdgcn_global_load_lds((const unsigned*)((const char*)(gbase) + (voff)[_i]), (PG8_LAS unsigned*)(lds + (bufoff) + ldsw + _i * 8192), 16, 0, AUXA); } while (0)
; #define PG8_LDA(dst, b, h) do { _Pragma("unroll") for (int m = 0; m < 4; ++m) _Pragma("unroll") for (int k = 0; k < 2; ++k) dst[m][k] = *(const PG8_LAS bf16x8*)(lds + PG8_SA(b, h) + aoff + m * 2048 + k * 1024); } while (0)
; #define PG8_LDB(dst, b, h) do { _Pragma("unroll") for (int n = 0; n < 2; ++n) _Pragma("unroll") for (int k = 0; k < 2; ++k) dst[n][k] = *(const PG8_LAS bf16x8*)(lds + PG8_SB(b, h) + boff + n * 2048 + k * 1024); } while (0)
; #define PG8_MMA(ai, bj, At, Bt) do { __builtin_amdgcn_s_setprio(1); _Pragma("unroll") for (int m = 0; m < 4; ++m) _Pragma("unroll") for (int n = 0; n < 2; ++n) _Pragma("unroll") for (int k = 0; k < 2; ++k) \
;         acc[ai][bj][m][n] = __builtin_amdgcn_mfma_f32_16x16x32_bf16(Bt[n][k], At[m][k], acc[ai][bj][m][n], 0, 0, 0); __builtin_amdgcn_s_setprio(0); } while (0)
; #define PG8_WAIT_V(n) asm volatile("s_waitcnt vmcnt(" #n ")" ::: "memory")
; #define PG8_WAIT_L(n) asm volatile("s_waitcnt lgkmcnt(" #n ")" ::: "memory")
; #define PG8_BAR __builtin_amdgcn_s_barrier()
; #define PG8_SCHED __builtin_amdgcn_sched_barrier(0)
;     ...
;             PG8_WAIT_V(8); PG8_WAIT_L(0); PG8_BAR; PG8_MMA(0, 0, At, B0); PG8_MMA(0, 1, At, B1); PG8_BAR; PG8_SCHED;
;             PG8_LDA(At, 0, 1); PG8_STAGE(PG8_SB(0, 0), b2, voffB); PG8_STAGE(PG8_SB(0, 1), b2 + hstepB, voffB); PG8_STAGEA(PG8_SA(0, 0), a2, voffA);
;             PG8_WAIT_V(8); PG8_WAIT_L(0); PG8_BAR; PG8_MMA(1, 0, At, B0); PG8_MMA(1, 1, At, B1); PG8_BAR; PG8_SCHED;
;             PG8_LDB(B0, 1, 0); PG8_LDB(B1, 1, 1); PG8_SCHED; PG8_LDA(At, 1, 0); PG8_STAGEA(PG8_SA(0, 1), a2 + hstep, voffA);
;             PG8_WAIT_V(8); PG8_WAIT_L(0); PG8_BAR; PG8_MMA(0, 0, At, B0); PG8_MMA(0, 1, At, B1); PG8_BAR; PG8_SCHED;
	s_waitcnt lgkmcnt(0)
	v_mfma_f32_16x16x32_bf16 v[60:63], v[148:151], v[184:187], v[60:63]
	v_mfma_f32_16x16x32_bf16 v[56:59], v[156:159], v[184:187], v[56:59]
	v_mfma_f32_16x16x32_bf16 v[44:47], v[148:151], v[192:195], v[44:47]
	v_mfma_f32_16x16x32_bf16 v[40:43], v[156:159], v[192:195], v[40:43]
	v_mfma_f32_16x16x32_bf16 v[28:31], v[148:151], v[202:205], v[28:31]
	v_mfma_f32_16x16x32_bf16 v[24:27], v[156:159], v[202:205], v[24:27]
	v_mfma_f32_16x16x32_bf16 v[12:15], v[148:151], v[214:217], v[12:15]
	v_mfma_f32_16x16x32_bf16 v[8:11], v[156:159], v[214:217], v[8:11]
	v_mfma_f32_16x16x32_bf16 v[60:63], v[152:155], v[188:191], v[60:63]
	v_mfma_f32_16x16x32_bf16 v[56:59], v[160:163], v[188:191], v[56:59]
	v_mfma_f32_16x16x32_bf16 v[44:47], v[152:155], v[196:199], v[44:47]
	v_mfma_f32_16x16x32_bf16 v[40:43], v[160:163], v[196:199], v[40:43]
	v_mfma_f32_16x16x32_bf16 v[28:31], v[152:155], v[210:213], v[28:31]
	v_mfma_f32_16x16x32_bf16 v[24:27], v[160:163], v[210:213], v[24:27]
	v_mfma_f32_16x16x32_bf16 v[12:15], v[152:155], v[218:221], v[12:15]
	v_mfma_f32_16x16x32_bf16 v[8:11], v[160:163], v[218:221], v[8:11]
	v_mfma_f32_16x16x32_bf16 v[52:55], v[164:167], v[184:187], v[52:55]
	v_mfma_f32_16x16x32_bf16 v[48:51], v[176:179], v[184:187], v[48:51]
	v_mfma_f32_16x16x32_bf16 v[36:39], v[164:167], v[192:195], v[36:39]
	v_mfma_f32_16x16x32_bf16 v[32:35], v[176:179], v[192:195], v[32:35]
	v_mfma_f32_16x16x32_bf16 v[20:23], v[164:167], v[202:205], v[20:23]
	v_mfma_f32_16x16x32_bf16 v[16:19], v[176:179], v[202:205], v[16:19]
	v_mfma_f32_16x16x32_bf16 v[4:7], v[164:167], v[214:217], v[4:7]
	v_mfma_f32_16x16x32_bf16 v[0:3], v[176:179], v[214:217], v[0:3]
	v_mfma_f32_16x16x32_bf16 v[52:55], v[168:171], v[188:191], v[52:55]
	v_mfma_f32_16x16x32_bf16 v[48:51], v[180:183], v[188:191], v[48:51]
	v_mfma_f32_16x16x32_bf16 v[36:39], v[168:171], v[196:199], v[36:39]
	v_mfma_f32_16x16x32_bf16 v[32:35], v[180:183], v[196:199], v[32:35]
	v_mfma_f32_16x16x32_bf16 v[20:23], v[168:171], v[210:213], v[20:23]
	v_mfma_f32_16x16x32_bf16 v[16:19], v[180:183], v[210:213], v[16:19]
	v_mfma_f32_16x16x32_bf16 v[4:7], v[168:171], v[218:221], v[4:7]
	v_mfma_f32_16x16x32_bf16 v[0:3], v[180:183], v[218:221], v[0:3]
	s_barrier
	ds_read_b128 v[148:151], v145
	ds_read_b128 v[152:155], v145 offset:1024
	ds_read_b128 v[156:159], v145 offset:2048
	ds_read_b128 v[160:163], v145 offset:3072
	ds_read_b128 v[164:167], v146
	ds_read_b128 v[168:171], v146 offset:1024
	ds_read_b128 v[176:179], v146 offset:2048
	ds_read_b128 v[180:183], v146 offset:3072
	s_add_u32 s16, s16, 0x40000
	s_addc_u32 s17, s17, 0
	s_mov_b32 m0, s18
	v_lshl_add_u64 v[226:227], s[16:17], 0, v[136:137]
	ds_read_b128 v[184:187], v144 offset:32768
	ds_read_b128 v[188:191], v144 offset:33792
	ds_read_b128 v[192:195], v144 offset:34816
	ds_read_b128 v[196:199], v144 offset:35840
	ds_read_b128 v[202:205], v144 offset:36864
	ds_read_b128 v[210:213], v144 offset:37888
	ds_read_b128 v[214:217], v144 offset:38912
	ds_read_b128 v[218:221], v144 offset:39936
	global_load_lds_dwordx4 v[226:227], off
	v_lshl_add_u64 v[226:227], s[16:17], 0, v[132:133]
	s_mov_b32 m0, s19
	s_nop 0
	global_load_lds_dwordx4 v[226:227], off
	s_waitcnt vmcnt(8)
	s_waitcnt lgkmcnt(0)
	s_barrier
	s_waitcnt lgkmcnt(0)
	v_mfma_f32_16x16x32_bf16 v[124:127], v[148:151], v[184:187], v[124:127]
	v_mfma_f32_16x16x32_bf16 v[120:123], v[156:159], v[184:187], v[120:123]
	v_mfma_f32_16x16x32_bf16 v[108:111], v[148:151], v[192:195], v[108:111]
	v_mfma_f32_16x16x32_bf16 v[104:107], v[156:159], v[192:195], v[104:107]
	v_mfma_f32_16x16x32_bf16 v[92:95], v[148:151], v[202:205], v[92:95]
	v_mfma_f32_16x16x32_bf16 v[88:91], v[156:159], v[202:205], v[88:91]
	v_mfma_f32_16x16x32_bf16 v[76:79], v[148:151], v[214:217], v[76:79]
	v_mfma_f32_16x16x32_bf16 v[72:75], v[156:159], v[214:217], v[72:75]
	v_mfma_f32_16x16x32_bf16 v[124:127], v[152:155], v[188:191], v[124:127]
	v_mfma_f32_16x16x32_bf16 v[120:123], v[160:163], v[188:191], v[120:123]
	v_mfma_f32_16x16x32_bf16 v[108:111], v[152:155], v[196:199], v[108:111]
	v_mfma_f32_16x16x32_bf16 v[104:107], v[160:163], v[196:199], v[104:107]
	v_mfma_f32_16x16x32_bf16 v[92:95], v[152:155], v[210:213], v[92:95]
	v_mfma_f32_16x16x32_bf16 v[88:91], v[160:163], v[210:213], v[88:91]
	v_mfma_f32_16x16x32_bf16 v[76:79], v[152:155], v[218:221], v[76:79]
	v_mfma_f32_16x16x32_bf16 v[72:75], v[160:163], v[218:221], v[72:75]
	v_mfma_f32_16x16x32_bf16 v[116:119], v[164:167], v[184:187], v[116:119]
	v_mfma_f32_16x16x32_bf16 v[112:115], v[176:179], v[184:187], v[112:115]
	v_mfma_f32_16x16x32_bf16 v[100:103], v[164:167], v[192:195], v[100:103]
	v_mfma_f32_16x16x32_bf16 v[96:99], v[176:179], v[192:195], v[96:99]
	v_mfma_f32_16x16x32_bf16 v[84:87], v[164:167], v[202:205], v[84:87]
	v_mfma_f32_16x16x32_bf16 v[80:83], v[176:179], v[202:205], v[80:83]
	v_mfma_f32_16x16x32_bf16 v[68:71], v[164:167], v[214:217], v[68:71]
	v_mfma_f32_16x16x32_bf16 v[64:67], v[176:179], v[214:217], v[64:67]
	v_mfma_f32_16x16x32_bf16 v[116:119], v[168:171], v[188:191], v[116:119]
	v_mfma_f32_16x16x32_bf16 v[112:115], v[180:183], v[188:191], v[112:115]
	v_mfma_f32_16x16x32_bf16 v[100:103], v[168:171], v[196:199], v[100:103]
	v_mfma_f32_16x16x32_bf16 v[96:99], v[180:183], v[196:199], v[96:99]
	v_mfma_f32_16x16x32_bf16 v[84:87], v[168:171], v[210:213], v[84:87]
	v_mfma_f32_16x16x32_bf16 v[80:83], v[180:183], v[210:213], v[80:83]
	v_mfma_f32_16x16x32_bf16 v[68:71], v[168:171], v[218:221], v[68:71]
	v_mfma_f32_16x16x32_bf16 v[64:67], v[180:183], v[218:221], v[64:67]
	s_barrier
; #define PG8_STAGE(bufoff, gbase, voff) do { _Pragma("unroll") for (int _i = 0; _i < 2; ++_i) \
;         __builtin_amdgcn_global_load_lds((const unsigned*)((const char*)(gbase) + (voff)[_i]), (PG8_LAS unsigned*)(lds + (bufoff) + ldsw + _i * 8192), 16, 0, 0); } while (0)
; #define PG8_STAGEA(bufoff, gbase, voff) do { _Pragma("unroll") for (int _i = 0; _i < 2; ++_i) \
;         __builtin_amdgcn_global_load_lds((const unsigned*)((const char*)(gbase) + (voff)[_i]), (PG8_LAS unsigned*)(lds + (bufoff) + ldsw + _i * 8192), 16, 0, AUXA); } while (0)
; #define PG8_LDA(dst, b, h) do { _Pragma("unroll") for (int m = 0; m < 4; ++m) _Pragma("unroll") for (int k = 0; k < 2; ++k) dst[m][k] = *(const PG8_LAS bf16x8*)(lds + PG8_SA(b, h) + aoff + m * 2048 + k * 1024); } while (0)
; #define PG8_WAIT_V(n) asm volatile("s_waitcnt vmcnt(" #n ")" ::: "memory")
; #define PG8_BAR __builtin_amdgcn_s_barrier()
;     ...
;         for (int t = 0; t < nt; t += 2) {
;             const bool last = (t == nt - 2);
;             const char* a1 = cA + (size_t)(t + 1) * kstep;
;             const char* a2 = last ? nA : cA + (size_t)(t + 2) * kstep; const char* b2 = last ? nB : cB + (size_t)(t + 2) * kstep;
;             const char* a3 = a2 + kstep; const char* b3 = b2 + kstep;
;             if (last && has_next) S.a_ready(nxt);
;             if constexpr (SP2) {
;             PG8_LDB(B0, 0, 0); PG8_LDB(B1, 0, 1); PG8_SCHED; PG8_LDA(At, 0, 0); PG8_STAGEA(PG8_SA(1, 1), a1 + hstep, voffA);
;             PG8_WAIT_V(8); PG8_WAIT_L(0); PG8_BAR; PG8_MMA(0, 0, At, B0); PG8_MMA(0, 1, At, B1); PG8_BAR; PG8_SCHED;
;             PG8_LDA(At, 0, 1); PG8_STAGE(PG8_SB(0, 0), b2, voffB); PG8_STAGE(PG8_SB(0, 1), b2 + hstepB, voffB); PG8_STAGEA(PG8_SA(0, 0), a2, voffA);
;             PG8_WAIT_V(8); PG8_WAIT_L(0); PG8_BAR; PG8_MMA(1, 0, At, B0); PG8_MMA(1, 1, At, B1); PG8_BAR; PG8_SCHED;
;             PG8_LDB(B0, 1, 0); PG8_LDB(B1, 1, 1); PG8_SCHED; PG8_LDA(At, 1, 0); PG8_STAGEA(PG8_SA(0, 1), a2 + hstep, voffA);
;             PG8_WAIT_V(8); PG8_WAIT_L(0); PG8_BAR; PG8_MMA(0, 0, At, B0); PG8_MMA(0, 1, At, B1); PG8_BAR; PG8_SCHED;
;             PG8_LDA(At, 1, 1); PG8_STAGE(PG8_SB(1, 0), b3, voffB); PG8_STAGE(PG8_SB(1, 1), b3 + hstepB, voffB); PG8_STAGEA(PG8_SA(1, 0), a3, voffA);
;             PG8_WAIT_V(8); PG8_WAIT_L(0); PG8_BAR; PG8_MMA(1, 0, At, B0); PG8_MMA(1, 1, At, B1); PG8_BAR; PG8_SCHED;
	s_mov_b32 m0, s29
	v_lshl_add_u64 v[172:173], v[172:173], 0, s[10:11]
	s_add_u32 s14, s14, 0x10080
	ds_read_b128 v[184:187], v144 offset:49152
	ds_read_b128 v[188:191], v144 offset:50176
	ds_read_b128 v[192:195], v144 offset:51200
	ds_read_b128 v[196:199], v144 offset:52224
	ds_read_b128 v[202:205], v144 offset:53248
	ds_read_b128 v[210:213], v144 offset:54272
	ds_read_b128 v[214:217], v144 offset:55296
	ds_read_b128 v[218:221], v144 offset:56320
	global_load_lds_dwordx4 v[172:173], off
	v_lshl_add_u64 v[172:173], v[206:207], 0, s[10:11]
	s_mov_b32 m0, s30
	s_addc_u32 s15, s15, 0
	global_load_lds_dwordx4 v[172:173], off
	v_lshl_add_u64 v[172:173], s[14:15], 0, v[134:135]
	s_mov_b32 m0, s31
	s_nop 0
	global_load_lds_dwordx4 v[172:173], off
	v_lshl_add_u64 v[172:173], s[14:15], 0, v[130:131]
	s_mov_b32 m0, s34
	s_nop 0
	global_load_lds_dwordx4 v[172:173], off
	v_lshl_add_u64 v[172:173], v[222:223], 0, s[10:11]
	s_mov_b32 m0, s20
	s_nop 0
	global_load_lds_dwordx4 v[172:173], off
	v_lshl_add_u64 v[172:173], v[224:225], 0, s[10:11]
	s_mov_b32 m0, s21
	s_nop 0
	global_load_lds_dwordx4 v[172:173], off
	s_waitcnt vmcnt(8)
	s_waitcnt lgkmcnt(0)
	s_barrier
	s_waitcnt lgkmcnt(0)
	v_mfma_f32_16x16x32_bf16 v[60:63], v[148:151], v[184:187], v[60:63]
	v_mfma_f32_16x16x32_bf16 v[56:59], v[156:159], v[184:187], v[56:59]
	v_mfma_f32_16x16x32_bf16 v[44:47], v[148:151], v[192:195], v[44:47]
	v_mfma_f32_16x16x32_bf16 v[40:43], v[156:159], v[192:195], v[40:43]
	v_mfma_f32_16x16x32_bf16 v[28:31], v[148:151], v[202:205], v[28:31]
	v_mfma_f32_16x16x32_bf16 v[24:27], v[156:159], v[202:205], v[24:27]
	v_mfma_f32_16x16x32_bf16 v[12:15], v[148:151], v[214:217], v[12:15]
	v_mfma_f32_16x16x32_bf16 v[8:11], v[156:159], v[214:217], v[8:11]
	v_mfma_f32_16x16x32_bf16 v[60:63], v[152:155], v[188:191], v[60:63]
	v_mfma_f32_16x16x32_bf16 v[56:59], v[160:163], v[188:191], v[56:59]
	v_mfma_f32_16x16x32_bf16 v[44:47], v[152:155], v[196:199], v[44:47]
	v_mfma_f32_16x16x32_bf16 v[40:43], v[160:163], v[196:199], v[40:43]
	v_mfma_f32_16x16x32_bf16 v[28:31], v[152:155], v[210:213], v[28:31]
	v_mfma_f32_16x16x32_bf16 v[24:27], v[160:163], v[210:213], v[24:27]
	v_mfma_f32_16x16x32_bf16 v[12:15], v[152:155], v[218:221], v[12:15]
	v_mfma_f32_16x16x32_bf16 v[8:11], v[160:163], v[218:221], v[8:11]
	v_mfma_f32_16x16x32_bf16 v[52:55], v[164:167], v[184:187], v[52:55]
	v_mfma_f32_16x16x32_bf16 v[48:51], v[176:179], v[184:187], v[48:51]
	v_mfma_f32_16x16x32_bf16 v[36:39], v[164:167], v[192:195], v[36:39]
	v_mfma_f32_16x16x32_bf16 v[32:35], v[176:179], v[192:195], v[32:35]
	v_mfma_f32_16x16x32_bf16 v[20:23], v[164:167], v[202:205], v[20:23]
	v_mfma_f32_16x16x32_bf16 v[16:19], v[176:179], v[202:205], v[16:19]
	v_mfma_f32_16x16x32_bf16 v[4:7], v[164:167], v[214:217], v[4:7]
	v_mfma_f32_16x16x32_bf16 v[0:3], v[176:179], v[214:217], v[0:3]
	v_mfma_f32_16x16x32_bf16 v[52:55], v[168:171], v[188:191], v[52:55]
	v_mfma_f32_16x16x32_bf16 v[48:51], v[180:183], v[188:191], v[48:51]
	v_mfma_f32_16x16x32_bf16 v[36:39], v[168:171], v[196:199], v[36:39]
	v_mfma_f32_16x16x32_bf16 v[32:35], v[180:183], v[196:199], v[32:35]
	v_mfma_f32_16x16x32_bf16 v[20:23], v[168:171], v[210:213], v[20:23]
	v_mfma_f32_16x16x32_bf16 v[16:19], v[180:183], v[210:213], v[16:19]
	v_mfma_f32_16x16x32_bf16 v[4:7], v[168:171], v[218:221], v[4:7]
	v_mfma_f32_16x16x32_bf16 v[0:3], v[180:183], v[218:221], v[0:3]
	s_add_i32 s22, s22, 2
	s_add_u32 s12, s12, 0x100
	s_addc_u32 s13, s13, 0
	s_cmp_gt_u32 s22, 13
	s_barrier
	s_cbranch_scc0 .LBB0_758
	s_setprio 0
	v_readlane_b32 s1, v255, 10
	s_cmpk_lt_u32 s1, 0x100
	s_cbranch_scc0 .LBB0_761
	s_barrier

; #define PG8_STAGE(bufoff, gbase, voff) do { _Pragma("unroll") for (int _i = 0; _i < 2; ++_i) \
;         __builtin_amdgcn_global_load_lds((const unsigned*)((const char*)(gbase) + (voff)[_i]), (PG8_LAS unsigned*)(lds + (bufoff) + ldsw + _i * 8192), 16, 0, 0); } while (0)
; #define PG8_STAGEA(bufoff, gbase, voff) do { _Pragma("unroll") for (int _i = 0; _i < 2; ++_i) \
;         __builtin_amdgcn_global_load_lds((const unsigned*)((const char*)(gbase) + (voff)[_i]), (PG8_LAS unsigned*)(lds + (bufoff) + ldsw + _i * 8192), 16, 0, AUXA); } while (0)
; #define PG8_LDA(dst, b, h) do { _Pragma("unroll") for (int m = 0; m < 4; ++m) _Pragma("unroll") for (int k = 0; k < 2; ++k) dst[m][k] = *(const PG8_LAS bf16x8*)(lds + PG8_SA(b, h) + aoff + m * 2048 + k * 1024); } while (0)
; #define PG8_LDB(dst, b, h) do { _Pragma("unroll") for (int n = 0; n < 2; ++n) _Pragma("unroll") for (int k = 0; k < 2; ++k) dst[n][k] = *(const PG8_LAS bf16x8*)(lds + PG8_SB(b, h) + boff + n * 2048 + k * 1024); } while (0)
; #define PG8_MMA(ai, bj, At, Bt) do { __builtin_amdgcn_s_setprio(1); _Pragma("unroll") for (int m = 0; m < 4; ++m) _Pragma("unroll") for (int n = 0; n < 2; ++n) _Pragma("unroll") for (int k = 0; k < 2; ++k) \
;         acc[ai][bj][m][n] = __builtin_amdgcn_mfma_f32_16x16x32_bf16(Bt[n][k], At[m][k], acc[ai][bj][m][n], 0, 0, 0); __builtin_amdgcn_s_setprio(0); } while (0)
; #define PG8_WAIT_V(n) asm volatile("s_waitcnt vmcnt(" #n ")" ::: "memory")
; #define PG8_WAIT_L(n) asm volatile("s_waitcnt lgkmcnt(" #n ")" ::: "memory")
; #define PG8_BAR __builtin_amdgcn_s_barrier()
; #define PG8_SCHED __builtin_amdgcn_sched_barrier(0)
;     ...
;             if constexpr (SP2) {
;             PG8_LDB(B0, 0, 0); PG8_LDB(B1, 0, 1); PG8_SCHED; PG8_LDA(At, 0, 0); PG8_STAGEA(PG8_SA(1, 1), a1 + hstep, voffA);
;             PG8_WAIT_V(8); PG8_WAIT_L(0); PG8_BAR; PG8_MMA(0, 0, At, B0); PG8_MMA(0, 1, At, B1); PG8_BAR; PG8_SCHED;
;             PG8_LDA(At, 0, 1); PG8_STAGE(PG8_SB(0, 0), b2, voffB); PG8_STAGE(PG8_SB(0, 1), b2 + hstepB, voffB); PG8_STAGEA(PG8_SA(0, 0), a2, voffA);
;             PG8_WAIT_V(8); PG8_WAIT_L(0); PG8_BAR; PG8_MMA(1, 0, At, B0); PG8_MMA(1, 1, At, B1); PG8_BAR; PG8_SCHED;
.Lsprio_3:
.LBB0_854:
	ds_read_b128 v[142:145], v151
	ds_read_b128 v[154:157], v151 offset:1024
	ds_read_b128 v[158:161], v151 offset:2048
	ds_read_b128 v[162:165], v151 offset:3072
	ds_read_b128 v[166:169], v152
	ds_read_b128 v[170:173], v152 offset:1024
	ds_read_b128 v[176:179], v152 offset:2048
	ds_read_b128 v[180:183], v152 offset:3072
	s_add_u32 s36, s34, 0xfffc0080
	s_addc_u32 s37, s35, -1
	s_cmp_eq_u32 s58, 12
	s_cselect_b32 s39, s15, s37
	s_cselect_b32 s38, s25, s36
	s_cselect_b32 s37, s23, s57
	s_cselect_b32 s36, s31, s56
	v_lshl_add_u64 v[206:207], s[34:35], 0, v[136:137]
	s_add_i32 m0, s40, 0xc000
	ds_read_b128 v[184:187], v153
	ds_read_b128 v[188:191], v153 offset:1024
	ds_read_b128 v[192:195], v153 offset:2048
	ds_read_b128 v[196:199], v153 offset:3072
	ds_read_b128 v[202:205], v153 offset:4096
	ds_read_b128 v[210:213], v153 offset:5120
	ds_read_b128 v[214:217], v153 offset:6144
	ds_read_b128 v[218:221], v153 offset:7168
	global_load_lds_dwordx4 v[206:207], off
	v_lshl_add_u64 v[206:207], s[34:35], 0, v[138:139]
	s_add_i32 m0, s40, 0xe000
	s_nop 0
	global_load_lds_dwordx4 v[206:207], off
	s_waitcnt vmcnt(8)
	s_waitcnt lgkmcnt(0)
	s_barrier
	s_waitcnt lgkmcnt(0)
	v_mfma_f32_16x16x32_bf16 v[124:127], v[142:145], v[184:187], v[124:127]
	v_mfma_f32_16x16x32_bf16 v[120:123], v[158:161], v[184:187], v[120:123]
	v_mfma_f32_16x16x32_bf16 v[108:111], v[142:145], v[192:195], v[108:111]
	v_mfma_f32_16x16x32_bf16 v[104:107], v[158:161], v[192:195], v[104:107]
	v_mfma_f32_16x16x32_bf16 v[92:95], v[142:145], v[202:205], v[92:95]
	v_mfma_f32_16x16x32_bf16 v[88:91], v[158:161], v[202:205], v[88:91]
	v_mfma_f32_16x16x32_bf16 v[76:79], v[142:145], v[214:217], v[76:79]
	v_mfma_f32_16x16x32_bf16 v[72:75], v[158:161], v[214:217], v[72:75]
	v_mfma_f32_16x16x32_bf16 v[124:127], v[154:157], v[188:191], v[124:127]
	v_mfma_f32_16x16x32_bf16 v[120:123], v[162:165], v[188:191], v[120:123]
	v_mfma_f32_16x16x32_bf16 v[108:111], v[154:157], v[196:199], v[108:111]
	v_mfma_f32_16x16x32_bf16 v[104:107], v[162:165], v[196:199], v[104:107]
	v_mfma_f32_16x16x32_bf16 v[92:95], v[154:157], v[210:213], v[92:95]
	v_mfma_f32_16x16x32_bf16 v[88:91], v[162:165], v[210:213], v[88:91]
	v_mfma_f32_16x16x32_bf16 v[76:79], v[154:157], v[218:221], v[76:79]
	v_mfma_f32_16x16x32_bf16 v[72:75], v[162:165], v[218:221], v[72:75]
	v_mfma_f32_16x16x32_bf16 v[116:119], v[166:169], v[184:187], v[116:119]
	v_mfma_f32_16x16x32_bf16 v[112:115], v[176:179], v[184:187], v[112:115]
	v_mfma_f32_16x16x32_bf16 v[100:103], v[166:169], v[192:195], v[100:103]
	v_mfma_f32_16x16x32_bf16 v[96:99], v[176:179], v[192:195], v[96:99]
	v_mfma_f32_16x16x32_bf16 v[84:87], v[166:169], v[202:205], v[84:87]
	v_mfma_f32_16x16x32_bf16 v[80:83], v[176:179], v[202:205], v[80:83]
	v_mfma_f32_16x16x32_bf16 v[68:71], v[166:169], v[214:217], v[68:71]
	v_mfma_f32_16x16x32_bf16 v[64:67], v[176:179], v[214:217], v[64:67]
	v_mfma_f32_16x16x32_bf16 v[116:119], v[170:173], v[188:191], v[116:119]
	v_mfma_f32_16x16x32_bf16 v[112:115], v[180:183], v[188:191], v[112:115]
	v_mfma_f32_16x16x32_bf16 v[100:103], v[170:173], v[196:199], v[100:103]
	v_mfma_f32_16x16x32_bf16 v[96:99], v[180:183], v[196:199], v[96:99]
	v_mfma_f32_16x16x32_bf16 v[84:87], v[170:173], v[210:213], v[84:87]
	v_mfma_f32_16x16x32_bf16 v[80:83], v[180:183], v[210:213], v[80:83]
	v_mfma_f32_16x16x32_bf16 v[68:71], v[170:173], v[218:221], v[68:71]
	v_mfma_f32_16x16x32_bf16 v[64:67], v[180:183], v[218:221], v[64:67]
	s_barrier
	s_add_i32 s59, s54, s67
	v_lshl_add_u64 v[206:207], s[36:37], 0, v[130:131]
	s_mov_b32 m0, s59
	ds_read_b128 v[184:187], v153 offset:16384
	ds_read_b128 v[188:191], v153 offset:17408
	ds_read_b128 v[192:195], v153 offset:18432
	ds_read_b128 v[196:199], v153 offset:19456
	ds_read_b128 v[202:205], v153 offset:20480
	ds_read_b128 v[210:213], v153 offset:21504
	ds_read_b128 v[214:217], v153 offset:22528
	ds_read_b128 v[218:221], v153 offset:23552
	global_load_lds_dwordx4 v[206:207], off
	s_add_i32 m0, s59, 0x2000
	s_add_u32 s70, s36, 0x10000
	v_lshl_add_u64 v[222:223], s[36:37], 0, v[134:135]
	s_addc_u32 s71, s37, 0
	s_add_i32 s59, s55, s67
	global_load_lds_dwordx4 v[222:223], off
	v_lshl_add_u64 v[224:225], s[70:71], 0, v[130:131]
	s_mov_b32 m0, s59
	v_lshl_add_u64 v[226:227], s[38:39], 0, v[132:133]
	global_load_lds_dwordx4 v[224:225], off
	v_lshl_add_u64 v[224:225], s[70:71], 0, v[134:135]
	s_add_i32 m0, s59, 0x2000
	s_nop 0
	global_load_lds_dwordx4 v[224:225], off
	v_lshl_add_u64 v[224:225], s[38:39], 0, v[128:129]
	s_mov_b32 m0, s40
	s_nop 0
	global_load_lds_dwordx4 v[224:225], off
	s_mov_b32 m0, s41
	s_nop 0
	global_load_lds_dwordx4 v[226:227], off
	s_waitcnt vmcnt(8)
	s_waitcnt lgkmcnt(0)
	s_barrier
; #define PG8_STAGE(bufoff, gbase, voff) do { _Pragma("unroll") for (int _i = 0; _i < 2; ++_i) \
;         __builtin_amdgcn_global_load_lds((const unsigned*)((const char*)(gbase) + (voff)[_i]), (PG8_LAS unsigned*)(lds + (bufoff) + ldsw + _i * 8192), 16, 0, 0); } while (0)
; #define PG8_STAGEA(bufoff, gbase, voff) do { _Pragma("unroll") for (int _i = 0; _i < 2; ++_i) \
;         __builtin_amdgcn_global_load_lds((const unsigned*)((const char*)(gbase) + (voff)[_i]), (PG8_LAS unsigned*)(lds + (bufoff) + ldsw + _i * 8192), 16, 0, AUXA); } while (0)
; #define PG8_LDA(dst, b, h) do { _Pragma("unroll") for (int m = 0; m < 4; ++m) _Pragma("unroll") for (int k = 0; k < 2; ++k) dst[m][k] = *(const PG8_LAS bf16x8*)(lds + PG8_SA(b, h) + aoff + m * 2048 + k * 1024); } while (0)
; #define PG8_LDB(dst, b, h) do { _Pragma("unroll") for (int n = 0; n < 2; ++n) _Pragma("unroll") for (int k = 0; k < 2; ++k) dst[n][k] = *(const PG8_LAS bf16x8*)(lds + PG8_SB(b, h) + boff + n * 2048 + k * 1024); } while (0)
; #define PG8_MMA(ai, bj, At, Bt) do { __builtin_amdgcn_s_setprio(1); _Pragma("unroll") for (int m = 0; m < 4; ++m) _Pragma("unroll") for (int n = 0; n < 2; ++n) _Pragma("unroll") for (int k = 0; k < 2; ++k) \
;         acc[ai][bj][m][n] = __builtin_amdgcn_mfma_f32_16x16x32_bf16(Bt[n][k], At[m][k], acc[ai][bj][m][n], 0, 0, 0); __builtin_amdgcn_s_setprio(0); } while (0)
; #define PG8_WAIT_V(n) asm volatile("s_waitcnt vmcnt(" #n ")" ::: "memory")
; #define PG8_WAIT_L(n) asm volatile("s_waitcnt lgkmcnt(" #n ")" ::: "memory")
; #define PG8_BAR __builtin_amdgcn_s_barrier()
; #define PG8_SCHED __builtin_amdgcn_sched_barrier(0)
;     ...
;             PG8_WAIT_V(8); PG8_WAIT_L(0); PG8_BAR; PG8_MMA(0, 0, At, B0); PG8_MMA(0, 1, At, B1); PG8_BAR; PG8_SCHED;
;             PG8_LDA(At, 0, 1); PG8_STAGE(PG8_SB(0, 0), b2, voffB); PG8_STAGE(PG8_SB(0, 1), b2 + hstepB, voffB); PG8_STAGEA(PG8_SA(0, 0), a2, voffA);
;             PG8_WAIT_V(8); PG8_WAIT_L(0); PG8_BAR; PG8_MMA(1, 0, At, B0); PG8_MMA(1, 1, At, B1); PG8_BAR; PG8_SCHED;
;             PG8_LDB(B0, 1, 0); PG8_LDB(B1, 1, 1); PG8_SCHED; PG8_LDA(At, 1, 0); PG8_STAGEA(PG8_SA(0, 1), a2 + hstep, voffA);
;             PG8_WAIT_V(8); PG8_WAIT_L(0); PG8_BAR; PG8_MMA(0, 0, At, B0); PG8_MMA(0, 1, At, B1); PG8_BAR; PG8_SCHED;
	s_waitcnt lgkmcnt(0)
	v_mfma_f32_16x16x32_bf16 v[60:63], v[142:145], v[184:187], v[60:63]
	v_mfma_f32_16x16x32_bf16 v[56:59], v[158:161], v[184:187], v[56:59]
	v_mfma_f32_16x16x32_bf16 v[44:47], v[142:145], v[192:195], v[44:47]
	v_mfma_f32_16x16x32_bf16 v[40:43], v[158:161], v[192:195], v[40:43]
	v_mfma_f32_16x16x32_bf16 v[28:31], v[142:145], v[202:205], v[28:31]
	v_mfma_f32_16x16x32_bf16 v[24:27], v[158:161], v[202:205], v[24:27]
	v_mfma_f32_16x16x32_bf16 v[12:15], v[142:145], v[214:217], v[12:15]
	v_mfma_f32_16x16x32_bf16 v[8:11], v[158:161], v[214:217], v[8:11]
	v_mfma_f32_16x16x32_bf16 v[60:63], v[154:157], v[188:191], v[60:63]
	v_mfma_f32_16x16x32_bf16 v[56:59], v[162:165], v[188:191], v[56:59]
	v_mfma_f32_16x16x32_bf16 v[44:47], v[154:157], v[196:199], v[44:47]
	v_mfma_f32_16x16x32_bf16 v[40:43], v[162:165], v[196:199], v[40:43]
	v_mfma_f32_16x16x32_bf16 v[28:31], v[154:157], v[210:213], v[28:31]
	v_mfma_f32_16x16x32_bf16 v[24:27], v[162:165], v[210:213], v[24:27]
	v_mfma_f32_16x16x32_bf16 v[12:15], v[154:157], v[218:221], v[12:15]
	v_mfma_f32_16x16x32_bf16 v[8:11], v[162:165], v[218:221], v[8:11]
	v_mfma_f32_16x16x32_bf16 v[52:55], v[166:169], v[184:187], v[52:55]
	v_mfma_f32_16x16x32_bf16 v[48:51], v[176:179], v[184:187], v[48:51]
	v_mfma_f32_16x16x32_bf16 v[36:39], v[166:169], v[192:195], v[36:39]
	v_mfma_f32_16x16x32_bf16 v[32:35], v[176:179], v[192:195], v[32:35]
	v_mfma_f32_16x16x32_bf16 v[20:23], v[166:169], v[202:205], v[20:23]
	v_mfma_f32_16x16x32_bf16 v[16:19], v[176:179], v[202:205], v[16:19]
	v_mfma_f32_16x16x32_bf16 v[4:7], v[166:169], v[214:217], v[4:7]
	v_mfma_f32_16x16x32_bf16 v[0:3], v[176:179], v[214:217], v[0:3]
	v_mfma_f32_16x16x32_bf16 v[52:55], v[170:173], v[188:191], v[52:55]
	v_mfma_f32_16x16x32_bf16 v[48:51], v[180:183], v[188:191], v[48:51]
	v_mfma_f32_16x16x32_bf16 v[36:39], v[170:173], v[196:199], v[36:39]
	v_mfma_f32_16x16x32_bf16 v[32:35], v[180:183], v[196:199], v[32:35]
	v_mfma_f32_16x16x32_bf16 v[20:23], v[170:173], v[210:213], v[20:23]
	v_mfma_f32_16x16x32_bf16 v[16:19], v[180:183], v[210:213], v[16:19]
	v_mfma_f32_16x16x32_bf16 v[4:7], v[170:173], v[218:221], v[4:7]
	v_mfma_f32_16x16x32_bf16 v[0:3], v[180:183], v[218:221], v[0:3]
	s_barrier
	s_add_i32 s59, 0, 0x18000
	s_add_i32 s70, 0, 0x1c000
	v_add_u32_e32 v162, s59, v147
	v_add_u32_e32 v174, s70, v147
	ds_read_b128 v[142:145], v162
	ds_read_b128 v[154:157], v162 offset:1024
	ds_read_b128 v[158:161], v162 offset:2048
	ds_read_b128 v[162:165], v162 offset:3072
	ds_read_b128 v[166:169], v174
	ds_read_b128 v[170:173], v174 offset:1024
	ds_read_b128 v[176:179], v174 offset:2048
	ds_read_b128 v[180:183], v174 offset:3072
	s_add_u32 s38, s38, 0x40000
	s_addc_u32 s39, s39, 0
	s_mov_b32 m0, s43
	v_lshl_add_u64 v[228:229], s[38:39], 0, v[128:129]
	ds_read_b128 v[184:187], v153 offset:32768
	ds_read_b128 v[188:191], v153 offset:33792
	ds_read_b128 v[192:195], v153 offset:34816
	ds_read_b128 v[196:199], v153 offset:35840
	ds_read_b128 v[202:205], v153 offset:36864
	ds_read_b128 v[210:213], v153 offset:37888
	ds_read_b128 v[214:217], v153 offset:38912
	ds_read_b128 v[218:221], v153 offset:39936
	global_load_lds_dwordx4 v[228:229], off
	v_lshl_add_u64 v[228:229], s[38:39], 0, v[132:133]
	s_mov_b32 m0, s44
	s_nop 0
	global_load_lds_dwordx4 v[228:229], off
	s_waitcnt vmcnt(8)
	s_waitcnt lgkmcnt(0)
	s_barrier
	s_waitcnt lgkmcnt(0)
	v_mfma_f32_16x16x32_bf16 v[124:127], v[142:145], v[184:187], v[124:127]
	v_mfma_f32_16x16x32_bf16 v[120:123], v[158:161], v[184:187], v[120:123]
	v_mfma_f32_16x16x32_bf16 v[108:111], v[142:145], v[192:195], v[108:111]
	v_mfma_f32_16x16x32_bf16 v[104:107], v[158:161], v[192:195], v[104:107]
	v_mfma_f32_16x16x32_bf16 v[92:95], v[142:145], v[202:205], v[92:95]
	v_mfma_f32_16x16x32_bf16 v[88:91], v[158:161], v[202:205], v[88:91]
	v_mfma_f32_16x16x32_bf16 v[76:79], v[142:145], v[214:217], v[76:79]
	v_mfma_f32_16x16x32_bf16 v[72:75], v[158:161], v[214:217], v[72:75]
	v_mfma_f32_16x16x32_bf16 v[124:127], v[154:157], v[188:191], v[124:127]
	v_mfma_f32_16x16x32_bf16 v[120:123], v[162:165], v[188:191], v[120:123]
	v_mfma_f32_16x16x32_bf16 v[108:111], v[154:157], v[196:199], v[108:111]
	v_mfma_f32_16x16x32_bf16 v[104:107], v[162:165], v[196:199], v[104:107]
	v_mfma_f32_16x16x32_bf16 v[92:95], v[154:157], v[210:213], v[92:95]
	v_mfma_f32_16x16x32_bf16 v[88:91], v[162:165], v[210:213], v[88:91]
	v_mfma_f32_16x16x32_bf16 v[76:79], v[154:157], v[218:221], v[76:79]
	v_mfma_f32_16x16x32_bf16 v[72:75], v[162:165], v[218:221], v[72:75]
	v_mfma_f32_16x16x32_bf16 v[116:119], v[166:169], v[184:187], v[116:119]
	v_mfma_f32_16x16x32_bf16 v[112:115], v[176:179], v[184:187], v[112:115]
	v_mfma_f32_16x16x32_bf16 v[100:103], v[166:169], v[192:195], v[100:103]
	v_mfma_f32_16x16x32_bf16 v[96:99], v[176:179], v[192:195], v[96:99]
	v_mfma_f32_16x16x32_bf16 v[84:87], v[166:169], v[202:205], v[84:87]
	v_mfma_f32_16x16x32_bf16 v[80:83], v[176:179], v[202:205], v[80:83]
	v_mfma_f32_16x16x32_bf16 v[68:71], v[166:169], v[214:217], v[68:71]
	v_mfma_f32_16x16x32_bf16 v[64:67], v[176:179], v[214:217], v[64:67]
	v_mfma_f32_16x16x32_bf16 v[116:119], v[170:173], v[188:191], v[116:119]
	v_mfma_f32_16x16x32_bf16 v[112:115], v[180:183], v[188:191], v[112:115]
	v_mfma_f32_16x16x32_bf16 v[100:103], v[170:173], v[196:199], v[100:103]
	v_mfma_f32_16x16x32_bf16 v[96:99], v[180:183], v[196:199], v[96:99]
	v_mfma_f32_16x16x32_bf16 v[84:87], v[170:173], v[210:213], v[84:87]
	v_mfma_f32_16x16x32_bf16 v[80:83], v[180:183], v[210:213], v[80:83]
	v_mfma_f32_16x16x32_bf16 v[68:71], v[170:173], v[218:221], v[68:71]
	v_mfma_f32_16x16x32_bf16 v[64:67], v[180:183], v[218:221], v[64:67]
	s_barrier
; #define PG8_STAGE(bufoff, gbase, voff) do { _Pragma("unroll") for (int _i = 0; _i < 2; ++_i) \
;         __builtin_amdgcn_global_load_lds((const unsigned*)((const char*)(gbase) + (voff)[_i]), (PG8_LAS unsigned*)(lds + (bufoff) + ldsw + _i * 8192), 16, 0, 0); } while (0)
; #define PG8_STAGEA(bufoff, gbase, voff) do { _Pragma("unroll") for (int _i = 0; _i < 2; ++_i) \
;         __builtin_amdgcn_global_load_lds((const unsigned*)((const char*)(gbase) + (voff)[_i]), (PG8_LAS unsigned*)(lds + (bufoff) + ldsw + _i * 8192), 16, 0, AUXA); } while (0)
; #define PG8_LDA(dst, b, h) do { _Pragma("unroll") for (int m = 0; m < 4; ++m) _Pragma("unroll") for (int k = 0; k < 2; ++k) dst[m][k] = *(const PG8_LAS bf16x8*)(lds + PG8_SA(b, h) + aoff + m * 2048 + k * 1024); } while (0)
; #define PG8_WAIT_V(n) asm volatile("s_waitcnt vmcnt(" #n ")" ::: "memory")
; #define PG8_BAR __builtin_amdgcn_s_barrier()
;     ...
;         for (int t = 0; t < nt; t += 2) {
;             const bool last = (t == nt - 2);
;             const char* a1 = cA + (size_t)(t + 1) * kstep;
;             const char* a2 = last ? nA : cA + (size_t)(t + 2) * kstep; const char* b2 = last ? nB : cB + (size_t)(t + 2) * kstep;
;             const char* a3 = a2 + kstep; const char* b3 = b2 + kstep;
;             if (last && has_next) S.a_ready(nxt);
;             if constexpr (SP2) {
;             PG8_LDB(B0, 0, 0); PG8_LDB(B1, 0, 1); PG8_SCHED; PG8_LDA(At, 0, 0); PG8_STAGEA(PG8_SA(1, 1), a1 + hstep, voffA);
;             PG8_WAIT_V(8); PG8_WAIT_L(0); PG8_BAR; PG8_MMA(0, 0, At, B0); PG8_MMA(0, 1, At, B1); PG8_BAR; PG8_SCHED;
;             PG8_LDA(At, 0, 1); PG8_STAGE(PG8_SB(0, 0), b2, voffB); PG8_STAGE(PG8_SB(0, 1), b2 + hstepB, voffB); PG8_STAGEA(PG8_SA(0, 0), a2, voffA);
;             PG8_WAIT_V(8); PG8_WAIT_L(0); PG8_BAR; PG8_MMA(1, 0, At, B0); PG8_MMA(1, 1, At, B1); PG8_BAR; PG8_SCHED;
;             PG8_LDB(B0, 1, 0); PG8_LDB(B1, 1, 1); PG8_SCHED; PG8_LDA(At, 1, 0); PG8_STAGEA(PG8_SA(0, 1), a2 + hstep, voffA);
;             PG8_WAIT_V(8); PG8_WAIT_L(0); PG8_BAR; PG8_MMA(0, 0, At, B0); PG8_MMA(0, 1, At, B1); PG8_BAR; PG8_SCHED;
;             PG8_LDA(At, 1, 1); PG8_STAGE(PG8_SB(1, 0), b3, voffB); PG8_STAGE(PG8_SB(1, 1), b3 + hstepB, voffB); PG8_STAGEA(PG8_SA(1, 0), a3, voffA);
;             PG8_WAIT_V(8); PG8_WAIT_L(0); PG8_BAR; PG8_MMA(1, 0, At, B0); PG8_MMA(1, 1, At, B1); PG8_BAR; PG8_SCHED;
	s_add_i32 s38, s59, s67
	v_lshl_add_u64 v[206:207], v[206:207], 0, s[18:19]
	s_mov_b32 m0, s38
	ds_read_b128 v[184:187], v153 offset:49152
	ds_read_b128 v[188:191], v153 offset:50176
	ds_read_b128 v[192:195], v153 offset:51200
	ds_read_b128 v[196:199], v153 offset:52224
	ds_read_b128 v[202:205], v153 offset:53248
	ds_read_b128 v[210:213], v153 offset:54272
	ds_read_b128 v[214:217], v153 offset:55296
	ds_read_b128 v[218:221], v153 offset:56320
	global_load_lds_dwordx4 v[206:207], off
	s_add_i32 m0, s38, 0x2000
	s_add_u32 s36, s36, 0x10080
	v_lshl_add_u64 v[206:207], v[222:223], 0, s[18:19]
	s_addc_u32 s37, s37, 0
	s_add_i32 s38, s70, s67
	global_load_lds_dwordx4 v[206:207], off
	v_lshl_add_u64 v[206:207], s[36:37], 0, v[130:131]
	s_mov_b32 m0, s38
	s_nop 0
	global_load_lds_dwordx4 v[206:207], off
	v_lshl_add_u64 v[206:207], s[36:37], 0, v[134:135]
	s_add_i32 m0, s38, 0x2000
	s_nop 0
	global_load_lds_dwordx4 v[206:207], off
	v_lshl_add_u64 v[206:207], v[224:225], 0, s[18:19]
	s_mov_b32 m0, s45
	s_nop 0
	global_load_lds_dwordx4 v[206:207], off
	v_lshl_add_u64 v[206:207], v[226:227], 0, s[18:19]
	s_mov_b32 m0, s46
	s_nop 0
	global_load_lds_dwordx4 v[206:207], off
	s_waitcnt vmcnt(8)
	s_waitcnt lgkmcnt(0)
	s_barrier
	s_waitcnt lgkmcnt(0)
	v_mfma_f32_16x16x32_bf16 v[60:63], v[142:145], v[184:187], v[60:63]
	v_mfma_f32_16x16x32_bf16 v[56:59], v[158:161], v[184:187], v[56:59]
	v_mfma_f32_16x16x32_bf16 v[44:47], v[142:145], v[192:195], v[44:47]
	v_mfma_f32_16x16x32_bf16 v[40:43], v[158:161], v[192:195], v[40:43]
	v_mfma_f32_16x16x32_bf16 v[28:31], v[142:145], v[202:205], v[28:31]
	v_mfma_f32_16x16x32_bf16 v[24:27], v[158:161], v[202:205], v[24:27]
	v_mfma_f32_16x16x32_bf16 v[12:15], v[142:145], v[214:217], v[12:15]
	v_mfma_f32_16x16x32_bf16 v[8:11], v[158:161], v[214:217], v[8:11]
	v_mfma_f32_16x16x32_bf16 v[60:63], v[154:157], v[188:191], v[60:63]
	v_mfma_f32_16x16x32_bf16 v[56:59], v[162:165], v[188:191], v[56:59]
	v_mfma_f32_16x16x32_bf16 v[44:47], v[154:157], v[196:199], v[44:47]
	v_mfma_f32_16x16x32_bf16 v[40:43], v[162:165], v[196:199], v[40:43]
	v_mfma_f32_16x16x32_bf16 v[28:31], v[154:157], v[210:213], v[28:31]
	v_mfma_f32_16x16x32_bf16 v[24:27], v[162:165], v[210:213], v[24:27]
	v_mfma_f32_16x16x32_bf16 v[12:15], v[154:157], v[218:221], v[12:15]
	v_mfma_f32_16x16x32_bf16 v[8:11], v[162:165], v[218:221], v[8:11]
	v_mfma_f32_16x16x32_bf16 v[52:55], v[166:169], v[184:187], v[52:55]
	v_mfma_f32_16x16x32_bf16 v[48:51], v[176:179], v[184:187], v[48:51]
	v_mfma_f32_16x16x32_bf16 v[36:39], v[166:169], v[192:195], v[36:39]
	v_mfma_f32_16x16x32_bf16 v[32:35], v[176:179], v[192:195], v[32:35]
	v_mfma_f32_16x16x32_bf16 v[20:23], v[166:169], v[202:205], v[20:23]
	v_mfma_f32_16x16x32_bf16 v[16:19], v[176:179], v[202:205], v[16:19]
	v_mfma_f32_16x16x32_bf16 v[4:7], v[166:169], v[214:217], v[4:7]
	v_mfma_f32_16x16x32_bf16 v[0:3], v[176:179], v[214:217], v[0:3]
	v_mfma_f32_16x16x32_bf16 v[52:55], v[170:173], v[188:191], v[52:55]
	v_mfma_f32_16x16x32_bf16 v[48:51], v[180:183], v[188:191], v[48:51]
	v_mfma_f32_16x16x32_bf16 v[36:39], v[170:173], v[196:199], v[36:39]
	v_mfma_f32_16x16x32_bf16 v[32:35], v[180:183], v[196:199], v[32:35]
	v_mfma_f32_16x16x32_bf16 v[20:23], v[170:173], v[210:213], v[20:23]
	v_mfma_f32_16x16x32_bf16 v[16:19], v[180:183], v[210:213], v[16:19]
	v_mfma_f32_16x16x32_bf16 v[4:7], v[170:173], v[218:221], v[4:7]
	v_mfma_f32_16x16x32_bf16 v[0:3], v[180:183], v[218:221], v[0:3]
	s_add_i32 s58, s58, 2
	s_add_u32 s34, s34, 0x100
	s_addc_u32 s35, s35, 0
	s_add_u32 s56, s56, 0x100
	s_addc_u32 s57, s57, 0
	s_cmp_gt_u32 s58, 13
	s_barrier
	s_cbranch_scc0 .LBB0_854
	s_setprio 0
	s_and_b64 vcc, exec, s[20:21]
	s_cbranch_vccz .LBB0_857
	s_barrier

;     __host__ __device__ bool next(int i, Unit& u) const { return at((long)i * G + c, u); }
;     __host__ __device__ bool next(int i, Unit& u) const { if (i != 0 || c >= cnt) return false; u.pm = pm0 + c / nN; u.pn = c % nN; u.k0 = 0; u.nt = ntk; return true; }
; #define PG8_STAGE(bufoff, gbase, voff) do { _Pragma("unroll") for (int _i = 0; _i < 2; ++_i) \
;         __builtin_amdgcn_global_load_lds((const unsigned*)((const char*)(gbase) + (voff)[_i]), (PG8_LAS unsigned*)(lds + (bufoff) + ldsw + _i * 8192), 16, 0, 0); } while (0)
; #define PG8_STAGEA(bufoff, gbase, voff) do { _Pragma("unroll") for (int _i = 0; _i < 2; ++_i) \
;         __builtin_amdgcn_global_load_lds((const unsigned*)((const char*)(gbase) + (voff)[_i]), (PG8_LAS unsigned*)(lds + (bufoff) + ldsw + _i * 8192), 16, 0, AUXA); } while (0)
; #define PG8_LDA(dst, b, h) do { _Pragma("unroll") for (int m = 0; m < 4; ++m) _Pragma("unroll") for (int k = 0; k < 2; ++k) dst[m][k] = *(const PG8_LAS bf16x8*)(lds + PG8_SA(b, h) + aoff + m * 2048 + k * 1024); } while (0)
; #define PG8_WAIT_V(n) asm volatile("s_waitcnt vmcnt(" #n ")" ::: "memory")
;     ...
;         const bool has_next = S.next(ui + 1, nxt);
;         const char* nA = has_next ? (const char*)g.A + (size_t)nxt.pm * tstep + (size_t)nxt.k0 * (BK * 2) : cA; const char* nB = has_next ? (const char*)g.Bt + (size_t)nxt.pn * tstep + (size_t)nxt.k0 * (BK * 2) : cB;
;         const int nt = cur.nt;
;         for (int t = 0; t < nt; t += 2) {
;             const bool last = (t == nt - 2);
;             const char* a1 = cA + (size_t)(t + 1) * kstep;
;             const char* a2 = last ? nA : cA + (size_t)(t + 2) * kstep; const char* b2 = last ? nB : cB + (size_t)(t + 2) * kstep;
;             const char* a3 = a2 + kstep; const char* b3 = b2 + kstep;
;             if (last && has_next) S.a_ready(nxt);
;             if constexpr (SP2) {
;             PG8_LDB(B0, 0, 0); PG8_LDB(B1, 0, 1); PG8_SCHED; PG8_LDA(At, 0, 0); PG8_STAGEA(PG8_SA(1, 1), a1 + hstep, voffA);
;             PG8_WAIT_V(8); PG8_WAIT_L(0); PG8_BAR; PG8_MMA(0, 0, At, B0); PG8_MMA(0, 1, At, B1); PG8_BAR; PG8_SCHED;
;             PG8_LDA(At, 0, 1); PG8_STAGE(PG8_SB(0, 0), b2, voffB); PG8_STAGE(PG8_SB(0, 1), b2 + hstepB, voffB); PG8_STAGEA(PG8_SA(0, 0), a2, voffA);
;             PG8_WAIT_V(8); PG8_WAIT_L(0); PG8_BAR; PG8_MMA(1, 0, At, B0); PG8_MMA(1, 1, At, B1); PG8_BAR; PG8_SCHED;
.Lsprio_4:
.LBB0_888:
	v_add_u32_e32 v162, s12, v148
	v_add_u32_e32 v174, s50, v148
	s_add_u32 s38, s34, s36
	ds_read_b128 v[150:153], v162
	ds_read_b128 v[154:157], v162 offset:1024
	ds_read_b128 v[158:161], v162 offset:2048
	ds_read_b128 v[162:165], v162 offset:3072
	ds_read_b128 v[166:169], v174
	ds_read_b128 v[170:173], v174 offset:1024
	ds_read_b128 v[176:179], v174 offset:2048
	ds_read_b128 v[180:183], v174 offset:3072
	s_addc_u32 s39, s35, s37
	s_add_u32 s38, s38, 0x100
	s_addc_u32 s39, s39, 0
	s_add_u32 s59, s54, s36
	s_addc_u32 s70, s55, s37
	s_cmpk_eq_i32 s36, 0x700
	s_cselect_b32 s41, s27, s39
	s_cselect_b32 s40, s56, s38
	s_cselect_b32 s39, s25, s70
	s_cselect_b32 s38, s57, s59
	v_lshl_add_u64 v[206:207], v[142:143], 0, s[36:37]
	s_add_i32 m0, s17, 0xc000
	ds_read_b128 v[184:187], v149
	ds_read_b128 v[188:191], v149 offset:1024
	ds_read_b128 v[192:195], v149 offset:2048
	ds_read_b128 v[196:199], v149 offset:3072
	ds_read_b128 v[202:205], v149 offset:4096
	ds_read_b128 v[210:213], v149 offset:5120
	ds_read_b128 v[214:217], v149 offset:6144
	ds_read_b128 v[218:221], v149 offset:7168
	global_load_lds_dwordx4 v[206:207], off
	v_lshl_add_u64 v[206:207], v[144:145], 0, s[36:37]
	s_add_i32 m0, s17, 0xe000
	s_nop 0
	global_load_lds_dwordx4 v[206:207], off
	s_waitcnt vmcnt(8)
	s_waitcnt lgkmcnt(0)
	s_barrier
	s_waitcnt lgkmcnt(0)
	v_mfma_f32_16x16x32_bf16 v[124:127], v[150:153], v[184:187], v[124:127]
	v_mfma_f32_16x16x32_bf16 v[120:123], v[158:161], v[184:187], v[120:123]
	v_mfma_f32_16x16x32_bf16 v[108:111], v[150:153], v[192:195], v[108:111]
	v_mfma_f32_16x16x32_bf16 v[104:107], v[158:161], v[192:195], v[104:107]
	v_mfma_f32_16x16x32_bf16 v[92:95], v[150:153], v[202:205], v[92:95]
	v_mfma_f32_16x16x32_bf16 v[88:91], v[158:161], v[202:205], v[88:91]
	v_mfma_f32_16x16x32_bf16 v[76:79], v[150:153], v[214:217], v[76:79]
	v_mfma_f32_16x16x32_bf16 v[72:75], v[158:161], v[214:217], v[72:75]
	v_mfma_f32_16x16x32_bf16 v[124:127], v[154:157], v[188:191], v[124:127]
	v_mfma_f32_16x16x32_bf16 v[120:123], v[162:165], v[188:191], v[120:123]
	v_mfma_f32_16x16x32_bf16 v[108:111], v[154:157], v[196:199], v[108:111]
	v_mfma_f32_16x16x32_bf16 v[104:107], v[162:165], v[196:199], v[104:107]
	v_mfma_f32_16x16x32_bf16 v[92:95], v[154:157], v[210:213], v[92:95]
	v_mfma_f32_16x16x32_bf16 v[88:91], v[162:165], v[210:213], v[88:91]
	v_mfma_f32_16x16x32_bf16 v[76:79], v[154:157], v[218:221], v[76:79]
	v_mfma_f32_16x16x32_bf16 v[72:75], v[162:165], v[218:221], v[72:75]
	v_mfma_f32_16x16x32_bf16 v[116:119], v[166:169], v[184:187], v[116:119]
	v_mfma_f32_16x16x32_bf16 v[112:115], v[176:179], v[184:187], v[112:115]
	v_mfma_f32_16x16x32_bf16 v[100:103], v[166:169], v[192:195], v[100:103]
	v_mfma_f32_16x16x32_bf16 v[96:99], v[176:179], v[192:195], v[96:99]
	v_mfma_f32_16x16x32_bf16 v[84:87], v[166:169], v[202:205], v[84:87]
	v_mfma_f32_16x16x32_bf16 v[80:83], v[176:179], v[202:205], v[80:83]
	v_mfma_f32_16x16x32_bf16 v[68:71], v[166:169], v[214:217], v[68:71]
	v_mfma_f32_16x16x32_bf16 v[64:67], v[176:179], v[214:217], v[64:67]
	v_mfma_f32_16x16x32_bf16 v[116:119], v[170:173], v[188:191], v[116:119]
	v_mfma_f32_16x16x32_bf16 v[112:115], v[180:183], v[188:191], v[112:115]
	v_mfma_f32_16x16x32_bf16 v[100:103], v[170:173], v[196:199], v[100:103]
	v_mfma_f32_16x16x32_bf16 v[96:99], v[180:183], v[196:199], v[96:99]
	v_mfma_f32_16x16x32_bf16 v[84:87], v[170:173], v[210:213], v[84:87]
	v_mfma_f32_16x16x32_bf16 v[80:83], v[180:183], v[210:213], v[80:83]
	v_mfma_f32_16x16x32_bf16 v[68:71], v[170:173], v[218:221], v[68:71]
	v_mfma_f32_16x16x32_bf16 v[64:67], v[180:183], v[218:221], v[64:67]
	s_barrier
	s_add_i32 s59, s12, s67
	v_lshl_add_u64 v[206:207], s[38:39], 0, v[132:133]
	s_mov_b32 m0, s59
	ds_read_b128 v[184:187], v149 offset:16384
	ds_read_b128 v[188:191], v149 offset:17408
	ds_read_b128 v[192:195], v149 offset:18432
	ds_read_b128 v[196:199], v149 offset:19456
	ds_read_b128 v[202:205], v149 offset:20480
	ds_read_b128 v[210:213], v149 offset:21504
	ds_read_b128 v[214:217], v149 offset:22528
	ds_read_b128 v[218:221], v149 offset:23552
	global_load_lds_dwordx4 v[206:207], off
	s_add_i32 m0, s59, 0x2000
	s_add_u32 s70, s38, 0x10000
	v_lshl_add_u64 v[222:223], s[38:39], 0, v[128:129]
	s_addc_u32 s71, s39, 0
	s_add_i32 s59, s50, s67
	global_load_lds_dwordx4 v[222:223], off
	v_lshl_add_u64 v[224:225], s[70:71], 0, v[132:133]
	s_mov_b32 m0, s59
	v_lshl_add_u64 v[226:227], s[40:41], 0, v[130:131]
	global_load_lds_dwordx4 v[224:225], off
	v_lshl_add_u64 v[224:225], s[70:71], 0, v[128:129]
	s_add_i32 m0, s59, 0x2000
	s_nop 0
	global_load_lds_dwordx4 v[224:225], off
	v_lshl_add_u64 v[224:225], s[40:41], 0, v[134:135]
	s_mov_b32 m0, s17
	s_nop 0
	global_load_lds_dwordx4 v[224:225], off
	s_mov_b32 m0, s43
	s_nop 0
	global_load_lds_dwordx4 v[226:227], off
	s_waitcnt vmcnt(8)
	s_waitcnt lgkmcnt(0)
	s_barrier
; #define PG8_STAGE(bufoff, gbase, voff) do { _Pragma("unroll") for (int _i = 0; _i < 2; ++_i) \
;         __builtin_amdgcn_global_load_lds((const unsigned*)((const char*)(gbase) + (voff)[_i]), (PG8_LAS unsigned*)(lds + (bufoff) + ldsw + _i * 8192), 16, 0, 0); } while (0)
; #define PG8_STAGEA(bufoff, gbase, voff) do { _Pragma("unroll") for (int _i = 0; _i < 2; ++_i) \
;         __builtin_amdgcn_global_load_lds((const unsigned*)((const char*)(gbase) + (voff)[_i]), (PG8_LAS unsigned*)(lds + (bufoff) + ldsw + _i * 8192), 16, 0, AUXA); } while (0)
; #define PG8_LDA(dst, b, h) do { _Pragma("unroll") for (int m = 0; m < 4; ++m) _Pragma("unroll") for (int k = 0; k < 2; ++k) dst[m][k] = *(const PG8_LAS bf16x8*)(lds + PG8_SA(b, h) + aoff + m * 2048 + k * 1024); } while (0)
; #define PG8_LDB(dst, b, h) do { _Pragma("unroll") for (int n = 0; n < 2; ++n) _Pragma("unroll") for (int k = 0; k < 2; ++k) dst[n][k] = *(const PG8_LAS bf16x8*)(lds + PG8_SB(b, h) + boff + n * 2048 + k * 1024); } while (0)
; #define PG8_MMA(ai, bj, At, Bt) do { __builtin_amdgcn_s_setprio(1); _Pragma("unroll") for (int m = 0; m < 4; ++m) _Pragma("unroll") for (int n = 0; n < 2; ++n) _Pragma("unroll") for (int k = 0; k < 2; ++k) \
;         acc[ai][bj][m][n] = __builtin_amdgcn_mfma_f32_16x16x32_bf16(Bt[n][k], At[m][k], acc[ai][bj][m][n], 0, 0, 0); __builtin_amdgcn_s_setprio(0); } while (0)
; #define PG8_WAIT_V(n) asm volatile("s_waitcnt vmcnt(" #n ")" ::: "memory")
; #define PG8_WAIT_L(n) asm volatile("s_waitcnt lgkmcnt(" #n ")" ::: "memory")
; #define PG8_BAR __builtin_amdgcn_s_barrier()
; #define PG8_SCHED __builtin_amdgcn_sched_barrier(0)
;     ...
;             PG8_WAIT_V(8); PG8_WAIT_L(0); PG8_BAR; PG8_MMA(1, 0, At, B0); PG8_MMA(1, 1, At, B1); PG8_BAR; PG8_SCHED;
;             PG8_LDB(B0, 1, 0); PG8_LDB(B1, 1, 1); PG8_SCHED; PG8_LDA(At, 1, 0); PG8_STAGEA(PG8_SA(0, 1), a2 + hstep, voffA);
;             PG8_WAIT_V(8); PG8_WAIT_L(0); PG8_BAR; PG8_MMA(0, 0, At, B0); PG8_MMA(0, 1, At, B1); PG8_BAR; PG8_SCHED;
;             PG8_LDA(At, 1, 1); PG8_STAGE(PG8_SB(1, 0), b3, voffB); PG8_STAGE(PG8_SB(1, 1), b3 + hstepB, voffB); PG8_STAGEA(PG8_SA(1, 0), a3, voffA);
	s_waitcnt lgkmcnt(0)
	v_mfma_f32_16x16x32_bf16 v[60:63], v[150:153], v[184:187], v[60:63]
	v_mfma_f32_16x16x32_bf16 v[56:59], v[158:161], v[184:187], v[56:59]
	v_mfma_f32_16x16x32_bf16 v[44:47], v[150:153], v[192:195], v[44:47]
	v_mfma_f32_16x16x32_bf16 v[40:43], v[158:161], v[192:195], v[40:43]
	v_mfma_f32_16x16x32_bf16 v[28:31], v[150:153], v[202:205], v[28:31]
	v_mfma_f32_16x16x32_bf16 v[24:27], v[158:161], v[202:205], v[24:27]
	v_mfma_f32_16x16x32_bf16 v[12:15], v[150:153], v[214:217], v[12:15]
	v_mfma_f32_16x16x32_bf16 v[8:11], v[158:161], v[214:217], v[8:11]
	v_mfma_f32_16x16x32_bf16 v[60:63], v[154:157], v[188:191], v[60:63]
	v_mfma_f32_16x16x32_bf16 v[56:59], v[162:165], v[188:191], v[56:59]
	v_mfma_f32_16x16x32_bf16 v[44:47], v[154:157], v[196:199], v[44:47]
	v_mfma_f32_16x16x32_bf16 v[40:43], v[162:165], v[196:199], v[40:43]
	v_mfma_f32_16x16x32_bf16 v[28:31], v[154:157], v[210:213], v[28:31]
	v_mfma_f32_16x16x32_bf16 v[24:27], v[162:165], v[210:213], v[24:27]
	v_mfma_f32_16x16x32_bf16 v[12:15], v[154:157], v[218:221], v[12:15]
	v_mfma_f32_16x16x32_bf16 v[8:11], v[162:165], v[218:221], v[8:11]
	v_mfma_f32_16x16x32_bf16 v[52:55], v[166:169], v[184:187], v[52:55]
	v_mfma_f32_16x16x32_bf16 v[48:51], v[176:179], v[184:187], v[48:51]
	v_mfma_f32_16x16x32_bf16 v[36:39], v[166:169], v[192:195], v[36:39]
	v_mfma_f32_16x16x32_bf16 v[32:35], v[176:179], v[192:195], v[32:35]
	v_mfma_f32_16x16x32_bf16 v[20:23], v[166:169], v[202:205], v[20:23]
	v_mfma_f32_16x16x32_bf16 v[16:19], v[176:179], v[202:205], v[16:19]
	v_mfma_f32_16x16x32_bf16 v[4:7], v[166:169], v[214:217], v[4:7]
	v_mfma_f32_16x16x32_bf16 v[0:3], v[176:179], v[214:217], v[0:3]
	v_mfma_f32_16x16x32_bf16 v[52:55], v[170:173], v[188:191], v[52:55]
	v_mfma_f32_16x16x32_bf16 v[48:51], v[180:183], v[188:191], v[48:51]
	v_mfma_f32_16x16x32_bf16 v[36:39], v[170:173], v[196:199], v[36:39]
	v_mfma_f32_16x16x32_bf16 v[32:35], v[180:183], v[196:199], v[32:35]
	v_mfma_f32_16x16x32_bf16 v[20:23], v[170:173], v[210:213], v[20:23]
	v_mfma_f32_16x16x32_bf16 v[16:19], v[180:183], v[210:213], v[16:19]
	v_mfma_f32_16x16x32_bf16 v[4:7], v[170:173], v[218:221], v[4:7]
	v_mfma_f32_16x16x32_bf16 v[0:3], v[180:183], v[218:221], v[0:3]
	s_barrier
	s_add_i32 s59, 0, 0x18000
	s_add_i32 s70, 0, 0x1c000
	v_add_u32_e32 v162, s59, v148
	v_add_u32_e32 v174, s70, v148
	ds_read_b128 v[150:153], v162
	ds_read_b128 v[154:157], v162 offset:1024
	ds_read_b128 v[158:161], v162 offset:2048
	ds_read_b128 v[162:165], v162 offset:3072
	ds_read_b128 v[166:169], v174
	ds_read_b128 v[170:173], v174 offset:1024
	ds_read_b128 v[176:179], v174 offset:2048
	ds_read_b128 v[180:183], v174 offset:3072
	s_add_u32 s40, s40, 0x40000
	s_addc_u32 s41, s41, 0
	s_mov_b32 m0, s44
	v_lshl_add_u64 v[228:229], s[40:41], 0, v[134:135]
	ds_read_b128 v[184:187], v149 offset:32768
	ds_read_b128 v[188:191], v149 offset:33792
	ds_read_b128 v[192:195], v149 offset:34816
	ds_read_b128 v[196:199], v149 offset:35840
	ds_read_b128 v[202:205], v149 offset:36864
	ds_read_b128 v[210:213], v149 offset:37888
	ds_read_b128 v[214:217], v149 offset:38912
	ds_read_b128 v[218:221], v149 offset:39936
	global_load_lds_dwordx4 v[228:229], off
	v_lshl_add_u64 v[228:229], s[40:41], 0, v[130:131]
	s_mov_b32 m0, s45
	s_nop 0
	global_load_lds_dwordx4 v[228:229], off
	s_waitcnt vmcnt(8)
	s_waitcnt lgkmcnt(0)
	s_barrier
	s_waitcnt lgkmcnt(0)
	v_mfma_f32_16x16x32_bf16 v[124:127], v[150:153], v[184:187], v[124:127]
	v_mfma_f32_16x16x32_bf16 v[120:123], v[158:161], v[184:187], v[120:123]
	v_mfma_f32_16x16x32_bf16 v[108:111], v[150:153], v[192:195], v[108:111]
	v_mfma_f32_16x16x32_bf16 v[104:107], v[158:161], v[192:195], v[104:107]
	v_mfma_f32_16x16x32_bf16 v[92:95], v[150:153], v[202:205], v[92:95]
	v_mfma_f32_16x16x32_bf16 v[88:91], v[158:161], v[202:205], v[88:91]
	v_mfma_f32_16x16x32_bf16 v[76:79], v[150:153], v[214:217], v[76:79]
	v_mfma_f32_16x16x32_bf16 v[72:75], v[158:161], v[214:217], v[72:75]
	v_mfma_f32_16x16x32_bf16 v[124:127], v[154:157], v[188:191], v[124:127]
	v_mfma_f32_16x16x32_bf16 v[120:123], v[162:165], v[188:191], v[120:123]
	v_mfma_f32_16x16x32_bf16 v[108:111], v[154:157], v[196:199], v[108:111]
	v_mfma_f32_16x16x32_bf16 v[104:107], v[162:165], v[196:199], v[104:107]
	v_mfma_f32_16x16x32_bf16 v[92:95], v[154:157], v[210:213], v[92:95]
	v_mfma_f32_16x16x32_bf16 v[88:91], v[162:165], v[210:213], v[88:91]
	v_mfma_f32_16x16x32_bf16 v[76:79], v[154:157], v[218:221], v[76:79]
	v_mfma_f32_16x16x32_bf16 v[72:75], v[162:165], v[218:221], v[72:75]
	v_mfma_f32_16x16x32_bf16 v[116:119], v[166:169], v[184:187], v[116:119]
	v_mfma_f32_16x16x32_bf16 v[112:115], v[176:179], v[184:187], v[112:115]
	v_mfma_f32_16x16x32_bf16 v[100:103], v[166:169], v[192:195], v[100:103]
	v_mfma_f32_16x16x32_bf16 v[96:99], v[176:179], v[192:195], v[96:99]
	v_mfma_f32_16x16x32_bf16 v[84:87], v[166:169], v[202:205], v[84:87]
	v_mfma_f32_16x16x32_bf16 v[80:83], v[176:179], v[202:205], v[80:83]
	v_mfma_f32_16x16x32_bf16 v[68:71], v[166:169], v[214:217], v[68:71]
	v_mfma_f32_16x16x32_bf16 v[64:67], v[176:179], v[214:217], v[64:67]
	v_mfma_f32_16x16x32_bf16 v[116:119], v[170:173], v[188:191], v[116:119]
	v_mfma_f32_16x16x32_bf16 v[112:115], v[180:183], v[188:191], v[112:115]
	v_mfma_f32_16x16x32_bf16 v[100:103], v[170:173], v[196:199], v[100:103]
	v_mfma_f32_16x16x32_bf16 v[96:99], v[180:183], v[196:199], v[96:99]
	v_mfma_f32_16x16x32_bf16 v[84:87], v[170:173], v[210:213], v[84:87]
	v_mfma_f32_16x16x32_bf16 v[80:83], v[180:183], v[210:213], v[80:83]
	v_mfma_f32_16x16x32_bf16 v[68:71], v[170:173], v[218:221], v[68:71]
	v_mfma_f32_16x16x32_bf16 v[64:67], v[180:183], v[218:221], v[64:67]
	s_barrier
; #define PG8_STAGE(bufoff, gbase, voff) do { _Pragma("unroll") for (int _i = 0; _i < 2; ++_i) \
;         __builtin_amdgcn_global_load_lds((const unsigned*)((const char*)(gbase) + (voff)[_i]), (PG8_LAS unsigned*)(lds + (bufoff) + ldsw + _i * 8192), 16, 0, 0); } while (0)
; #define PG8_STAGEA(bufoff, gbase, voff) do { _Pragma("unroll") for (int _i = 0; _i < 2; ++_i) \
;         __builtin_amdgcn_global_load_lds((const unsigned*)((const char*)(gbase) + (voff)[_i]), (PG8_LAS unsigned*)(lds + (bufoff) + ldsw + _i * 8192), 16, 0, AUXA); } while (0)
; #define PG8_LDA(dst, b, h) do { _Pragma("unroll") for (int m = 0; m < 4; ++m) _Pragma("unroll") for (int k = 0; k < 2; ++k) dst[m][k] = *(const PG8_LAS bf16x8*)(lds + PG8_SA(b, h) + aoff + m * 2048 + k * 1024); } while (0)
; #define PG8_MMA(ai, bj, At, Bt) do { __builtin_amdgcn_s_setprio(1); _Pragma("unroll") for (int m = 0; m < 4; ++m) _Pragma("unroll") for (int n = 0; n < 2; ++n) _Pragma("unroll") for (int k = 0; k < 2; ++k) \
;         acc[ai][bj][m][n] = __builtin_amdgcn_mfma_f32_16x16x32_bf16(Bt[n][k], At[m][k], acc[ai][bj][m][n], 0, 0, 0); __builtin_amdgcn_s_setprio(0); } while (0)
; #define PG8_WAIT_V(n) asm volatile("s_waitcnt vmcnt(" #n ")" ::: "memory")
; #define PG8_WAIT_L(n) asm volatile("s_waitcnt lgkmcnt(" #n ")" ::: "memory")
; #define PG8_BAR __builtin_amdgcn_s_barrier()
; #define PG8_SCHED __builtin_amdgcn_sched_barrier(0)
;     ...
;         for (int t = 0; t < nt; t += 2) {
;     ...
;             PG8_LDA(At, 1, 1); PG8_STAGE(PG8_SB(1, 0), b3, voffB); PG8_STAGE(PG8_SB(1, 1), b3 + hstepB, voffB); PG8_STAGEA(PG8_SA(1, 0), a3, voffA);
;             PG8_WAIT_V(8); PG8_WAIT_L(0); PG8_BAR; PG8_MMA(1, 0, At, B0); PG8_MMA(1, 1, At, B1); PG8_BAR; PG8_SCHED;
	s_add_i32 s40, s59, s67
	v_lshl_add_u64 v[206:207], v[206:207], 0, s[20:21]
	s_mov_b32 m0, s40
	ds_read_b128 v[184:187], v149 offset:49152
	ds_read_b128 v[188:191], v149 offset:50176
	ds_read_b128 v[192:195], v149 offset:51200
	ds_read_b128 v[196:199], v149 offset:52224
	ds_read_b128 v[202:205], v149 offset:53248
	ds_read_b128 v[210:213], v149 offset:54272
	ds_read_b128 v[214:217], v149 offset:55296
	ds_read_b128 v[218:221], v149 offset:56320
	global_load_lds_dwordx4 v[206:207], off
	s_add_i32 m0, s40, 0x2000
	s_add_u32 s38, s38, 0x10080
	v_lshl_add_u64 v[206:207], v[222:223], 0, s[20:21]
	s_addc_u32 s39, s39, 0
	s_add_i32 s40, s70, s67
	global_load_lds_dwordx4 v[206:207], off
	v_lshl_add_u64 v[206:207], s[38:39], 0, v[132:133]
	s_mov_b32 m0, s40
	s_nop 0
	global_load_lds_dwordx4 v[206:207], off
	v_lshl_add_u64 v[206:207], s[38:39], 0, v[128:129]
	s_add_i32 m0, s40, 0x2000
	s_nop 0
	global_load_lds_dwordx4 v[206:207], off
	v_lshl_add_u64 v[206:207], v[224:225], 0, s[20:21]
	s_mov_b32 m0, s46
	s_nop 0
	global_load_lds_dwordx4 v[206:207], off
	v_lshl_add_u64 v[206:207], v[226:227], 0, s[20:21]
	s_mov_b32 m0, s47
	s_nop 0
	global_load_lds_dwordx4 v[206:207], off
	s_waitcnt vmcnt(8)
	s_waitcnt lgkmcnt(0)
	s_barrier
	s_waitcnt lgkmcnt(0)
	v_mfma_f32_16x16x32_bf16 v[60:63], v[150:153], v[184:187], v[60:63]
	v_mfma_f32_16x16x32_bf16 v[56:59], v[158:161], v[184:187], v[56:59]
	v_mfma_f32_16x16x32_bf16 v[44:47], v[150:153], v[192:195], v[44:47]
	v_mfma_f32_16x16x32_bf16 v[40:43], v[158:161], v[192:195], v[40:43]
	v_mfma_f32_16x16x32_bf16 v[28:31], v[150:153], v[202:205], v[28:31]
	v_mfma_f32_16x16x32_bf16 v[24:27], v[158:161], v[202:205], v[24:27]
	v_mfma_f32_16x16x32_bf16 v[12:15], v[150:153], v[214:217], v[12:15]
	v_mfma_f32_16x16x32_bf16 v[8:11], v[158:161], v[214:217], v[8:11]
	v_mfma_f32_16x16x32_bf16 v[60:63], v[154:157], v[188:191], v[60:63]
	v_mfma_f32_16x16x32_bf16 v[56:59], v[162:165], v[188:191], v[56:59]
	v_mfma_f32_16x16x32_bf16 v[44:47], v[154:157], v[196:199], v[44:47]
	v_mfma_f32_16x16x32_bf16 v[40:43], v[162:165], v[196:199], v[40:43]
	v_mfma_f32_16x16x32_bf16 v[28:31], v[154:157], v[210:213], v[28:31]
	v_mfma_f32_16x16x32_bf16 v[24:27], v[162:165], v[210:213], v[24:27]
	v_mfma_f32_16x16x32_bf16 v[12:15], v[154:157], v[218:221], v[12:15]
	v_mfma_f32_16x16x32_bf16 v[8:11], v[162:165], v[218:221], v[8:11]
	v_mfma_f32_16x16x32_bf16 v[52:55], v[166:169], v[184:187], v[52:55]
	v_mfma_f32_16x16x32_bf16 v[48:51], v[176:179], v[184:187], v[48:51]
	v_mfma_f32_16x16x32_bf16 v[36:39], v[166:169], v[192:195], v[36:39]
	v_mfma_f32_16x16x32_bf16 v[32:35], v[176:179], v[192:195], v[32:35]
	v_mfma_f32_16x16x32_bf16 v[20:23], v[166:169], v[202:205], v[20:23]
	v_mfma_f32_16x16x32_bf16 v[16:19], v[176:179], v[202:205], v[16:19]
	v_mfma_f32_16x16x32_bf16 v[4:7], v[166:169], v[214:217], v[4:7]
	v_mfma_f32_16x16x32_bf16 v[0:3], v[176:179], v[214:217], v[0:3]
	v_mfma_f32_16x16x32_bf16 v[52:55], v[170:173], v[188:191], v[52:55]
	v_mfma_f32_16x16x32_bf16 v[48:51], v[180:183], v[188:191], v[48:51]
	v_mfma_f32_16x16x32_bf16 v[36:39], v[170:173], v[196:199], v[36:39]
	v_mfma_f32_16x16x32_bf16 v[32:35], v[180:183], v[196:199], v[32:35]
	v_mfma_f32_16x16x32_bf16 v[20:23], v[170:173], v[210:213], v[20:23]
	v_mfma_f32_16x16x32_bf16 v[16:19], v[180:183], v[210:213], v[16:19]
	v_mfma_f32_16x16x32_bf16 v[4:7], v[170:173], v[218:221], v[4:7]
	v_mfma_f32_16x16x32_bf16 v[0:3], v[180:183], v[218:221], v[0:3]
	s_add_i32 s58, s58, 2
	s_add_u32 s36, s36, 0x100
	s_addc_u32 s37, s37, 0
	s_cmp_gt_u32 s58, 13
	s_barrier
	s_cbranch_scc0 .LBB0_888
	s_setprio 0
	s_and_b64 vcc, exec, s[22:23]
	s_cbranch_vccz .LBB0_891
	s_barrier

; #define PG8_STAGE(bufoff, gbase, voff) do { _Pragma("unroll") for (int _i = 0; _i < 2; ++_i) \
;         __builtin_amdgcn_global_load_lds((const unsigned*)((const char*)(gbase) + (voff)[_i]), (PG8_LAS unsigned*)(lds + (bufoff) + ldsw + _i * 8192), 16, 0, 0); } while (0)
; #define PG8_STAGEA(bufoff, gbase, voff) do { _Pragma("unroll") for (int _i = 0; _i < 2; ++_i) \
;         __builtin_amdgcn_global_load_lds((const unsigned*)((const char*)(gbase) + (voff)[_i]), (PG8_LAS unsigned*)(lds + (bufoff) + ldsw + _i * 8192), 16, 0, AUXA); } while (0)
; #define PG8_LDA(dst, b, h) do { _Pragma("unroll") for (int m = 0; m < 4; ++m) _Pragma("unroll") for (int k = 0; k < 2; ++k) dst[m][k] = *(const PG8_LAS bf16x8*)(lds + PG8_SA(b, h) + aoff + m * 2048 + k * 1024); } while (0)
; #define PG8_LDB(dst, b, h) do { _Pragma("unroll") for (int n = 0; n < 2; ++n) _Pragma("unroll") for (int k = 0; k < 2; ++k) dst[n][k] = *(const PG8_LAS bf16x8*)(lds + PG8_SB(b, h) + boff + n * 2048 + k * 1024); } while (0)
; #define PG8_MMA(ai, bj, At, Bt) do { __builtin_amdgcn_s_setprio(1); _Pragma("unroll") for (int m = 0; m < 4; ++m) _Pragma("unroll") for (int n = 0; n < 2; ++n) _Pragma("unroll") for (int k = 0; k < 2; ++k) \
;         acc[ai][bj][m][n] = __builtin_amdgcn_mfma_f32_16x16x32_bf16(Bt[n][k], At[m][k], acc[ai][bj][m][n], 0, 0, 0); __builtin_amdgcn_s_setprio(0); } while (0)
; #define PG8_WAIT_V(n) asm volatile("s_waitcnt vmcnt(" #n ")" ::: "memory")
; #define PG8_WAIT_L(n) asm volatile("s_waitcnt lgkmcnt(" #n ")" ::: "memory")
; #define PG8_BAR __builtin_amdgcn_s_barrier()
; #define PG8_SCHED __builtin_amdgcn_sched_barrier(0)
;     ...
;             PG8_WAIT_V(8); PG8_WAIT_L(0); PG8_BAR; PG8_MMA(1, 0, At, B0); PG8_MMA(1, 1, At, B1); PG8_BAR; PG8_SCHED;
;             PG8_LDB(B0, 1, 0); PG8_LDB(B1, 1, 1); PG8_SCHED; PG8_LDA(At, 1, 0); PG8_STAGEA(PG8_SA(0, 1), a2 + hstep, voffA);
;             PG8_WAIT_V(8); PG8_WAIT_L(0); PG8_BAR; PG8_MMA(0, 0, At, B0); PG8_MMA(0, 1, At, B1); PG8_BAR; PG8_SCHED;
;             PG8_LDA(At, 1, 1); PG8_STAGE(PG8_SB(1, 0), b3, voffB); PG8_STAGE(PG8_SB(1, 1), b3 + hstepB, voffB); PG8_STAGEA(PG8_SA(1, 0), a3, voffA);
.Lfiw_p6_0:
	s_waitcnt lgkmcnt(0)
	s_barrier
	s_waitcnt lgkmcnt(0)
	v_mfma_f32_16x16x32_bf16 v[60:63], v[144:147], v[184:187], v[60:63]
	v_mfma_f32_16x16x32_bf16 v[56:59], v[152:155], v[184:187], v[56:59]
	v_mfma_f32_16x16x32_bf16 v[44:47], v[144:147], v[192:195], v[44:47]
	v_mfma_f32_16x16x32_bf16 v[40:43], v[152:155], v[192:195], v[40:43]
	v_mfma_f32_16x16x32_bf16 v[28:31], v[144:147], v[202:205], v[28:31]
	v_mfma_f32_16x16x32_bf16 v[24:27], v[152:155], v[202:205], v[24:27]
	v_mfma_f32_16x16x32_bf16 v[12:15], v[144:147], v[214:217], v[12:15]
	v_mfma_f32_16x16x32_bf16 v[8:11], v[152:155], v[214:217], v[8:11]
	v_mfma_f32_16x16x32_bf16 v[60:63], v[148:151], v[188:191], v[60:63]
	v_mfma_f32_16x16x32_bf16 v[56:59], v[156:159], v[188:191], v[56:59]
	v_mfma_f32_16x16x32_bf16 v[44:47], v[148:151], v[196:199], v[44:47]
	v_mfma_f32_16x16x32_bf16 v[40:43], v[156:159], v[196:199], v[40:43]
	v_mfma_f32_16x16x32_bf16 v[28:31], v[148:151], v[210:213], v[28:31]
	v_mfma_f32_16x16x32_bf16 v[24:27], v[156:159], v[210:213], v[24:27]
	v_mfma_f32_16x16x32_bf16 v[12:15], v[148:151], v[218:221], v[12:15]
	v_mfma_f32_16x16x32_bf16 v[8:11], v[156:159], v[218:221], v[8:11]
	v_mfma_f32_16x16x32_bf16 v[52:55], v[160:163], v[184:187], v[52:55]
	v_mfma_f32_16x16x32_bf16 v[48:51], v[176:179], v[184:187], v[48:51]
	v_mfma_f32_16x16x32_bf16 v[36:39], v[160:163], v[192:195], v[36:39]
	v_mfma_f32_16x16x32_bf16 v[32:35], v[176:179], v[192:195], v[32:35]
	v_mfma_f32_16x16x32_bf16 v[20:23], v[160:163], v[202:205], v[20:23]
	v_mfma_f32_16x16x32_bf16 v[16:19], v[176:179], v[202:205], v[16:19]
	v_mfma_f32_16x16x32_bf16 v[4:7], v[160:163], v[214:217], v[4:7]
	v_mfma_f32_16x16x32_bf16 v[0:3], v[176:179], v[214:217], v[0:3]
	v_mfma_f32_16x16x32_bf16 v[52:55], v[164:167], v[188:191], v[52:55]
	v_mfma_f32_16x16x32_bf16 v[48:51], v[180:183], v[188:191], v[48:51]
	v_mfma_f32_16x16x32_bf16 v[36:39], v[164:167], v[196:199], v[36:39]
	v_mfma_f32_16x16x32_bf16 v[32:35], v[180:183], v[196:199], v[32:35]
	v_mfma_f32_16x16x32_bf16 v[20:23], v[164:167], v[210:213], v[20:23]
	v_mfma_f32_16x16x32_bf16 v[16:19], v[180:183], v[210:213], v[16:19]
	v_mfma_f32_16x16x32_bf16 v[4:7], v[164:167], v[218:221], v[4:7]
	v_mfma_f32_16x16x32_bf16 v[0:3], v[180:183], v[218:221], v[0:3]
	s_barrier
	s_add_i32 s73, 0, 0x18000
	s_add_i32 s74, 0, 0x1c000
	v_add_u32_e32 v156, s73, v169
	v_add_u32_e32 v173, s74, v169
	ds_read_b128 v[144:147], v156
	ds_read_b128 v[148:151], v156 offset:1024
	ds_read_b128 v[152:155], v156 offset:2048
	ds_read_b128 v[156:159], v156 offset:3072
	ds_read_b128 v[160:163], v173
	ds_read_b128 v[164:167], v173 offset:1024
	ds_read_b128 v[176:179], v173 offset:2048
	ds_read_b128 v[180:183], v173 offset:3072
	s_add_u32 s42, s42, 0x40000
	s_addc_u32 s43, s43, 0
	s_mov_b32 m0, s47
	v_lshl_add_u64 v[228:229], s[42:43], 0, v[134:135]
	ds_read_b128 v[184:187], v172 offset:32768
	ds_read_b128 v[188:191], v172 offset:33792
	ds_read_b128 v[192:195], v172 offset:34816
	ds_read_b128 v[196:199], v172 offset:35840
	ds_read_b128 v[202:205], v172 offset:36864
	ds_read_b128 v[210:213], v172 offset:37888
	ds_read_b128 v[214:217], v172 offset:38912
	ds_read_b128 v[218:221], v172 offset:39936
	global_load_lds_dwordx4 v[228:229], off
	v_lshl_add_u64 v[228:229], s[42:43], 0, v[130:131]
	s_mov_b32 m0, s50
	s_nop 0
	global_load_lds_dwordx4 v[228:229], off
	s_mov_b32 s99, 0
	s_waitcnt vmcnt(8)
	s_waitcnt lgkmcnt(0)
	s_barrier
	s_waitcnt lgkmcnt(0)
	v_mfma_f32_16x16x32_bf16 v[124:127], v[144:147], v[184:187], v[124:127]
	v_mfma_f32_16x16x32_bf16 v[120:123], v[152:155], v[184:187], v[120:123]
	v_mfma_f32_16x16x32_bf16 v[108:111], v[144:147], v[192:195], v[108:111]
	v_mfma_f32_16x16x32_bf16 v[104:107], v[152:155], v[192:195], v[104:107]
	v_mfma_f32_16x16x32_bf16 v[92:95], v[144:147], v[202:205], v[92:95]
	v_mfma_f32_16x16x32_bf16 v[88:91], v[152:155], v[202:205], v[88:91]
	v_mfma_f32_16x16x32_bf16 v[76:79], v[144:147], v[214:217], v[76:79]
	v_mfma_f32_16x16x32_bf16 v[72:75], v[152:155], v[214:217], v[72:75]
	v_mfma_f32_16x16x32_bf16 v[124:127], v[148:151], v[188:191], v[124:127]
	v_mfma_f32_16x16x32_bf16 v[120:123], v[156:159], v[188:191], v[120:123]
	v_mfma_f32_16x16x32_bf16 v[108:111], v[148:151], v[196:199], v[108:111]
	v_mfma_f32_16x16x32_bf16 v[104:107], v[156:159], v[196:199], v[104:107]
	v_mfma_f32_16x16x32_bf16 v[92:95], v[148:151], v[210:213], v[92:95]
	v_mfma_f32_16x16x32_bf16 v[88:91], v[156:159], v[210:213], v[88:91]
	v_mfma_f32_16x16x32_bf16 v[76:79], v[148:151], v[218:221], v[76:79]
	v_mfma_f32_16x16x32_bf16 v[72:75], v[156:159], v[218:221], v[72:75]
	v_mfma_f32_16x16x32_bf16 v[116:119], v[160:163], v[184:187], v[116:119]
	v_mfma_f32_16x16x32_bf16 v[112:115], v[176:179], v[184:187], v[112:115]
	v_mfma_f32_16x16x32_bf16 v[100:103], v[160:163], v[192:195], v[100:103]
	v_mfma_f32_16x16x32_bf16 v[96:99], v[176:179], v[192:195], v[96:99]
	v_mfma_f32_16x16x32_bf16 v[84:87], v[160:163], v[202:205], v[84:87]
	v_mfma_f32_16x16x32_bf16 v[80:83], v[176:179], v[202:205], v[80:83]
	v_mfma_f32_16x16x32_bf16 v[68:71], v[160:163], v[214:217], v[68:71]
	v_mfma_f32_16x16x32_bf16 v[64:67], v[176:179], v[214:217], v[64:67]
	v_mfma_f32_16x16x32_bf16 v[116:119], v[164:167], v[188:191], v[116:119]
	v_mfma_f32_16x16x32_bf16 v[112:115], v[180:183], v[188:191], v[112:115]
	v_mfma_f32_16x16x32_bf16 v[100:103], v[164:167], v[196:199], v[100:103]
	v_mfma_f32_16x16x32_bf16 v[96:99], v[180:183], v[196:199], v[96:99]
	v_mfma_f32_16x16x32_bf16 v[84:87], v[164:167], v[210:213], v[84:87]
	v_mfma_f32_16x16x32_bf16 v[80:83], v[180:183], v[210:213], v[80:83]
	v_mfma_f32_16x16x32_bf16 v[68:71], v[164:167], v[218:221], v[68:71]
	v_mfma_f32_16x16x32_bf16 v[64:67], v[180:183], v[218:221], v[64:67]
	s_barrier
; #define PG8_STAGE(bufoff, gbase, voff) do { _Pragma("unroll") for (int _i = 0; _i < 2; ++_i) \
;         __builtin_amdgcn_global_load_lds((const unsigned*)((const char*)(gbase) + (voff)[_i]), (PG8_LAS unsigned*)(lds + (bufoff) + ldsw + _i * 8192), 16, 0, 0); } while (0)
; #define PG8_STAGEA(bufoff, gbase, voff) do { _Pragma("unroll") for (int _i = 0; _i < 2; ++_i) \
;         __builtin_amdgcn_global_load_lds((const unsigned*)((const char*)(gbase) + (voff)[_i]), (PG8_LAS unsigned*)(lds + (bufoff) + ldsw + _i * 8192), 16, 0, AUXA); } while (0)
; #define PG8_LDA(dst, b, h) do { _Pragma("unroll") for (int m = 0; m < 4; ++m) _Pragma("unroll") for (int k = 0; k < 2; ++k) dst[m][k] = *(const PG8_LAS bf16x8*)(lds + PG8_SA(b, h) + aoff + m * 2048 + k * 1024); } while (0)
; #define PG8_MMA(ai, bj, At, Bt) do { __builtin_amdgcn_s_setprio(1); _Pragma("unroll") for (int m = 0; m < 4; ++m) _Pragma("unroll") for (int n = 0; n < 2; ++n) _Pragma("unroll") for (int k = 0; k < 2; ++k) \
;         acc[ai][bj][m][n] = __builtin_amdgcn_mfma_f32_16x16x32_bf16(Bt[n][k], At[m][k], acc[ai][bj][m][n], 0, 0, 0); __builtin_amdgcn_s_setprio(0); } while (0)
; #define PG8_WAIT_V(n) asm volatile("s_waitcnt vmcnt(" #n ")" ::: "memory")
; #define PG8_WAIT_L(n) asm volatile("s_waitcnt lgkmcnt(" #n ")" ::: "memory")
; #define PG8_BAR __builtin_amdgcn_s_barrier()
; #define PG8_SCHED __builtin_amdgcn_sched_barrier(0)
;     ...
;         for (int t = 0; t < nt; t += 2) {
;     ...
;             PG8_LDA(At, 1, 1); PG8_STAGE(PG8_SB(1, 0), b3, voffB); PG8_STAGE(PG8_SB(1, 1), b3 + hstepB, voffB); PG8_STAGEA(PG8_SA(1, 0), a3, voffA);
;             PG8_WAIT_V(8); PG8_WAIT_L(0); PG8_BAR; PG8_MMA(1, 0, At, B0); PG8_MMA(1, 1, At, B1); PG8_BAR; PG8_SCHED;
	s_add_i32 s42, s73, s67
	v_lshl_add_u64 v[206:207], v[206:207], 0, s[16:17]
	s_mov_b32 m0, s42
	ds_read_b128 v[184:187], v172 offset:49152
	ds_read_b128 v[188:191], v172 offset:50176
	ds_read_b128 v[192:195], v172 offset:51200
	ds_read_b128 v[196:199], v172 offset:52224
	ds_read_b128 v[202:205], v172 offset:53248
	ds_read_b128 v[210:213], v172 offset:54272
	ds_read_b128 v[214:217], v172 offset:55296
	ds_read_b128 v[218:221], v172 offset:56320
	global_load_lds_dwordx4 v[206:207], off
	s_add_i32 m0, s42, 0x2000
	s_add_u32 s40, s40, 0x10080
	v_lshl_add_u64 v[206:207], v[222:223], 0, s[16:17]
	s_addc_u32 s41, s41, 0
	s_add_i32 s42, s74, s67
	global_load_lds_dwordx4 v[206:207], off
	v_lshl_add_u64 v[206:207], s[40:41], 0, v[132:133]
	s_mov_b32 m0, s42
	s_nop 0
	global_load_lds_dwordx4 v[206:207], off
	v_lshl_add_u64 v[206:207], s[40:41], 0, v[128:129]
	s_add_i32 m0, s42, 0x2000
	s_nop 0
	global_load_lds_dwordx4 v[206:207], off
	v_lshl_add_u64 v[206:207], v[224:225], 0, s[16:17]
	s_mov_b32 m0, s51
	s_nop 0
	global_load_lds_dwordx4 v[206:207], off
	v_lshl_add_u64 v[206:207], v[226:227], 0, s[16:17]
	s_mov_b32 m0, s52
	s_nop 0
	global_load_lds_dwordx4 v[206:207], off
	s_waitcnt vmcnt(8)
	s_waitcnt lgkmcnt(0)
	s_barrier
	s_waitcnt lgkmcnt(0)
	v_mfma_f32_16x16x32_bf16 v[60:63], v[144:147], v[184:187], v[60:63]
	v_mfma_f32_16x16x32_bf16 v[56:59], v[152:155], v[184:187], v[56:59]
	v_mfma_f32_16x16x32_bf16 v[44:47], v[144:147], v[192:195], v[44:47]
	v_mfma_f32_16x16x32_bf16 v[40:43], v[152:155], v[192:195], v[40:43]
	v_mfma_f32_16x16x32_bf16 v[28:31], v[144:147], v[202:205], v[28:31]
	v_mfma_f32_16x16x32_bf16 v[24:27], v[152:155], v[202:205], v[24:27]
	v_mfma_f32_16x16x32_bf16 v[12:15], v[144:147], v[214:217], v[12:15]
	v_mfma_f32_16x16x32_bf16 v[8:11], v[152:155], v[214:217], v[8:11]
	v_mfma_f32_16x16x32_bf16 v[60:63], v[148:151], v[188:191], v[60:63]
	v_mfma_f32_16x16x32_bf16 v[56:59], v[156:159], v[188:191], v[56:59]
	v_mfma_f32_16x16x32_bf16 v[44:47], v[148:151], v[196:199], v[44:47]
	v_mfma_f32_16x16x32_bf16 v[40:43], v[156:159], v[196:199], v[40:43]
	v_mfma_f32_16x16x32_bf16 v[28:31], v[148:151], v[210:213], v[28:31]
	v_mfma_f32_16x16x32_bf16 v[24:27], v[156:159], v[210:213], v[24:27]
	v_mfma_f32_16x16x32_bf16 v[12:15], v[148:151], v[218:221], v[12:15]
	v_mfma_f32_16x16x32_bf16 v[8:11], v[156:159], v[218:221], v[8:11]
	v_mfma_f32_16x16x32_bf16 v[52:55], v[160:163], v[184:187], v[52:55]
	v_mfma_f32_16x16x32_bf16 v[48:51], v[176:179], v[184:187], v[48:51]
	v_mfma_f32_16x16x32_bf16 v[36:39], v[160:163], v[192:195], v[36:39]
	v_mfma_f32_16x16x32_bf16 v[32:35], v[176:179], v[192:195], v[32:35]
	v_mfma_f32_16x16x32_bf16 v[20:23], v[160:163], v[202:205], v[20:23]
	v_mfma_f32_16x16x32_bf16 v[16:19], v[176:179], v[202:205], v[16:19]
	v_mfma_f32_16x16x32_bf16 v[4:7], v[160:163], v[214:217], v[4:7]
	v_mfma_f32_16x16x32_bf16 v[0:3], v[176:179], v[214:217], v[0:3]
	v_mfma_f32_16x16x32_bf16 v[52:55], v[164:167], v[188:191], v[52:55]
	v_mfma_f32_16x16x32_bf16 v[48:51], v[180:183], v[188:191], v[48:51]
	v_mfma_f32_16x16x32_bf16 v[36:39], v[164:167], v[196:199], v[36:39]
	v_mfma_f32_16x16x32_bf16 v[32:35], v[180:183], v[196:199], v[32:35]
	v_mfma_f32_16x16x32_bf16 v[20:23], v[164:167], v[210:213], v[20:23]
	v_mfma_f32_16x16x32_bf16 v[16:19], v[180:183], v[210:213], v[16:19]
	v_mfma_f32_16x16x32_bf16 v[4:7], v[164:167], v[218:221], v[4:7]
	v_mfma_f32_16x16x32_bf16 v[0:3], v[180:183], v[218:221], v[0:3]
	s_add_i32 s71, s71, 2
	s_add_u32 s38, s38, 0x100
	s_addc_u32 s39, s39, 0
	s_add_u32 s59, s59, 0x100
	s_addc_u32 s70, s70, 0
	s_cmp_gt_u32 s71, 13
	s_barrier
	s_cbranch_scc0 .LBB0_977
	s_setprio 0
	s_and_b64 vcc, exec, s[18:19]
	s_cbranch_vccz .LBB0_980
	s_barrier

;     __host__ __device__ bool next(int i, Unit& u) const { return at((long)i * G + c, u); }
;     __host__ __device__ bool next(int i, Unit& u) const { if (i != 0 || c >= cnt) return false; u.pm = pm0 + c / nN; u.pn = c % nN; u.k0 = 0; u.nt = ntk; return true; }
; #define PG8_STAGE(bufoff, gbase, voff) do { _Pragma("unroll") for (int _i = 0; _i < 2; ++_i) \
;         __builtin_amdgcn_global_load_lds((const unsigned*)((const char*)(gbase) + (voff)[_i]), (PG8_LAS unsigned*)(lds + (bufoff) + ldsw + _i * 8192), 16, 0, 0); } while (0)
; #define PG8_STAGEA(bufoff, gbase, voff) do { _Pragma("unroll") for (int _i = 0; _i < 2; ++_i) \
;         __builtin_amdgcn_global_load_lds((const unsigned*)((const char*)(gbase) + (voff)[_i]), (PG8_LAS unsigned*)(lds + (bufoff) + ldsw + _i * 8192), 16, 0, AUXA); } while (0)
; #define PG8_LDA(dst, b, h) do { _Pragma("unroll") for (int m = 0; m < 4; ++m) _Pragma("unroll") for (int k = 0; k < 2; ++k) dst[m][k] = *(const PG8_LAS bf16x8*)(lds + PG8_SA(b, h) + aoff + m * 2048 + k * 1024); } while (0)
; #define PG8_WAIT_V(n) asm volatile("s_waitcnt vmcnt(" #n ")" ::: "memory")
; #define PG8_WAIT_L(n) asm volatile("s_waitcnt lgkmcnt(" #n ")" ::: "memory")
; #define PG8_BAR __builtin_amdgcn_s_barrier()
;     ...
;         const bool has_next = S.next(ui + 1, nxt);
;         const char* nA = has_next ? (const char*)g.A + (size_t)nxt.pm * tstep + (size_t)nxt.k0 * (BK * 2) : cA; const char* nB = has_next ? (const char*)g.Bt + (size_t)nxt.pn * tstep + (size_t)nxt.k0 * (BK * 2) : cB;
;         const int nt = cur.nt;
;         for (int t = 0; t < nt; t += 2) {
;             const bool last = (t == nt - 2);
;             const char* a1 = cA + (size_t)(t + 1) * kstep;
;             const char* a2 = last ? nA : cA + (size_t)(t + 2) * kstep; const char* b2 = last ? nB : cB + (size_t)(t + 2) * kstep;
;             const char* a3 = a2 + kstep; const char* b3 = b2 + kstep;
;             if (last && has_next) S.a_ready(nxt);
;             if constexpr (SP2) {
;             PG8_LDB(B0, 0, 0); PG8_LDB(B1, 0, 1); PG8_SCHED; PG8_LDA(At, 0, 0); PG8_STAGEA(PG8_SA(1, 1), a1 + hstep, voffA);
;             PG8_WAIT_V(8); PG8_WAIT_L(0); PG8_BAR; PG8_MMA(0, 0, At, B0); PG8_MMA(0, 1, At, B1); PG8_BAR; PG8_SCHED;
;             PG8_LDA(At, 0, 1); PG8_STAGE(PG8_SB(0, 0), b2, voffB); PG8_STAGE(PG8_SB(0, 1), b2 + hstepB, voffB); PG8_STAGEA(PG8_SA(0, 0), a2, voffA);
.Lsprio_6:
.LBB0_1054:
	v_add_u32_e32 v128, s59, v163
	ds_read_b128 v[166:169], v128
	ds_read_b128 v[170:173], v128 offset:1024
	ds_read_b128 v[176:179], v128 offset:2048
	ds_read_b128 v[180:183], v128 offset:3072
	v_add_u32_e32 v128, s70, v163
	ds_read_b128 v[184:187], v128
	ds_read_b128 v[188:191], v128 offset:1024
	ds_read_b128 v[192:195], v128 offset:2048
	ds_read_b128 v[196:199], v128 offset:3072
	s_add_u32 s44, s38, s42
	s_addc_u32 s45, s39, s43
	s_add_u32 s74, s36, s42
	s_addc_u32 s75, s37, s43
	s_cmp_eq_u32 s57, s73
	s_cselect_b32 s51, s13, s45
	s_cselect_b32 s50, s23, s44
	s_cselect_b32 s45, s25, s75
	s_cselect_b32 s44, s27, s74
	v_lshl_add_u64 v[206:207], s[38:39], 0, v[150:151]
	s_add_i32 m0, s49, 0xc000
	ds_read_b128 v[202:205], v164
	ds_read_b128 v[210:213], v164 offset:1024
	ds_read_b128 v[214:217], v164 offset:2048
	ds_read_b128 v[218:221], v164 offset:3072
	ds_read_b128 v[222:225], v164 offset:4096
	ds_read_b128 v[226:229], v164 offset:5120
	ds_read_b128 v[230:233], v164 offset:6144
	ds_read_b128 v[234:237], v164 offset:7168
	global_load_lds_dwordx4 v[206:207], off
	v_lshl_add_u64 v[206:207], s[38:39], 0, v[130:131]
	s_add_i32 m0, s49, 0xe000
	s_nop 0
	global_load_lds_dwordx4 v[206:207], off
	s_waitcnt vmcnt(8)
	s_waitcnt lgkmcnt(0)
	s_barrier
	s_waitcnt lgkmcnt(0)
	v_mfma_f32_16x16x32_bf16 v[124:127], v[166:169], v[202:205], v[124:127]
	v_mfma_f32_16x16x32_bf16 v[120:123], v[176:179], v[202:205], v[120:123]
	v_mfma_f32_16x16x32_bf16 v[108:111], v[166:169], v[214:217], v[108:111]
	v_mfma_f32_16x16x32_bf16 v[104:107], v[176:179], v[214:217], v[104:107]
	v_mfma_f32_16x16x32_bf16 v[92:95], v[166:169], v[222:225], v[92:95]
	v_mfma_f32_16x16x32_bf16 v[88:91], v[176:179], v[222:225], v[88:91]
	v_mfma_f32_16x16x32_bf16 v[76:79], v[166:169], v[230:233], v[76:79]
	v_mfma_f32_16x16x32_bf16 v[72:75], v[176:179], v[230:233], v[72:75]
	v_mfma_f32_16x16x32_bf16 v[124:127], v[170:173], v[210:213], v[124:127]
	v_mfma_f32_16x16x32_bf16 v[120:123], v[180:183], v[210:213], v[120:123]
	v_mfma_f32_16x16x32_bf16 v[108:111], v[170:173], v[218:221], v[108:111]
	v_mfma_f32_16x16x32_bf16 v[104:107], v[180:183], v[218:221], v[104:107]
	v_mfma_f32_16x16x32_bf16 v[92:95], v[170:173], v[226:229], v[92:95]
	v_mfma_f32_16x16x32_bf16 v[88:91], v[180:183], v[226:229], v[88:91]
	v_mfma_f32_16x16x32_bf16 v[76:79], v[170:173], v[234:237], v[76:79]
	v_mfma_f32_16x16x32_bf16 v[72:75], v[180:183], v[234:237], v[72:75]
	v_mfma_f32_16x16x32_bf16 v[116:119], v[184:187], v[202:205], v[116:119]
	v_mfma_f32_16x16x32_bf16 v[112:115], v[192:195], v[202:205], v[112:115]
	v_mfma_f32_16x16x32_bf16 v[100:103], v[184:187], v[214:217], v[100:103]
	v_mfma_f32_16x16x32_bf16 v[96:99], v[192:195], v[214:217], v[96:99]
	v_mfma_f32_16x16x32_bf16 v[84:87], v[184:187], v[222:225], v[84:87]
	v_mfma_f32_16x16x32_bf16 v[80:83], v[192:195], v[222:225], v[80:83]
	v_mfma_f32_16x16x32_bf16 v[68:71], v[184:187], v[230:233], v[68:71]
	v_mfma_f32_16x16x32_bf16 v[64:67], v[192:195], v[230:233], v[64:67]
	v_mfma_f32_16x16x32_bf16 v[116:119], v[188:191], v[210:213], v[116:119]
	v_mfma_f32_16x16x32_bf16 v[112:115], v[196:199], v[210:213], v[112:115]
	v_mfma_f32_16x16x32_bf16 v[100:103], v[188:191], v[218:221], v[100:103]
	v_mfma_f32_16x16x32_bf16 v[96:99], v[196:199], v[218:221], v[96:99]
	v_mfma_f32_16x16x32_bf16 v[84:87], v[188:191], v[226:229], v[84:87]
	v_mfma_f32_16x16x32_bf16 v[80:83], v[196:199], v[226:229], v[80:83]
	v_mfma_f32_16x16x32_bf16 v[68:71], v[188:191], v[234:237], v[68:71]
	v_mfma_f32_16x16x32_bf16 v[64:67], v[196:199], v[234:237], v[64:67]
	s_barrier
	s_add_i32 s74, s59, s67
	v_lshl_add_u64 v[206:207], s[44:45], 0, v[136:137]
	s_mov_b32 m0, s74
	ds_read_b128 v[202:205], v164 offset:16384
	ds_read_b128 v[210:213], v164 offset:17408
	ds_read_b128 v[214:217], v164 offset:18432
	ds_read_b128 v[218:221], v164 offset:19456
	ds_read_b128 v[222:225], v164 offset:20480
	ds_read_b128 v[226:229], v164 offset:21504
	ds_read_b128 v[230:233], v164 offset:22528
	ds_read_b128 v[234:237], v164 offset:23552
	global_load_lds_dwordx4 v[206:207], off
	s_add_i32 m0, s74, 0x2000
	s_add_u32 s74, s44, 0x40000
	v_lshl_add_u64 v[238:239], s[44:45], 0, v[140:141]
	s_addc_u32 s75, s45, 0
	s_add_i32 s76, s70, s67
	global_load_lds_dwordx4 v[238:239], off
	v_lshl_add_u64 v[240:241], s[74:75], 0, v[136:137]
	s_mov_b32 m0, s76
	v_lshl_add_u64 v[242:243], s[50:51], 0, v[138:139]
	global_load_lds_dwordx4 v[240:241], off
	v_lshl_add_u64 v[240:241], s[74:75], 0, v[140:141]
	s_add_i32 m0, s76, 0x2000
	s_nop 0
	global_load_lds_dwordx4 v[240:241], off
	v_lshl_add_u64 v[240:241], s[50:51], 0, v[134:135]
	s_mov_b32 m0, s49
	s_nop 0
	global_load_lds_dwordx4 v[240:241], off
	s_mov_b32 m0, s52
	s_nop 0
	global_load_lds_dwordx4 v[242:243], off
	s_waitcnt vmcnt(8)
	s_waitcnt lgkmcnt(0)
	s_barrier
; #define PG8_STAGE(bufoff, gbase, voff) do { _Pragma("unroll") for (int _i = 0; _i < 2; ++_i) \
;         __builtin_amdgcn_global_load_lds((const unsigned*)((const char*)(gbase) + (voff)[_i]), (PG8_LAS unsigned*)(lds + (bufoff) + ldsw + _i * 8192), 16, 0, 0); } while (0)
; #define PG8_STAGEA(bufoff, gbase, voff) do { _Pragma("unroll") for (int _i = 0; _i < 2; ++_i) \
;         __builtin_amdgcn_global_load_lds((const unsigned*)((const char*)(gbase) + (voff)[_i]), (PG8_LAS unsigned*)(lds + (bufoff) + ldsw + _i * 8192), 16, 0, AUXA); } while (0)
; #define PG8_LDA(dst, b, h) do { _Pragma("unroll") for (int m = 0; m < 4; ++m) _Pragma("unroll") for (int k = 0; k < 2; ++k) dst[m][k] = *(const PG8_LAS bf16x8*)(lds + PG8_SA(b, h) + aoff + m * 2048 + k * 1024); } while (0)
; #define PG8_LDB(dst, b, h) do { _Pragma("unroll") for (int n = 0; n < 2; ++n) _Pragma("unroll") for (int k = 0; k < 2; ++k) dst[n][k] = *(const PG8_LAS bf16x8*)(lds + PG8_SB(b, h) + boff + n * 2048 + k * 1024); } while (0)
; #define PG8_MMA(ai, bj, At, Bt) do { __builtin_amdgcn_s_setprio(1); _Pragma("unroll") for (int m = 0; m < 4; ++m) _Pragma("unroll") for (int n = 0; n < 2; ++n) _Pragma("unroll") for (int k = 0; k < 2; ++k) \
;         acc[ai][bj][m][n] = __builtin_amdgcn_mfma_f32_16x16x32_bf16(Bt[n][k], At[m][k], acc[ai][bj][m][n], 0, 0, 0); __builtin_amdgcn_s_setprio(0); } while (0)
; #define PG8_WAIT_V(n) asm volatile("s_waitcnt vmcnt(" #n ")" ::: "memory")
; #define PG8_WAIT_L(n) asm volatile("s_waitcnt lgkmcnt(" #n ")" ::: "memory")
; #define PG8_BAR __builtin_amdgcn_s_barrier()
; #define PG8_SCHED __builtin_amdgcn_sched_barrier(0)
;     ...
;             PG8_WAIT_V(8); PG8_WAIT_L(0); PG8_BAR; PG8_MMA(1, 0, At, B0); PG8_MMA(1, 1, At, B1); PG8_BAR; PG8_SCHED;
;             PG8_LDB(B0, 1, 0); PG8_LDB(B1, 1, 1); PG8_SCHED; PG8_LDA(At, 1, 0); PG8_STAGEA(PG8_SA(0, 1), a2 + hstep, voffA);
;             PG8_WAIT_V(8); PG8_WAIT_L(0); PG8_BAR; PG8_MMA(0, 0, At, B0); PG8_MMA(0, 1, At, B1); PG8_BAR; PG8_SCHED;
;             PG8_LDA(At, 1, 1); PG8_STAGE(PG8_SB(1, 0), b3, voffB); PG8_STAGE(PG8_SB(1, 1), b3 + hstepB, voffB); PG8_STAGEA(PG8_SA(1, 0), a3, voffA);
	s_waitcnt lgkmcnt(0)
	v_mfma_f32_16x16x32_bf16 v[60:63], v[166:169], v[202:205], v[60:63]
	v_mfma_f32_16x16x32_bf16 v[56:59], v[176:179], v[202:205], v[56:59]
	v_mfma_f32_16x16x32_bf16 v[44:47], v[166:169], v[214:217], v[44:47]
	v_mfma_f32_16x16x32_bf16 v[40:43], v[176:179], v[214:217], v[40:43]
	v_mfma_f32_16x16x32_bf16 v[28:31], v[166:169], v[222:225], v[28:31]
	v_mfma_f32_16x16x32_bf16 v[24:27], v[176:179], v[222:225], v[24:27]
	v_mfma_f32_16x16x32_bf16 v[12:15], v[166:169], v[230:233], v[12:15]
	v_mfma_f32_16x16x32_bf16 v[8:11], v[176:179], v[230:233], v[8:11]
	v_mfma_f32_16x16x32_bf16 v[60:63], v[170:173], v[210:213], v[60:63]
	v_mfma_f32_16x16x32_bf16 v[56:59], v[180:183], v[210:213], v[56:59]
	v_mfma_f32_16x16x32_bf16 v[44:47], v[170:173], v[218:221], v[44:47]
	v_mfma_f32_16x16x32_bf16 v[40:43], v[180:183], v[218:221], v[40:43]
	v_mfma_f32_16x16x32_bf16 v[28:31], v[170:173], v[226:229], v[28:31]
	v_mfma_f32_16x16x32_bf16 v[24:27], v[180:183], v[226:229], v[24:27]
	v_mfma_f32_16x16x32_bf16 v[12:15], v[170:173], v[234:237], v[12:15]
	v_mfma_f32_16x16x32_bf16 v[8:11], v[180:183], v[234:237], v[8:11]
	v_mfma_f32_16x16x32_bf16 v[52:55], v[184:187], v[202:205], v[52:55]
	v_mfma_f32_16x16x32_bf16 v[48:51], v[192:195], v[202:205], v[48:51]
	v_mfma_f32_16x16x32_bf16 v[36:39], v[184:187], v[214:217], v[36:39]
	v_mfma_f32_16x16x32_bf16 v[32:35], v[192:195], v[214:217], v[32:35]
	v_mfma_f32_16x16x32_bf16 v[20:23], v[184:187], v[222:225], v[20:23]
	v_mfma_f32_16x16x32_bf16 v[16:19], v[192:195], v[222:225], v[16:19]
	v_mfma_f32_16x16x32_bf16 v[4:7], v[184:187], v[230:233], v[4:7]
	v_mfma_f32_16x16x32_bf16 v[0:3], v[192:195], v[230:233], v[0:3]
	v_mfma_f32_16x16x32_bf16 v[52:55], v[188:191], v[210:213], v[52:55]
	v_mfma_f32_16x16x32_bf16 v[48:51], v[196:199], v[210:213], v[48:51]
	v_mfma_f32_16x16x32_bf16 v[36:39], v[188:191], v[218:221], v[36:39]
	v_mfma_f32_16x16x32_bf16 v[32:35], v[196:199], v[218:221], v[32:35]
	v_mfma_f32_16x16x32_bf16 v[20:23], v[188:191], v[226:229], v[20:23]
	v_mfma_f32_16x16x32_bf16 v[16:19], v[196:199], v[226:229], v[16:19]
	v_mfma_f32_16x16x32_bf16 v[4:7], v[188:191], v[234:237], v[4:7]
	v_mfma_f32_16x16x32_bf16 v[0:3], v[196:199], v[234:237], v[0:3]
	s_barrier
	s_add_i32 s74, 0, 0x18000
	v_add_u32_e32 v128, s74, v163
	s_add_i32 s75, 0, 0x1c000
	ds_read_b128 v[166:169], v128
	ds_read_b128 v[170:173], v128 offset:1024
	ds_read_b128 v[176:179], v128 offset:2048
	ds_read_b128 v[180:183], v128 offset:3072
	v_add_u32_e32 v128, s75, v163
	ds_read_b128 v[184:187], v128
	ds_read_b128 v[188:191], v128 offset:1024
	ds_read_b128 v[192:195], v128 offset:2048
	ds_read_b128 v[196:199], v128 offset:3072
	s_add_u32 s50, s50, 0x100000
	s_addc_u32 s51, s51, 0
	s_mov_b32 m0, s53
	v_lshl_add_u64 v[244:245], s[50:51], 0, v[134:135]
	ds_read_b128 v[202:205], v164 offset:32768
	ds_read_b128 v[210:213], v164 offset:33792
	ds_read_b128 v[214:217], v164 offset:34816
	ds_read_b128 v[218:221], v164 offset:35840
	ds_read_b128 v[222:225], v164 offset:36864
	ds_read_b128 v[226:229], v164 offset:37888
	ds_read_b128 v[230:233], v164 offset:38912
	ds_read_b128 v[234:237], v164 offset:39936
	global_load_lds_dwordx4 v[244:245], off
	v_lshl_add_u64 v[244:245], s[50:51], 0, v[138:139]
	s_mov_b32 m0, s54
	s_nop 0
	global_load_lds_dwordx4 v[244:245], off
	s_waitcnt vmcnt(8)
	s_waitcnt lgkmcnt(0)
	s_barrier
	s_waitcnt lgkmcnt(0)
	v_mfma_f32_16x16x32_bf16 v[124:127], v[166:169], v[202:205], v[124:127]
	v_mfma_f32_16x16x32_bf16 v[120:123], v[176:179], v[202:205], v[120:123]
	v_mfma_f32_16x16x32_bf16 v[108:111], v[166:169], v[214:217], v[108:111]
	v_mfma_f32_16x16x32_bf16 v[104:107], v[176:179], v[214:217], v[104:107]
	v_mfma_f32_16x16x32_bf16 v[92:95], v[166:169], v[222:225], v[92:95]
	v_mfma_f32_16x16x32_bf16 v[88:91], v[176:179], v[222:225], v[88:91]
	v_mfma_f32_16x16x32_bf16 v[76:79], v[166:169], v[230:233], v[76:79]
	v_mfma_f32_16x16x32_bf16 v[72:75], v[176:179], v[230:233], v[72:75]
	v_mfma_f32_16x16x32_bf16 v[124:127], v[170:173], v[210:213], v[124:127]
	v_mfma_f32_16x16x32_bf16 v[120:123], v[180:183], v[210:213], v[120:123]
	v_mfma_f32_16x16x32_bf16 v[108:111], v[170:173], v[218:221], v[108:111]
	v_mfma_f32_16x16x32_bf16 v[104:107], v[180:183], v[218:221], v[104:107]
	v_mfma_f32_16x16x32_bf16 v[92:95], v[170:173], v[226:229], v[92:95]
	v_mfma_f32_16x16x32_bf16 v[88:91], v[180:183], v[226:229], v[88:91]
	v_mfma_f32_16x16x32_bf16 v[76:79], v[170:173], v[234:237], v[76:79]
	v_mfma_f32_16x16x32_bf16 v[72:75], v[180:183], v[234:237], v[72:75]
	v_mfma_f32_16x16x32_bf16 v[116:119], v[184:187], v[202:205], v[116:119]
	v_mfma_f32_16x16x32_bf16 v[112:115], v[192:195], v[202:205], v[112:115]
	v_mfma_f32_16x16x32_bf16 v[100:103], v[184:187], v[214:217], v[100:103]
	v_mfma_f32_16x16x32_bf16 v[96:99], v[192:195], v[214:217], v[96:99]
	v_mfma_f32_16x16x32_bf16 v[84:87], v[184:187], v[222:225], v[84:87]
	v_mfma_f32_16x16x32_bf16 v[80:83], v[192:195], v[222:225], v[80:83]
	v_mfma_f32_16x16x32_bf16 v[68:71], v[184:187], v[230:233], v[68:71]
	v_mfma_f32_16x16x32_bf16 v[64:67], v[192:195], v[230:233], v[64:67]
	v_mfma_f32_16x16x32_bf16 v[116:119], v[188:191], v[210:213], v[116:119]
	v_mfma_f32_16x16x32_bf16 v[112:115], v[196:199], v[210:213], v[112:115]
	v_mfma_f32_16x16x32_bf16 v[100:103], v[188:191], v[218:221], v[100:103]
	v_mfma_f32_16x16x32_bf16 v[96:99], v[196:199], v[218:221], v[96:99]
	v_mfma_f32_16x16x32_bf16 v[84:87], v[188:191], v[226:229], v[84:87]
	v_mfma_f32_16x16x32_bf16 v[80:83], v[196:199], v[226:229], v[80:83]
	v_mfma_f32_16x16x32_bf16 v[68:71], v[188:191], v[234:237], v[68:71]
	v_mfma_f32_16x16x32_bf16 v[64:67], v[196:199], v[234:237], v[64:67]
	s_barrier
; #define PG8_STAGE(bufoff, gbase, voff) do { _Pragma("unroll") for (int _i = 0; _i < 2; ++_i) \
;         __builtin_amdgcn_global_load_lds((const unsigned*)((const char*)(gbase) + (voff)[_i]), (PG8_LAS unsigned*)(lds + (bufoff) + ldsw + _i * 8192), 16, 0, 0); } while (0)
; #define PG8_STAGEA(bufoff, gbase, voff) do { _Pragma("unroll") for (int _i = 0; _i < 2; ++_i) \
;         __builtin_amdgcn_global_load_lds((const unsigned*)((const char*)(gbase) + (voff)[_i]), (PG8_LAS unsigned*)(lds + (bufoff) + ldsw + _i * 8192), 16, 0, AUXA); } while (0)
; #define PG8_LDA(dst, b, h) do { _Pragma("unroll") for (int m = 0; m < 4; ++m) _Pragma("unroll") for (int k = 0; k < 2; ++k) dst[m][k] = *(const PG8_LAS bf16x8*)(lds + PG8_SA(b, h) + aoff + m * 2048 + k * 1024); } while (0)
; #define PG8_MMA(ai, bj, At, Bt) do { __builtin_amdgcn_s_setprio(1); _Pragma("unroll") for (int m = 0; m < 4; ++m) _Pragma("unroll") for (int n = 0; n < 2; ++n) _Pragma("unroll") for (int k = 0; k < 2; ++k) \
;         acc[ai][bj][m][n] = __builtin_amdgcn_mfma_f32_16x16x32_bf16(Bt[n][k], At[m][k], acc[ai][bj][m][n], 0, 0, 0); __builtin_amdgcn_s_setprio(0); } while (0)
; #define PG8_WAIT_V(n) asm volatile("s_waitcnt vmcnt(" #n ")" ::: "memory")
; #define PG8_WAIT_L(n) asm volatile("s_waitcnt lgkmcnt(" #n ")" ::: "memory")
; #define PG8_BAR __builtin_amdgcn_s_barrier()
; #define PG8_SCHED __builtin_amdgcn_sched_barrier(0)
;     ...
;         for (int t = 0; t < nt; t += 2) {
;     ...
;             PG8_LDA(At, 1, 1); PG8_STAGE(PG8_SB(1, 0), b3, voffB); PG8_STAGE(PG8_SB(1, 1), b3 + hstepB, voffB); PG8_STAGEA(PG8_SA(1, 0), a3, voffA);
;             PG8_WAIT_V(8); PG8_WAIT_L(0); PG8_BAR; PG8_MMA(1, 0, At, B0); PG8_MMA(1, 1, At, B1); PG8_BAR; PG8_SCHED;
	s_add_i32 s50, s74, s67
	v_lshl_add_u64 v[206:207], v[206:207], 0, s[16:17]
	s_mov_b32 m0, s50
	ds_read_b128 v[202:205], v164 offset:49152
	ds_read_b128 v[210:213], v164 offset:50176
	ds_read_b128 v[214:217], v164 offset:51200
	ds_read_b128 v[218:221], v164 offset:52224
	ds_read_b128 v[222:225], v164 offset:53248
	ds_read_b128 v[226:229], v164 offset:54272
	ds_read_b128 v[230:233], v164 offset:55296
	ds_read_b128 v[234:237], v164 offset:56320
	global_load_lds_dwordx4 v[206:207], off
	s_add_i32 m0, s50, 0x2000
	s_add_u32 s44, s44, 0x40080
	v_lshl_add_u64 v[206:207], v[238:239], 0, s[16:17]
	s_addc_u32 s45, s45, 0
	s_add_i32 s50, s75, s67
	global_load_lds_dwordx4 v[206:207], off
	v_lshl_add_u64 v[206:207], s[44:45], 0, v[136:137]
	s_mov_b32 m0, s50
	s_nop 0
	global_load_lds_dwordx4 v[206:207], off
	v_lshl_add_u64 v[206:207], s[44:45], 0, v[140:141]
	s_add_i32 m0, s50, 0x2000
	s_nop 0
	global_load_lds_dwordx4 v[206:207], off
	v_lshl_add_u64 v[206:207], v[240:241], 0, s[16:17]
	s_mov_b32 m0, s55
	s_nop 0
	global_load_lds_dwordx4 v[206:207], off
	v_lshl_add_u64 v[206:207], v[242:243], 0, s[16:17]
	s_mov_b32 m0, s56
	s_nop 0
	global_load_lds_dwordx4 v[206:207], off
	s_waitcnt vmcnt(8)
	s_waitcnt lgkmcnt(0)
	s_barrier
	s_waitcnt lgkmcnt(0)
	v_mfma_f32_16x16x32_bf16 v[60:63], v[166:169], v[202:205], v[60:63]
	v_mfma_f32_16x16x32_bf16 v[56:59], v[176:179], v[202:205], v[56:59]
	v_mfma_f32_16x16x32_bf16 v[44:47], v[166:169], v[214:217], v[44:47]
	v_mfma_f32_16x16x32_bf16 v[40:43], v[176:179], v[214:217], v[40:43]
	v_mfma_f32_16x16x32_bf16 v[28:31], v[166:169], v[222:225], v[28:31]
	v_mfma_f32_16x16x32_bf16 v[24:27], v[176:179], v[222:225], v[24:27]
	v_mfma_f32_16x16x32_bf16 v[12:15], v[166:169], v[230:233], v[12:15]
	v_mfma_f32_16x16x32_bf16 v[8:11], v[176:179], v[230:233], v[8:11]
	v_mfma_f32_16x16x32_bf16 v[60:63], v[170:173], v[210:213], v[60:63]
	v_mfma_f32_16x16x32_bf16 v[56:59], v[180:183], v[210:213], v[56:59]
	v_mfma_f32_16x16x32_bf16 v[44:47], v[170:173], v[218:221], v[44:47]
	v_mfma_f32_16x16x32_bf16 v[40:43], v[180:183], v[218:221], v[40:43]
	v_mfma_f32_16x16x32_bf16 v[28:31], v[170:173], v[226:229], v[28:31]
	v_mfma_f32_16x16x32_bf16 v[24:27], v[180:183], v[226:229], v[24:27]
	v_mfma_f32_16x16x32_bf16 v[12:15], v[170:173], v[234:237], v[12:15]
	v_mfma_f32_16x16x32_bf16 v[8:11], v[180:183], v[234:237], v[8:11]
	v_mfma_f32_16x16x32_bf16 v[52:55], v[184:187], v[202:205], v[52:55]
	v_mfma_f32_16x16x32_bf16 v[48:51], v[192:195], v[202:205], v[48:51]
	v_mfma_f32_16x16x32_bf16 v[36:39], v[184:187], v[214:217], v[36:39]
	v_mfma_f32_16x16x32_bf16 v[32:35], v[192:195], v[214:217], v[32:35]
	v_mfma_f32_16x16x32_bf16 v[20:23], v[184:187], v[222:225], v[20:23]
	v_mfma_f32_16x16x32_bf16 v[16:19], v[192:195], v[222:225], v[16:19]
	v_mfma_f32_16x16x32_bf16 v[4:7], v[184:187], v[230:233], v[4:7]
	v_mfma_f32_16x16x32_bf16 v[0:3], v[192:195], v[230:233], v[0:3]
	v_mfma_f32_16x16x32_bf16 v[52:55], v[188:191], v[210:213], v[52:55]
	v_mfma_f32_16x16x32_bf16 v[48:51], v[196:199], v[210:213], v[48:51]
	v_mfma_f32_16x16x32_bf16 v[36:39], v[188:191], v[218:221], v[36:39]
	v_mfma_f32_16x16x32_bf16 v[32:35], v[196:199], v[218:221], v[32:35]
	v_mfma_f32_16x16x32_bf16 v[20:23], v[188:191], v[226:229], v[20:23]
	v_mfma_f32_16x16x32_bf16 v[16:19], v[196:199], v[226:229], v[16:19]
	v_mfma_f32_16x16x32_bf16 v[4:7], v[188:191], v[234:237], v[4:7]
	v_mfma_f32_16x16x32_bf16 v[0:3], v[196:199], v[234:237], v[0:3]
	s_add_i32 s44, s73, 2
	s_add_u32 s42, s42, 0x100
	s_addc_u32 s43, s43, 0
	v_lshl_add_u64 v[150:151], v[150:151], 0, s[20:21]
	v_lshl_add_u64 v[130:131], v[130:131], 0, s[20:21]
	s_cmp_ge_i32 s73, s57
	s_mov_b32 s73, s44
	s_barrier
	s_cbranch_scc0 .LBB0_1054
	s_setprio 0
	s_and_b64 vcc, exec, s[18:19]
	s_cbranch_vccz .LBB0_1057
	s_barrier
